# GEMM K-loop stagings use SGPR-base LDS-DMA loads (88 per-iteration 64-bit VALU address adds removed; phase-4 bases via SALU)
# speedup vs baseline: 1.0167x; 1.0167x over previous
; #define PG8_STAGE(bufoff, gbase, voff) do { _Pragma("unroll") for (int _i = 0; _i < 2; ++_i) \
;         __builtin_amdgcn_global_load_lds((const unsigned*)((const char*)(gbase) + (voff)[_i]), (LAS unsigned*)(lds + (bufoff) + ldsw + _i * 8192), 16, 0, 0); } while (0)
; #define PG8_LDA(dst, b, h) do { _Pragma("unroll") for (int m = 0; m < 4; ++m) _Pragma("unroll") for (int k = 0; k < 2; ++k) dst[m][k] = *(const LAS bf16x8*)(lds + PG8_SA(b, h) + aoff + m * 2048 + k * 1024); } while (0)
; #define PG8_LDB(dst, b, h) do { _Pragma("unroll") for (int n = 0; n < 2; ++n) _Pragma("unroll") for (int k = 0; k < 2; ++k) dst[n][k] = *(const LAS bf16x8*)(lds + PG8_SB(b, h) + boff + n * 2048 + k * 1024); } while (0)
; #define PG8_MMA(ai, bj, At, Bt) do { __builtin_amdgcn_s_setprio(1); _Pragma("unroll") for (int m = 0; m < 4; ++m) _Pragma("unroll") for (int n = 0; n < 2; ++n) _Pragma("unroll") for (int k = 0; k < 2; ++k) \
;         acc[ai][bj][m][n] = __builtin_amdgcn_mfma_f32_16x16x32_bf16(Bt[n][k], At[m][k], acc[ai][bj][m][n], 0, 0, 0); __builtin_amdgcn_s_setprio(0); } while (0)
; #define PG8_WAIT_V(n) asm volatile("s_waitcnt vmcnt(" #n ")" ::: "memory")
; #define PG8_WAIT_L(n) asm volatile("s_waitcnt lgkmcnt(" #n ")" ::: "memory")
; template <class Epi, class Sched>
; __device__ __forceinline__ void gemm_phase(LAS unsigned char* lds, const Gemm g, const Sched& S, const Epi& E) {
;     ...
;         for (int t = 0; t < nt; t += 2) {
;             const bool last = (t == nt - 2);
;             const char* a1 = cA + (size_t)(t + 1) * kstep;
;             const char* a2 = last ? nA : cA + (size_t)(t + 2) * kstep; const char* b2 = last ? nB : cB + (size_t)(t + 2) * kstep;
;             const char* a3 = a2 + kstep; const char* b3 = b2 + kstep;
;             PG8_LDB(B0, 0, 0); PG8_SCHED; PG8_LDA(At, 0, 0); PG8_STAGE(PG8_SA(1, 1), a1 + hstep, voffA);
;             PG8_WAIT_L(8); PG8_BAR; PG8_WAIT_L(0); PG8_MMA(0, 0, At, B0); PG8_BAR; PG8_SCHED;
;             PG8_LDB(B1, 0, 1); PG8_STAGE(PG8_SB(0, 0), b2, voffB);
;             PG8_BAR; PG8_WAIT_L(0); PG8_MMA(0, 1, At, B1); PG8_BAR;
;             PG8_LDA(At, 0, 1); PG8_STAGE(PG8_SA(0, 0), a2, voffA);
;             PG8_BAR; PG8_WAIT_L(0); PG8_MMA(1, 0, At, B0); PG8_BAR; PG8_SCHED;
;             PG8_STAGE(PG8_SB(0, 1), b2 + hstep, voffB);
;             PG8_WAIT_V(6); PG8_BAR; PG8_MMA(1, 1, At, B1); PG8_BAR;
.LBB0_44:
	s_add_u32 s50, s28, 0x100
	s_addc_u32 s51, s29, 0
	s_cmpk_eq_i32 s75, 0x7c
	s_cselect_b32 s55, s27, s51
	s_cselect_b32 s54, s71, s50
	s_cselect_b32 s53, s25, s74
	s_cselect_b32 s52, s72, s73
	v_lshl_add_u64 v[156:157], s[28:29], 0, v[150:151]
	s_add_i32 m0, s9, 0xc000
	s_nop 0
	global_load_lds_dwordx4 v[156:157], off
	v_lshl_add_u64 v[156:157], s[28:29], 0, v[148:149]
	s_add_i32 m0, s9, 0xe000
	s_nop 0
	global_load_lds_dwordx4 v[156:157], off
	s_add_i32 s38, 0, 0x10000
	v_add_u32_e32 v78, s38, v163
	ds_read_b128 v[66:69], v78
	ds_read_b128 v[70:73], v78 offset:1024
	ds_read_b128 v[74:77], v78 offset:2048
	ds_read_b128 v[78:81], v78 offset:3072
	ds_read_b128 v[152:155], v165
	ds_read_b128 v[166:169], v165 offset:1024
	ds_read_b128 v[170:173], v165 offset:2048
	ds_read_b128 v[174:177], v165 offset:3072
	ds_read_b128 v[178:181], v165 offset:4096
	ds_read_b128 v[182:185], v165 offset:5120
	ds_read_b128 v[186:189], v165 offset:6144
	ds_read_b128 v[190:193], v165 offset:7168
	s_add_i32 s39, 0, 0x14000
	v_add_u32_e32 v156, s39, v163
	ds_read_b128 v[194:197], v156
	ds_read_b128 v[198:201], v156 offset:1024
	ds_read_b128 v[202:205], v156 offset:2048
	ds_read_b128 v[210:213], v156 offset:3072
	s_waitcnt lgkmcnt(4)
	s_barrier
	s_waitcnt lgkmcnt(0)
	v_mfma_f32_16x16x32_bf16 v[142:145], v[66:69], v[152:155], v[142:145]
	v_mfma_f32_16x16x32_bf16 v[138:141], v[74:77], v[152:155], v[138:141]
	v_mfma_f32_16x16x32_bf16 v[126:129], v[66:69], v[170:173], v[126:129]
	v_mfma_f32_16x16x32_bf16 v[122:125], v[74:77], v[170:173], v[122:125]
	v_mfma_f32_16x16x32_bf16 v[110:113], v[66:69], v[178:181], v[110:113]
	v_mfma_f32_16x16x32_bf16 v[106:109], v[74:77], v[178:181], v[106:109]
	v_mfma_f32_16x16x32_bf16 v[102:105], v[66:69], v[186:189], v[102:105]
	v_mfma_f32_16x16x32_bf16 v[98:101], v[74:77], v[186:189], v[98:101]
	v_mfma_f32_16x16x32_bf16 v[142:145], v[70:73], v[166:169], v[142:145]
	v_mfma_f32_16x16x32_bf16 v[138:141], v[78:81], v[166:169], v[138:141]
	v_mfma_f32_16x16x32_bf16 v[126:129], v[70:73], v[174:177], v[126:129]
	v_mfma_f32_16x16x32_bf16 v[122:125], v[78:81], v[174:177], v[122:125]
	v_mfma_f32_16x16x32_bf16 v[110:113], v[70:73], v[182:185], v[110:113]
	v_mfma_f32_16x16x32_bf16 v[106:109], v[78:81], v[182:185], v[106:109]
	v_mfma_f32_16x16x32_bf16 v[102:105], v[70:73], v[190:193], v[102:105]
	v_mfma_f32_16x16x32_bf16 v[98:101], v[78:81], v[190:193], v[98:101]
	v_mfma_f32_16x16x32_bf16 v[134:137], v[194:197], v[152:155], v[134:137]
	v_mfma_f32_16x16x32_bf16 v[130:133], v[202:205], v[152:155], v[130:133]
	v_mfma_f32_16x16x32_bf16 v[118:121], v[194:197], v[170:173], v[118:121]
	v_mfma_f32_16x16x32_bf16 v[114:117], v[202:205], v[170:173], v[114:117]
	v_mfma_f32_16x16x32_bf16 v[94:97], v[194:197], v[178:181], v[94:97]
	v_mfma_f32_16x16x32_bf16 v[90:93], v[202:205], v[178:181], v[90:93]
	v_mfma_f32_16x16x32_bf16 v[86:89], v[194:197], v[186:189], v[86:89]
	v_mfma_f32_16x16x32_bf16 v[82:85], v[202:205], v[186:189], v[82:85]
	v_mfma_f32_16x16x32_bf16 v[134:137], v[198:201], v[166:169], v[134:137]
	v_mfma_f32_16x16x32_bf16 v[130:133], v[210:213], v[166:169], v[130:133]
	v_mfma_f32_16x16x32_bf16 v[118:121], v[198:201], v[174:177], v[118:121]
	v_mfma_f32_16x16x32_bf16 v[114:117], v[210:213], v[174:177], v[114:117]
	v_mfma_f32_16x16x32_bf16 v[94:97], v[198:201], v[182:185], v[94:97]
	v_mfma_f32_16x16x32_bf16 v[90:93], v[210:213], v[182:185], v[90:93]
	v_mfma_f32_16x16x32_bf16 v[86:89], v[198:201], v[190:193], v[86:89]
	v_mfma_f32_16x16x32_bf16 v[82:85], v[210:213], v[190:193], v[82:85]
	s_barrier
	s_add_i32 s28, s38, s60
	s_mov_b32 m0, s28
	s_nop 0
	global_load_lds_dwordx4 v0, s[52:53]
	s_add_i32 m0, s28, 0x2000
	s_nop 0
	global_load_lds_dwordx4 v146, s[52:53]
	s_mov_b32 m0, s9
	s_nop 0
	global_load_lds_dwordx4 v0, s[54:55]
	s_mov_b32 m0, s61
	s_nop 0
	global_load_lds_dwordx4 v146, s[54:55]
	ds_read_b128 v[152:155], v165 offset:16384
	ds_read_b128 v[166:169], v165 offset:17408
	ds_read_b128 v[170:173], v165 offset:18432
	ds_read_b128 v[174:177], v165 offset:19456
	ds_read_b128 v[178:181], v165 offset:20480
	ds_read_b128 v[182:185], v165 offset:21504
	ds_read_b128 v[186:189], v165 offset:22528
	ds_read_b128 v[190:193], v165 offset:23552
	s_waitcnt vmcnt(4)
	s_waitcnt lgkmcnt(0)
	s_barrier
	v_mfma_f32_16x16x32_bf16 v[62:65], v[66:69], v[152:155], v[62:65]
	v_mfma_f32_16x16x32_bf16 v[58:61], v[74:77], v[152:155], v[58:61]
	v_mfma_f32_16x16x32_bf16 v[46:49], v[66:69], v[170:173], v[46:49]
	v_mfma_f32_16x16x32_bf16 v[42:45], v[74:77], v[170:173], v[42:45]
	v_mfma_f32_16x16x32_bf16 v[30:33], v[66:69], v[178:181], v[30:33]
	v_mfma_f32_16x16x32_bf16 v[26:29], v[74:77], v[178:181], v[26:29]
	v_mfma_f32_16x16x32_bf16 v[22:25], v[66:69], v[186:189], v[22:25]
	v_mfma_f32_16x16x32_bf16 v[14:17], v[74:77], v[186:189], v[14:17]
	v_mfma_f32_16x16x32_bf16 v[62:65], v[70:73], v[166:169], v[62:65]
	v_mfma_f32_16x16x32_bf16 v[58:61], v[78:81], v[166:169], v[58:61]
	v_mfma_f32_16x16x32_bf16 v[46:49], v[70:73], v[174:177], v[46:49]
	v_mfma_f32_16x16x32_bf16 v[42:45], v[78:81], v[174:177], v[42:45]
	v_mfma_f32_16x16x32_bf16 v[30:33], v[70:73], v[182:185], v[30:33]
	v_mfma_f32_16x16x32_bf16 v[26:29], v[78:81], v[182:185], v[26:29]
	v_mfma_f32_16x16x32_bf16 v[22:25], v[70:73], v[190:193], v[22:25]
	v_mfma_f32_16x16x32_bf16 v[14:17], v[78:81], v[190:193], v[14:17]
	v_mfma_f32_16x16x32_bf16 v[54:57], v[194:197], v[152:155], v[54:57]
	v_mfma_f32_16x16x32_bf16 v[50:53], v[202:205], v[152:155], v[50:53]
	v_mfma_f32_16x16x32_bf16 v[38:41], v[194:197], v[170:173], v[38:41]
	v_mfma_f32_16x16x32_bf16 v[34:37], v[202:205], v[170:173], v[34:37]
	v_mfma_f32_16x16x32_bf16 v[18:21], v[194:197], v[178:181], v[18:21]
	v_mfma_f32_16x16x32_bf16 v[10:13], v[202:205], v[178:181], v[10:13]
	v_mfma_f32_16x16x32_bf16 v[6:9], v[194:197], v[186:189], v[6:9]
	v_mfma_f32_16x16x32_bf16 v[2:5], v[202:205], v[186:189], v[2:5]
	v_mfma_f32_16x16x32_bf16 v[54:57], v[198:201], v[166:169], v[54:57]
	v_mfma_f32_16x16x32_bf16 v[50:53], v[210:213], v[166:169], v[50:53]
	v_mfma_f32_16x16x32_bf16 v[38:41], v[198:201], v[174:177], v[38:41]
	v_mfma_f32_16x16x32_bf16 v[34:37], v[210:213], v[174:177], v[34:37]
	v_mfma_f32_16x16x32_bf16 v[18:21], v[198:201], v[182:185], v[18:21]
	v_mfma_f32_16x16x32_bf16 v[10:13], v[210:213], v[182:185], v[10:13]
	v_mfma_f32_16x16x32_bf16 v[6:9], v[198:201], v[190:193], v[6:9]
	v_mfma_f32_16x16x32_bf16 v[2:5], v[210:213], v[190:193], v[2:5]
	s_barrier
; #define PG8_STAGE(bufoff, gbase, voff) do { _Pragma("unroll") for (int _i = 0; _i < 2; ++_i) \
;         __builtin_amdgcn_global_load_lds((const unsigned*)((const char*)(gbase) + (voff)[_i]), (LAS unsigned*)(lds + (bufoff) + ldsw + _i * 8192), 16, 0, 0); } while (0)
; #define PG8_LDA(dst, b, h) do { _Pragma("unroll") for (int m = 0; m < 4; ++m) _Pragma("unroll") for (int k = 0; k < 2; ++k) dst[m][k] = *(const LAS bf16x8*)(lds + PG8_SA(b, h) + aoff + m * 2048 + k * 1024); } while (0)
; #define PG8_LDB(dst, b, h) do { _Pragma("unroll") for (int n = 0; n < 2; ++n) _Pragma("unroll") for (int k = 0; k < 2; ++k) dst[n][k] = *(const LAS bf16x8*)(lds + PG8_SB(b, h) + boff + n * 2048 + k * 1024); } while (0)
; #define PG8_MMA(ai, bj, At, Bt) do { __builtin_amdgcn_s_setprio(1); _Pragma("unroll") for (int m = 0; m < 4; ++m) _Pragma("unroll") for (int n = 0; n < 2; ++n) _Pragma("unroll") for (int k = 0; k < 2; ++k) \
;         acc[ai][bj][m][n] = __builtin_amdgcn_mfma_f32_16x16x32_bf16(Bt[n][k], At[m][k], acc[ai][bj][m][n], 0, 0, 0); __builtin_amdgcn_s_setprio(0); } while (0)
; #define PG8_WAIT_V(n) asm volatile("s_waitcnt vmcnt(" #n ")" ::: "memory")
; #define PG8_WAIT_L(n) asm volatile("s_waitcnt lgkmcnt(" #n ")" ::: "memory")
; #define PG8_BAR __builtin_amdgcn_s_barrier()
; #define PG8_SCHED __builtin_amdgcn_sched_barrier(0)
; template <class Epi, class Sched>
; __device__ __forceinline__ void gemm_phase(LAS unsigned char* lds, const Gemm g, const Sched& S, const Epi& E) {
;     ...
;             PG8_STAGE(PG8_SB(0, 1), b2 + hstep, voffB);
;             PG8_WAIT_V(6); PG8_BAR; PG8_MMA(1, 1, At, B1); PG8_BAR;
;             PG8_LDB(B0, 1, 0); PG8_SCHED; PG8_LDA(At, 1, 0); PG8_STAGE(PG8_SA(0, 1), a2 + hstep, voffA);
;             PG8_WAIT_L(8); PG8_BAR; PG8_WAIT_L(0); PG8_MMA(0, 0, At, B0); PG8_BAR; PG8_SCHED;
;             PG8_LDB(B1, 1, 1); PG8_STAGE(PG8_SB(1, 0), b3, voffB);
;             PG8_BAR; PG8_WAIT_L(0); PG8_MMA(0, 1, At, B1); PG8_BAR;
	s_add_u32 s28, s52, 0x200000
	s_addc_u32 s29, s53, 0
	s_add_i32 s38, s39, s60
	s_mov_b32 m0, s38
	s_nop 0
	global_load_lds_dwordx4 v0, s[28:29]
	s_add_i32 m0, s38, 0x2000
	s_nop 0
	global_load_lds_dwordx4 v146, s[28:29]
	s_add_u32 s28, s54, 0x200000
	s_addc_u32 s29, s55, 0
	s_mov_b32 m0, s62
	s_nop 0
	global_load_lds_dwordx4 v0, s[28:29]
	s_mov_b32 m0, s63
	s_nop 0
	global_load_lds_dwordx4 v146, s[28:29]
	s_add_i32 s38, 0, 0x18000
	v_add_u32_e32 v78, s38, v163
	ds_read_b128 v[66:69], v78
	ds_read_b128 v[70:73], v78 offset:1024
	ds_read_b128 v[74:77], v78 offset:2048
	ds_read_b128 v[78:81], v78 offset:3072
	ds_read_b128 v[152:155], v165 offset:32768
	ds_read_b128 v[166:169], v165 offset:33792
	ds_read_b128 v[170:173], v165 offset:34816
	ds_read_b128 v[174:177], v165 offset:35840
	ds_read_b128 v[178:181], v165 offset:36864
	ds_read_b128 v[182:185], v165 offset:37888
	ds_read_b128 v[186:189], v165 offset:38912
	ds_read_b128 v[190:193], v165 offset:39936
	s_add_i32 s39, 0, 0x1c000
	v_add_u32_e32 v210, s39, v163
	ds_read_b128 v[194:197], v210
	ds_read_b128 v[198:201], v210 offset:1024
	ds_read_b128 v[202:205], v210 offset:2048
	ds_read_b128 v[210:213], v210 offset:3072
	s_waitcnt lgkmcnt(4)
	s_barrier
	s_waitcnt lgkmcnt(0)
	v_mfma_f32_16x16x32_bf16 v[142:145], v[66:69], v[152:155], v[142:145]
	v_mfma_f32_16x16x32_bf16 v[138:141], v[74:77], v[152:155], v[138:141]
	v_mfma_f32_16x16x32_bf16 v[126:129], v[66:69], v[170:173], v[126:129]
	v_mfma_f32_16x16x32_bf16 v[122:125], v[74:77], v[170:173], v[122:125]
	v_mfma_f32_16x16x32_bf16 v[110:113], v[66:69], v[178:181], v[110:113]
	v_mfma_f32_16x16x32_bf16 v[106:109], v[74:77], v[178:181], v[106:109]
	v_mfma_f32_16x16x32_bf16 v[102:105], v[66:69], v[186:189], v[102:105]
	v_mfma_f32_16x16x32_bf16 v[98:101], v[74:77], v[186:189], v[98:101]
	v_mfma_f32_16x16x32_bf16 v[142:145], v[70:73], v[166:169], v[142:145]
	v_mfma_f32_16x16x32_bf16 v[138:141], v[78:81], v[166:169], v[138:141]
	v_mfma_f32_16x16x32_bf16 v[126:129], v[70:73], v[174:177], v[126:129]
	v_mfma_f32_16x16x32_bf16 v[122:125], v[78:81], v[174:177], v[122:125]
	v_mfma_f32_16x16x32_bf16 v[110:113], v[70:73], v[182:185], v[110:113]
	v_mfma_f32_16x16x32_bf16 v[106:109], v[78:81], v[182:185], v[106:109]
	v_mfma_f32_16x16x32_bf16 v[102:105], v[70:73], v[190:193], v[102:105]
	v_mfma_f32_16x16x32_bf16 v[98:101], v[78:81], v[190:193], v[98:101]
	v_mfma_f32_16x16x32_bf16 v[134:137], v[194:197], v[152:155], v[134:137]
	v_mfma_f32_16x16x32_bf16 v[130:133], v[202:205], v[152:155], v[130:133]
	v_mfma_f32_16x16x32_bf16 v[118:121], v[194:197], v[170:173], v[118:121]
	v_mfma_f32_16x16x32_bf16 v[114:117], v[202:205], v[170:173], v[114:117]
	v_mfma_f32_16x16x32_bf16 v[94:97], v[194:197], v[178:181], v[94:97]
	v_mfma_f32_16x16x32_bf16 v[90:93], v[202:205], v[178:181], v[90:93]
	v_mfma_f32_16x16x32_bf16 v[86:89], v[194:197], v[186:189], v[86:89]
	v_mfma_f32_16x16x32_bf16 v[82:85], v[202:205], v[186:189], v[82:85]
	v_mfma_f32_16x16x32_bf16 v[134:137], v[198:201], v[166:169], v[134:137]
	v_mfma_f32_16x16x32_bf16 v[130:133], v[210:213], v[166:169], v[130:133]
	v_mfma_f32_16x16x32_bf16 v[118:121], v[198:201], v[174:177], v[118:121]
	v_mfma_f32_16x16x32_bf16 v[114:117], v[210:213], v[174:177], v[114:117]
	v_mfma_f32_16x16x32_bf16 v[94:97], v[198:201], v[182:185], v[94:97]
	v_mfma_f32_16x16x32_bf16 v[90:93], v[210:213], v[182:185], v[90:93]
	v_mfma_f32_16x16x32_bf16 v[86:89], v[198:201], v[190:193], v[86:89]
	v_mfma_f32_16x16x32_bf16 v[82:85], v[210:213], v[190:193], v[82:85]
	s_barrier
; #define PG8_STAGE(bufoff, gbase, voff) do { _Pragma("unroll") for (int _i = 0; _i < 2; ++_i) \
;         __builtin_amdgcn_global_load_lds((const unsigned*)((const char*)(gbase) + (voff)[_i]), (LAS unsigned*)(lds + (bufoff) + ldsw + _i * 8192), 16, 0, 0); } while (0)
; #define PG8_LDA(dst, b, h) do { _Pragma("unroll") for (int m = 0; m < 4; ++m) _Pragma("unroll") for (int k = 0; k < 2; ++k) dst[m][k] = *(const LAS bf16x8*)(lds + PG8_SA(b, h) + aoff + m * 2048 + k * 1024); } while (0)
; #define PG8_LDB(dst, b, h) do { _Pragma("unroll") for (int n = 0; n < 2; ++n) _Pragma("unroll") for (int k = 0; k < 2; ++k) dst[n][k] = *(const LAS bf16x8*)(lds + PG8_SB(b, h) + boff + n * 2048 + k * 1024); } while (0)
; #define PG8_MMA(ai, bj, At, Bt) do { __builtin_amdgcn_s_setprio(1); _Pragma("unroll") for (int m = 0; m < 4; ++m) _Pragma("unroll") for (int n = 0; n < 2; ++n) _Pragma("unroll") for (int k = 0; k < 2; ++k) \
;         acc[ai][bj][m][n] = __builtin_amdgcn_mfma_f32_16x16x32_bf16(Bt[n][k], At[m][k], acc[ai][bj][m][n], 0, 0, 0); __builtin_amdgcn_s_setprio(0); } while (0)
; #define PG8_WAIT_V(n) asm volatile("s_waitcnt vmcnt(" #n ")" ::: "memory")
; #define PG8_WAIT_L(n) asm volatile("s_waitcnt lgkmcnt(" #n ")" ::: "memory")
; #define PG8_BAR __builtin_amdgcn_s_barrier()
; #define PG8_SCHED __builtin_amdgcn_sched_barrier(0)
; template <class Epi, class Sched>
; __device__ __forceinline__ void gemm_phase(LAS unsigned char* lds, const Gemm g, const Sched& S, const Epi& E) {
;     ...
;             PG8_LDB(B1, 1, 1); PG8_STAGE(PG8_SB(1, 0), b3, voffB);
;             PG8_BAR; PG8_WAIT_L(0); PG8_MMA(0, 1, At, B1); PG8_BAR;
;             PG8_LDA(At, 1, 1); PG8_STAGE(PG8_SA(1, 0), a3, voffA);
;             PG8_BAR; PG8_WAIT_L(0); PG8_MMA(1, 0, At, B0); PG8_BAR; PG8_SCHED;
;             PG8_STAGE(PG8_SB(1, 1), b3 + hstep, voffB);
;             PG8_WAIT_V(6); PG8_BAR; PG8_MMA(1, 1, At, B1); PG8_BAR;
;         }
;         E(acc, cur, wr, wc, fr, fq);
;         if (!has_next) break;
	s_add_i32 s28, s38, s60
	s_add_u32 s100, s52, s36
	s_addc_u32 s101, s53, s37
	s_mov_b32 m0, s28
	s_nop 0
	global_load_lds_dwordx4 v0, s[100:101]
	s_add_i32 m0, s28, 0x2000
	s_nop 0
	global_load_lds_dwordx4 v146, s[100:101]
	s_mov_b32 m0, s66
	s_add_u32 s100, s54, s36
	s_addc_u32 s101, s55, s37
	global_load_lds_dwordx4 v0, s[100:101]
	s_mov_b32 m0, s67
	s_nop 0
	global_load_lds_dwordx4 v146, s[100:101]
	ds_read_b128 v[152:155], v165 offset:49152
	ds_read_b128 v[166:169], v165 offset:50176
	ds_read_b128 v[170:173], v165 offset:51200
	ds_read_b128 v[174:177], v165 offset:52224
	ds_read_b128 v[178:181], v165 offset:53248
	ds_read_b128 v[182:185], v165 offset:54272
	ds_read_b128 v[186:189], v165 offset:55296
	ds_read_b128 v[190:193], v165 offset:56320
	s_waitcnt vmcnt(4)
	s_waitcnt lgkmcnt(0)
	s_barrier
	v_mfma_f32_16x16x32_bf16 v[62:65], v[66:69], v[152:155], v[62:65]
	v_mfma_f32_16x16x32_bf16 v[58:61], v[74:77], v[152:155], v[58:61]
	v_mfma_f32_16x16x32_bf16 v[46:49], v[66:69], v[170:173], v[46:49]
	v_mfma_f32_16x16x32_bf16 v[42:45], v[74:77], v[170:173], v[42:45]
	v_mfma_f32_16x16x32_bf16 v[30:33], v[66:69], v[178:181], v[30:33]
	v_mfma_f32_16x16x32_bf16 v[26:29], v[74:77], v[178:181], v[26:29]
	v_mfma_f32_16x16x32_bf16 v[22:25], v[66:69], v[186:189], v[22:25]
	v_mfma_f32_16x16x32_bf16 v[14:17], v[74:77], v[186:189], v[14:17]
	v_mfma_f32_16x16x32_bf16 v[62:65], v[70:73], v[166:169], v[62:65]
	v_mfma_f32_16x16x32_bf16 v[58:61], v[78:81], v[166:169], v[58:61]
	v_mfma_f32_16x16x32_bf16 v[46:49], v[70:73], v[174:177], v[46:49]
	v_mfma_f32_16x16x32_bf16 v[42:45], v[78:81], v[174:177], v[42:45]
	v_mfma_f32_16x16x32_bf16 v[30:33], v[70:73], v[182:185], v[30:33]
	v_mfma_f32_16x16x32_bf16 v[26:29], v[78:81], v[182:185], v[26:29]
	v_mfma_f32_16x16x32_bf16 v[22:25], v[70:73], v[190:193], v[22:25]
	v_mfma_f32_16x16x32_bf16 v[14:17], v[78:81], v[190:193], v[14:17]
	s_add_u32 s28, s52, 0x200080
	s_addc_u32 s29, s53, 0
	s_add_i32 s38, s39, s60
	s_mov_b32 m0, s38
	s_nop 0
	global_load_lds_dwordx4 v0, s[28:29]
	s_add_i32 m0, s38, 0x2000
	s_nop 0
	global_load_lds_dwordx4 v146, s[28:29]
	v_mfma_f32_16x16x32_bf16 v[54:57], v[194:197], v[152:155], v[54:57]
	v_mfma_f32_16x16x32_bf16 v[50:53], v[202:205], v[152:155], v[50:53]
	v_mfma_f32_16x16x32_bf16 v[38:41], v[194:197], v[170:173], v[38:41]
	v_mfma_f32_16x16x32_bf16 v[34:37], v[202:205], v[170:173], v[34:37]
	v_mfma_f32_16x16x32_bf16 v[18:21], v[194:197], v[178:181], v[18:21]
	v_mfma_f32_16x16x32_bf16 v[10:13], v[202:205], v[178:181], v[10:13]
	v_mfma_f32_16x16x32_bf16 v[6:9], v[194:197], v[186:189], v[6:9]
	v_mfma_f32_16x16x32_bf16 v[2:5], v[202:205], v[186:189], v[2:5]
	v_mfma_f32_16x16x32_bf16 v[54:57], v[198:201], v[166:169], v[54:57]
	v_mfma_f32_16x16x32_bf16 v[50:53], v[210:213], v[166:169], v[50:53]
	v_mfma_f32_16x16x32_bf16 v[38:41], v[198:201], v[174:177], v[38:41]
	v_mfma_f32_16x16x32_bf16 v[34:37], v[210:213], v[174:177], v[34:37]
	v_mfma_f32_16x16x32_bf16 v[18:21], v[198:201], v[182:185], v[18:21]
	v_mfma_f32_16x16x32_bf16 v[10:13], v[210:213], v[182:185], v[10:13]
	v_mfma_f32_16x16x32_bf16 v[6:9], v[198:201], v[190:193], v[6:9]
	v_mfma_f32_16x16x32_bf16 v[2:5], v[210:213], v[190:193], v[2:5]
	s_add_i32 s75, s75, 2
	s_add_u32 s73, s73, 0x100
	s_addc_u32 s74, s74, 0
	s_cmpk_gt_u32 s75, 0x7d
	s_mov_b64 s[28:29], s[50:51]
	s_barrier
	s_cbranch_scc0 .LBB0_44
	s_cmp_lt_i32 s8, 64
	s_cselect_b64 s[50:51], -1, 0
	s_cmp_gt_i32 s8, 63
	s_cbranch_scc0 .LBB0_35
	s_mov_b64 s[52:53], 0x18000
	s_mov_b64 s[28:29], s[46:47]
	s_branch .LBB0_36

; #define PG8_STAGE(bufoff, gbase, voff) do { _Pragma("unroll") for (int _i = 0; _i < 2; ++_i) \
;         __builtin_amdgcn_global_load_lds((const unsigned*)((const char*)(gbase) + (voff)[_i]), (LAS unsigned*)(lds + (bufoff) + ldsw + _i * 8192), 16, 0, 0); } while (0)
; #define PG8_LDA(dst, b, h) do { _Pragma("unroll") for (int m = 0; m < 4; ++m) _Pragma("unroll") for (int k = 0; k < 2; ++k) dst[m][k] = *(const LAS bf16x8*)(lds + PG8_SA(b, h) + aoff + m * 2048 + k * 1024); } while (0)
; #define PG8_LDB(dst, b, h) do { _Pragma("unroll") for (int n = 0; n < 2; ++n) _Pragma("unroll") for (int k = 0; k < 2; ++k) dst[n][k] = *(const LAS bf16x8*)(lds + PG8_SB(b, h) + boff + n * 2048 + k * 1024); } while (0)
; #define PG8_MMA(ai, bj, At, Bt) do { __builtin_amdgcn_s_setprio(1); _Pragma("unroll") for (int m = 0; m < 4; ++m) _Pragma("unroll") for (int n = 0; n < 2; ++n) _Pragma("unroll") for (int k = 0; k < 2; ++k) \
;         acc[ai][bj][m][n] = __builtin_amdgcn_mfma_f32_16x16x32_bf16(Bt[n][k], At[m][k], acc[ai][bj][m][n], 0, 0, 0); __builtin_amdgcn_s_setprio(0); } while (0)
; #define PG8_WAIT_V(n) asm volatile("s_waitcnt vmcnt(" #n ")" ::: "memory")
; #define PG8_WAIT_L(n) asm volatile("s_waitcnt lgkmcnt(" #n ")" ::: "memory")
; #define PG8_BAR __builtin_amdgcn_s_barrier()
; #define PG8_SCHED __builtin_amdgcn_sched_barrier(0)
; template <class Epi, class Sched>
; __device__ __forceinline__ void gemm_phase(LAS unsigned char* lds, const Gemm g, const Sched& S, const Epi& E) {
;     ...
;             PG8_LDB(B0, 0, 0); PG8_SCHED; PG8_LDA(At, 0, 0); PG8_STAGE(PG8_SA(1, 1), a1 + hstep, voffA);
;             PG8_WAIT_L(8); PG8_BAR; PG8_WAIT_L(0); PG8_MMA(0, 0, At, B0); PG8_BAR; PG8_SCHED;
;             PG8_LDB(B1, 0, 1); PG8_STAGE(PG8_SB(0, 0), b2, voffB);
;             PG8_BAR; PG8_WAIT_L(0); PG8_MMA(0, 1, At, B1); PG8_BAR;
;             PG8_LDA(At, 0, 1); PG8_STAGE(PG8_SA(0, 0), a2, voffA);
;             PG8_BAR; PG8_WAIT_L(0); PG8_MMA(1, 0, At, B0); PG8_BAR; PG8_SCHED;
;             PG8_STAGE(PG8_SB(0, 1), b2 + hstep, voffB);
;             PG8_WAIT_V(6); PG8_BAR; PG8_MMA(1, 1, At, B1); PG8_BAR;
.LBB0_58:
	s_add_u32 s52, s50, 0x100
	s_addc_u32 s53, s51, 0
	s_cmp_eq_u32 s71, 28
	s_cselect_b32 s57, s11, s53
	s_cselect_b32 s56, s29, s52
	s_cselect_b32 s55, s41, s70
	s_cselect_b32 s54, s43, s69
	v_lshl_add_u64 v[156:157], s[50:51], 0, v[134:135]
	s_add_i32 m0, s25, 0xc000
	s_nop 0
	global_load_lds_dwordx4 v[156:157], off
	v_lshl_add_u64 v[156:157], s[50:51], 0, v[132:133]
	s_add_i32 m0, s25, 0xe000
	s_nop 0
	global_load_lds_dwordx4 v[156:157], off
	s_add_i32 s38, 0, 0x10000
	v_add_u32_e32 v152, s38, v137
	ds_read_b128 v[140:143], v152
	ds_read_b128 v[144:147], v152 offset:1024
	ds_read_b128 v[148:151], v152 offset:2048
	ds_read_b128 v[152:155], v152 offset:3072
	ds_read_b128 v[160:163], v139
	ds_read_b128 v[164:167], v139 offset:1024
	ds_read_b128 v[168:171], v139 offset:2048
	ds_read_b128 v[172:175], v139 offset:3072
	ds_read_b128 v[176:179], v139 offset:4096
	ds_read_b128 v[180:183], v139 offset:5120
	ds_read_b128 v[184:187], v139 offset:6144
	ds_read_b128 v[188:191], v139 offset:7168
	s_add_i32 s50, 0, 0x14000
	v_add_u32_e32 v156, s50, v137
	ds_read_b128 v[192:195], v156
	ds_read_b128 v[196:199], v156 offset:1024
	ds_read_b128 v[200:203], v156 offset:2048
	ds_read_b128 v[204:207], v156 offset:3072
	s_waitcnt lgkmcnt(4)
	s_barrier
	s_waitcnt lgkmcnt(0)
	v_mfma_f32_16x16x32_bf16 v[126:129], v[140:143], v[160:163], v[126:129]
	v_mfma_f32_16x16x32_bf16 v[122:125], v[148:151], v[160:163], v[122:125]
	v_mfma_f32_16x16x32_bf16 v[118:121], v[140:143], v[168:171], v[118:121]
	v_mfma_f32_16x16x32_bf16 v[114:117], v[148:151], v[168:171], v[114:117]
	v_mfma_f32_16x16x32_bf16 v[106:109], v[140:143], v[176:179], v[106:109]
	v_mfma_f32_16x16x32_bf16 v[98:101], v[148:151], v[176:179], v[98:101]
	v_mfma_f32_16x16x32_bf16 v[90:93], v[140:143], v[184:187], v[90:93]
	v_mfma_f32_16x16x32_bf16 v[82:85], v[148:151], v[184:187], v[82:85]
	v_mfma_f32_16x16x32_bf16 v[126:129], v[144:147], v[164:167], v[126:129]
	v_mfma_f32_16x16x32_bf16 v[122:125], v[152:155], v[164:167], v[122:125]
	v_mfma_f32_16x16x32_bf16 v[118:121], v[144:147], v[172:175], v[118:121]
	v_mfma_f32_16x16x32_bf16 v[114:117], v[152:155], v[172:175], v[114:117]
	v_mfma_f32_16x16x32_bf16 v[106:109], v[144:147], v[180:183], v[106:109]
	v_mfma_f32_16x16x32_bf16 v[98:101], v[152:155], v[180:183], v[98:101]
	v_mfma_f32_16x16x32_bf16 v[90:93], v[144:147], v[188:191], v[90:93]
	v_mfma_f32_16x16x32_bf16 v[82:85], v[152:155], v[188:191], v[82:85]
	v_mfma_f32_16x16x32_bf16 v[110:113], v[192:195], v[160:163], v[110:113]
	v_mfma_f32_16x16x32_bf16 v[102:105], v[200:203], v[160:163], v[102:105]
	v_mfma_f32_16x16x32_bf16 v[94:97], v[192:195], v[168:171], v[94:97]
	v_mfma_f32_16x16x32_bf16 v[86:89], v[200:203], v[168:171], v[86:89]
	v_mfma_f32_16x16x32_bf16 v[78:81], v[192:195], v[176:179], v[78:81]
	v_mfma_f32_16x16x32_bf16 v[74:77], v[200:203], v[176:179], v[74:77]
	v_mfma_f32_16x16x32_bf16 v[70:73], v[192:195], v[184:187], v[70:73]
	v_mfma_f32_16x16x32_bf16 v[66:69], v[200:203], v[184:187], v[66:69]
	v_mfma_f32_16x16x32_bf16 v[110:113], v[196:199], v[164:167], v[110:113]
	v_mfma_f32_16x16x32_bf16 v[102:105], v[204:207], v[164:167], v[102:105]
	v_mfma_f32_16x16x32_bf16 v[94:97], v[196:199], v[172:175], v[94:97]
	v_mfma_f32_16x16x32_bf16 v[86:89], v[204:207], v[172:175], v[86:89]
	v_mfma_f32_16x16x32_bf16 v[78:81], v[196:199], v[180:183], v[78:81]
	v_mfma_f32_16x16x32_bf16 v[74:77], v[204:207], v[180:183], v[74:77]
	v_mfma_f32_16x16x32_bf16 v[70:73], v[196:199], v[188:191], v[70:73]
	v_mfma_f32_16x16x32_bf16 v[66:69], v[204:207], v[188:191], v[66:69]
	s_barrier
	s_add_i32 s38, s38, s63
	s_mov_b32 m0, s38
	s_nop 0
	global_load_lds_dwordx4 v0, s[54:55]
	s_add_i32 m0, s38, 0x2000
	s_nop 0
	global_load_lds_dwordx4 v130, s[54:55]
	s_mov_b32 m0, s25
	s_nop 0
	global_load_lds_dwordx4 v0, s[56:57]
	s_mov_b32 m0, s27
	s_nop 0
	global_load_lds_dwordx4 v130, s[56:57]
	ds_read_b128 v[160:163], v139 offset:16384
	ds_read_b128 v[164:167], v139 offset:17408
	ds_read_b128 v[168:171], v139 offset:18432
	ds_read_b128 v[172:175], v139 offset:19456
	ds_read_b128 v[176:179], v139 offset:20480
	ds_read_b128 v[180:183], v139 offset:21504
	ds_read_b128 v[184:187], v139 offset:22528
	ds_read_b128 v[188:191], v139 offset:23552
	s_waitcnt vmcnt(4)
	s_waitcnt lgkmcnt(0)
	s_barrier
	v_mfma_f32_16x16x32_bf16 v[62:65], v[140:143], v[160:163], v[62:65]
	v_mfma_f32_16x16x32_bf16 v[58:61], v[148:151], v[160:163], v[58:61]
	v_mfma_f32_16x16x32_bf16 v[54:57], v[140:143], v[168:171], v[54:57]
	v_mfma_f32_16x16x32_bf16 v[50:53], v[148:151], v[168:171], v[50:53]
	v_mfma_f32_16x16x32_bf16 v[38:41], v[140:143], v[176:179], v[38:41]
	v_mfma_f32_16x16x32_bf16 v[34:37], v[148:151], v[176:179], v[34:37]
	v_mfma_f32_16x16x32_bf16 v[22:25], v[140:143], v[184:187], v[22:25]
	v_mfma_f32_16x16x32_bf16 v[18:21], v[148:151], v[184:187], v[18:21]
	v_mfma_f32_16x16x32_bf16 v[62:65], v[144:147], v[164:167], v[62:65]
	v_mfma_f32_16x16x32_bf16 v[58:61], v[152:155], v[164:167], v[58:61]
	v_mfma_f32_16x16x32_bf16 v[54:57], v[144:147], v[172:175], v[54:57]
	v_mfma_f32_16x16x32_bf16 v[50:53], v[152:155], v[172:175], v[50:53]
	v_mfma_f32_16x16x32_bf16 v[38:41], v[144:147], v[180:183], v[38:41]
	v_mfma_f32_16x16x32_bf16 v[34:37], v[152:155], v[180:183], v[34:37]
	v_mfma_f32_16x16x32_bf16 v[22:25], v[144:147], v[188:191], v[22:25]
	v_mfma_f32_16x16x32_bf16 v[18:21], v[152:155], v[188:191], v[18:21]
	v_mfma_f32_16x16x32_bf16 v[46:49], v[192:195], v[160:163], v[46:49]
	v_mfma_f32_16x16x32_bf16 v[42:45], v[200:203], v[160:163], v[42:45]
	v_mfma_f32_16x16x32_bf16 v[30:33], v[192:195], v[168:171], v[30:33]
	v_mfma_f32_16x16x32_bf16 v[26:29], v[200:203], v[168:171], v[26:29]
	v_mfma_f32_16x16x32_bf16 v[14:17], v[192:195], v[176:179], v[14:17]
	v_mfma_f32_16x16x32_bf16 v[10:13], v[200:203], v[176:179], v[10:13]
	v_mfma_f32_16x16x32_bf16 v[6:9], v[192:195], v[184:187], v[6:9]
	v_mfma_f32_16x16x32_bf16 v[2:5], v[200:203], v[184:187], v[2:5]
	v_mfma_f32_16x16x32_bf16 v[46:49], v[196:199], v[164:167], v[46:49]
	v_mfma_f32_16x16x32_bf16 v[42:45], v[204:207], v[164:167], v[42:45]
	v_mfma_f32_16x16x32_bf16 v[30:33], v[196:199], v[172:175], v[30:33]
	v_mfma_f32_16x16x32_bf16 v[26:29], v[204:207], v[172:175], v[26:29]
	v_mfma_f32_16x16x32_bf16 v[14:17], v[196:199], v[180:183], v[14:17]
	v_mfma_f32_16x16x32_bf16 v[10:13], v[204:207], v[180:183], v[10:13]
	v_mfma_f32_16x16x32_bf16 v[6:9], v[196:199], v[188:191], v[6:9]
	v_mfma_f32_16x16x32_bf16 v[2:5], v[204:207], v[188:191], v[2:5]
	s_barrier
; #define PG8_STAGE(bufoff, gbase, voff) do { _Pragma("unroll") for (int _i = 0; _i < 2; ++_i) \
;         __builtin_amdgcn_global_load_lds((const unsigned*)((const char*)(gbase) + (voff)[_i]), (LAS unsigned*)(lds + (bufoff) + ldsw + _i * 8192), 16, 0, 0); } while (0)
; #define PG8_LDA(dst, b, h) do { _Pragma("unroll") for (int m = 0; m < 4; ++m) _Pragma("unroll") for (int k = 0; k < 2; ++k) dst[m][k] = *(const LAS bf16x8*)(lds + PG8_SA(b, h) + aoff + m * 2048 + k * 1024); } while (0)
; #define PG8_LDB(dst, b, h) do { _Pragma("unroll") for (int n = 0; n < 2; ++n) _Pragma("unroll") for (int k = 0; k < 2; ++k) dst[n][k] = *(const LAS bf16x8*)(lds + PG8_SB(b, h) + boff + n * 2048 + k * 1024); } while (0)
; #define PG8_MMA(ai, bj, At, Bt) do { __builtin_amdgcn_s_setprio(1); _Pragma("unroll") for (int m = 0; m < 4; ++m) _Pragma("unroll") for (int n = 0; n < 2; ++n) _Pragma("unroll") for (int k = 0; k < 2; ++k) \
;         acc[ai][bj][m][n] = __builtin_amdgcn_mfma_f32_16x16x32_bf16(Bt[n][k], At[m][k], acc[ai][bj][m][n], 0, 0, 0); __builtin_amdgcn_s_setprio(0); } while (0)
; #define PG8_WAIT_V(n) asm volatile("s_waitcnt vmcnt(" #n ")" ::: "memory")
; #define PG8_WAIT_L(n) asm volatile("s_waitcnt lgkmcnt(" #n ")" ::: "memory")
; #define PG8_BAR __builtin_amdgcn_s_barrier()
; #define PG8_SCHED __builtin_amdgcn_sched_barrier(0)
; template <class Epi, class Sched>
; __device__ __forceinline__ void gemm_phase(LAS unsigned char* lds, const Gemm g, const Sched& S, const Epi& E) {
;     ...
;             PG8_STAGE(PG8_SB(0, 1), b2 + hstep, voffB);
;             PG8_WAIT_V(6); PG8_BAR; PG8_MMA(1, 1, At, B1); PG8_BAR;
;             PG8_LDB(B0, 1, 0); PG8_SCHED; PG8_LDA(At, 1, 0); PG8_STAGE(PG8_SA(0, 1), a2 + hstep, voffA);
;             PG8_WAIT_L(8); PG8_BAR; PG8_WAIT_L(0); PG8_MMA(0, 0, At, B0); PG8_BAR; PG8_SCHED;
;             PG8_LDB(B1, 1, 1); PG8_STAGE(PG8_SB(1, 0), b3, voffB);
;             PG8_BAR; PG8_WAIT_L(0); PG8_MMA(0, 1, At, B1); PG8_BAR;
;             PG8_LDA(At, 1, 1); PG8_STAGE(PG8_SA(1, 0), a3, voffA);
;             PG8_BAR; PG8_WAIT_L(0); PG8_MMA(1, 0, At, B0); PG8_BAR; PG8_SCHED;
;             PG8_STAGE(PG8_SB(1, 1), b3 + hstep, voffB);
	s_add_u32 s38, s54, 0x200000
	s_addc_u32 s39, s55, 0
	s_add_i32 s50, s50, s63
	s_mov_b32 m0, s50
	s_nop 0
	global_load_lds_dwordx4 v0, s[38:39]
	s_add_i32 m0, s50, 0x2000
	s_nop 0
	global_load_lds_dwordx4 v130, s[38:39]
	s_add_u32 s38, s56, 0x200000
	s_addc_u32 s39, s57, 0
	s_mov_b32 m0, s64
	s_nop 0
	global_load_lds_dwordx4 v0, s[38:39]
	s_mov_b32 m0, s65
	s_nop 0
	global_load_lds_dwordx4 v130, s[38:39]
	s_add_i32 s50, 0, 0x18000
	v_add_u32_e32 v152, s50, v137
	ds_read_b128 v[140:143], v152
	ds_read_b128 v[144:147], v152 offset:1024
	ds_read_b128 v[148:151], v152 offset:2048
	ds_read_b128 v[152:155], v152 offset:3072
	ds_read_b128 v[160:163], v139 offset:32768
	ds_read_b128 v[164:167], v139 offset:33792
	ds_read_b128 v[168:171], v139 offset:34816
	ds_read_b128 v[172:175], v139 offset:35840
	ds_read_b128 v[176:179], v139 offset:36864
	ds_read_b128 v[180:183], v139 offset:37888
	ds_read_b128 v[184:187], v139 offset:38912
	ds_read_b128 v[188:191], v139 offset:39936
	s_add_i32 s51, 0, 0x1c000
	v_add_u32_e32 v204, s51, v137
	ds_read_b128 v[192:195], v204
	ds_read_b128 v[196:199], v204 offset:1024
	ds_read_b128 v[200:203], v204 offset:2048
	ds_read_b128 v[204:207], v204 offset:3072
	s_waitcnt lgkmcnt(4)
	s_barrier
	s_waitcnt lgkmcnt(0)
	v_mfma_f32_16x16x32_bf16 v[126:129], v[140:143], v[160:163], v[126:129]
	v_mfma_f32_16x16x32_bf16 v[122:125], v[148:151], v[160:163], v[122:125]
	v_mfma_f32_16x16x32_bf16 v[118:121], v[140:143], v[168:171], v[118:121]
	v_mfma_f32_16x16x32_bf16 v[114:117], v[148:151], v[168:171], v[114:117]
	v_mfma_f32_16x16x32_bf16 v[106:109], v[140:143], v[176:179], v[106:109]
	v_mfma_f32_16x16x32_bf16 v[98:101], v[148:151], v[176:179], v[98:101]
	v_mfma_f32_16x16x32_bf16 v[90:93], v[140:143], v[184:187], v[90:93]
	v_mfma_f32_16x16x32_bf16 v[82:85], v[148:151], v[184:187], v[82:85]
	v_mfma_f32_16x16x32_bf16 v[126:129], v[144:147], v[164:167], v[126:129]
	v_mfma_f32_16x16x32_bf16 v[122:125], v[152:155], v[164:167], v[122:125]
	v_mfma_f32_16x16x32_bf16 v[118:121], v[144:147], v[172:175], v[118:121]
	v_mfma_f32_16x16x32_bf16 v[114:117], v[152:155], v[172:175], v[114:117]
	v_mfma_f32_16x16x32_bf16 v[106:109], v[144:147], v[180:183], v[106:109]
	v_mfma_f32_16x16x32_bf16 v[98:101], v[152:155], v[180:183], v[98:101]
	v_mfma_f32_16x16x32_bf16 v[90:93], v[144:147], v[188:191], v[90:93]
	v_mfma_f32_16x16x32_bf16 v[82:85], v[152:155], v[188:191], v[82:85]
	v_mfma_f32_16x16x32_bf16 v[110:113], v[192:195], v[160:163], v[110:113]
	v_mfma_f32_16x16x32_bf16 v[102:105], v[200:203], v[160:163], v[102:105]
	v_mfma_f32_16x16x32_bf16 v[94:97], v[192:195], v[168:171], v[94:97]
	v_mfma_f32_16x16x32_bf16 v[86:89], v[200:203], v[168:171], v[86:89]
	v_mfma_f32_16x16x32_bf16 v[78:81], v[192:195], v[176:179], v[78:81]
	v_mfma_f32_16x16x32_bf16 v[74:77], v[200:203], v[176:179], v[74:77]
	v_mfma_f32_16x16x32_bf16 v[70:73], v[192:195], v[184:187], v[70:73]
	v_mfma_f32_16x16x32_bf16 v[66:69], v[200:203], v[184:187], v[66:69]
	v_mfma_f32_16x16x32_bf16 v[110:113], v[196:199], v[164:167], v[110:113]
	v_mfma_f32_16x16x32_bf16 v[102:105], v[204:207], v[164:167], v[102:105]
	v_mfma_f32_16x16x32_bf16 v[94:97], v[196:199], v[172:175], v[94:97]
	v_mfma_f32_16x16x32_bf16 v[86:89], v[204:207], v[172:175], v[86:89]
	v_mfma_f32_16x16x32_bf16 v[78:81], v[196:199], v[180:183], v[78:81]
	v_mfma_f32_16x16x32_bf16 v[74:77], v[204:207], v[180:183], v[74:77]
	v_mfma_f32_16x16x32_bf16 v[70:73], v[196:199], v[188:191], v[70:73]
	v_mfma_f32_16x16x32_bf16 v[66:69], v[204:207], v[188:191], v[66:69]
	s_barrier
	s_add_i32 s38, s50, s63
	s_add_u32 s100, s54, s36
	s_addc_u32 s101, s55, s37
	s_mov_b32 m0, s38
	s_nop 0
	global_load_lds_dwordx4 v0, s[100:101]
	s_add_i32 m0, s38, 0x2000
	s_nop 0
	global_load_lds_dwordx4 v130, s[100:101]
	s_mov_b32 m0, s66
	s_add_u32 s100, s56, s36
	s_addc_u32 s101, s57, s37
	global_load_lds_dwordx4 v0, s[100:101]
	s_mov_b32 m0, s67
	s_nop 0
	global_load_lds_dwordx4 v130, s[100:101]
	ds_read_b128 v[160:163], v139 offset:49152
	ds_read_b128 v[164:167], v139 offset:50176
	ds_read_b128 v[168:171], v139 offset:51200
	ds_read_b128 v[172:175], v139 offset:52224
	ds_read_b128 v[176:179], v139 offset:53248
	ds_read_b128 v[180:183], v139 offset:54272
	ds_read_b128 v[184:187], v139 offset:55296
	ds_read_b128 v[188:191], v139 offset:56320
	s_waitcnt vmcnt(4)
	s_waitcnt lgkmcnt(0)
	s_barrier
; #define PG8_STAGE(bufoff, gbase, voff) do { _Pragma("unroll") for (int _i = 0; _i < 2; ++_i) \
;         __builtin_amdgcn_global_load_lds((const unsigned*)((const char*)(gbase) + (voff)[_i]), (LAS unsigned*)(lds + (bufoff) + ldsw + _i * 8192), 16, 0, 0); } while (0)
; #define PG8_LDA(dst, b, h) do { _Pragma("unroll") for (int m = 0; m < 4; ++m) _Pragma("unroll") for (int k = 0; k < 2; ++k) dst[m][k] = *(const LAS bf16x8*)(lds + PG8_SA(b, h) + aoff + m * 2048 + k * 1024); } while (0)
; #define PG8_MMA(ai, bj, At, Bt) do { __builtin_amdgcn_s_setprio(1); _Pragma("unroll") for (int m = 0; m < 4; ++m) _Pragma("unroll") for (int n = 0; n < 2; ++n) _Pragma("unroll") for (int k = 0; k < 2; ++k) \
;         acc[ai][bj][m][n] = __builtin_amdgcn_mfma_f32_16x16x32_bf16(Bt[n][k], At[m][k], acc[ai][bj][m][n], 0, 0, 0); __builtin_amdgcn_s_setprio(0); } while (0)
; #define PG8_WAIT_V(n) asm volatile("s_waitcnt vmcnt(" #n ")" ::: "memory")
; #define PG8_WAIT_L(n) asm volatile("s_waitcnt lgkmcnt(" #n ")" ::: "memory")
; #define PG8_BAR __builtin_amdgcn_s_barrier()
; #define PG8_SCHED __builtin_amdgcn_sched_barrier(0)
;     __device__ __forceinline__ void operator()(const f32x4 (&acc)[2][2][4][2], const Unit& u, int wr, int wc, int fr, int fq) const {
;         const int row0 = u.pm * BM + wr * 64 + fr, col0 = u.pn * BM + wc * 32 + 4 * fq;
;         float* base = part + (size_t)u.ks * Mp * ldc;
; #pragma unroll
;         for (int ai = 0; ai < 2; ++ai)
; #pragma unroll
;             for (int m = 0; m < 4; ++m) { float* rowp = base + (size_t)(row0 + ai * HALF + m * 16) * ldc + col0;
; #pragma unroll
;                 for (int bj = 0; bj < 2; ++bj)
; #pragma unroll
;                     for (int n = 0; n < 2; ++n) *(f32x4*)(rowp + bj * HALF + n * 16) = acc[ai][bj][m][n]; }
;     }
; template <class Epi, class Sched>
; __device__ __forceinline__ void gemm_phase(LAS unsigned char* lds, const Gemm g, const Sched& S, const Epi& E) {
;     ...
;             PG8_LDA(At, 1, 1); PG8_STAGE(PG8_SA(1, 0), a3, voffA);
;             PG8_BAR; PG8_WAIT_L(0); PG8_MMA(1, 0, At, B0); PG8_BAR; PG8_SCHED;
;             PG8_STAGE(PG8_SB(1, 1), b3 + hstep, voffB);
;             PG8_WAIT_V(6); PG8_BAR; PG8_MMA(1, 1, At, B1); PG8_BAR;
;         }
;         E(acc, cur, wr, wc, fr, fq);
;         if (!has_next) break;
	v_mfma_f32_16x16x32_bf16 v[62:65], v[140:143], v[160:163], v[62:65]
	v_mfma_f32_16x16x32_bf16 v[58:61], v[148:151], v[160:163], v[58:61]
	v_mfma_f32_16x16x32_bf16 v[54:57], v[140:143], v[168:171], v[54:57]
	v_mfma_f32_16x16x32_bf16 v[50:53], v[148:151], v[168:171], v[50:53]
	v_mfma_f32_16x16x32_bf16 v[38:41], v[140:143], v[176:179], v[38:41]
	v_mfma_f32_16x16x32_bf16 v[34:37], v[148:151], v[176:179], v[34:37]
	v_mfma_f32_16x16x32_bf16 v[22:25], v[140:143], v[184:187], v[22:25]
	v_mfma_f32_16x16x32_bf16 v[18:21], v[148:151], v[184:187], v[18:21]
	v_mfma_f32_16x16x32_bf16 v[62:65], v[144:147], v[164:167], v[62:65]
	v_mfma_f32_16x16x32_bf16 v[58:61], v[152:155], v[164:167], v[58:61]
	v_mfma_f32_16x16x32_bf16 v[54:57], v[144:147], v[172:175], v[54:57]
	v_mfma_f32_16x16x32_bf16 v[50:53], v[152:155], v[172:175], v[50:53]
	v_mfma_f32_16x16x32_bf16 v[38:41], v[144:147], v[180:183], v[38:41]
	v_mfma_f32_16x16x32_bf16 v[34:37], v[152:155], v[180:183], v[34:37]
	v_mfma_f32_16x16x32_bf16 v[22:25], v[144:147], v[188:191], v[22:25]
	v_mfma_f32_16x16x32_bf16 v[18:21], v[152:155], v[188:191], v[18:21]
	s_add_u32 s38, s54, 0x200080
	s_addc_u32 s39, s55, 0
	s_add_i32 s50, s51, s63
	s_mov_b32 m0, s50
	s_nop 0
	global_load_lds_dwordx4 v0, s[38:39]
	s_add_i32 m0, s50, 0x2000
	s_nop 0
	global_load_lds_dwordx4 v130, s[38:39]
	v_mfma_f32_16x16x32_bf16 v[46:49], v[192:195], v[160:163], v[46:49]
	v_mfma_f32_16x16x32_bf16 v[42:45], v[200:203], v[160:163], v[42:45]
	v_mfma_f32_16x16x32_bf16 v[30:33], v[192:195], v[168:171], v[30:33]
	v_mfma_f32_16x16x32_bf16 v[26:29], v[200:203], v[168:171], v[26:29]
	v_mfma_f32_16x16x32_bf16 v[14:17], v[192:195], v[176:179], v[14:17]
	v_mfma_f32_16x16x32_bf16 v[10:13], v[200:203], v[176:179], v[10:13]
	v_mfma_f32_16x16x32_bf16 v[6:9], v[192:195], v[184:187], v[6:9]
	v_mfma_f32_16x16x32_bf16 v[2:5], v[200:203], v[184:187], v[2:5]
	v_mfma_f32_16x16x32_bf16 v[46:49], v[196:199], v[164:167], v[46:49]
	v_mfma_f32_16x16x32_bf16 v[42:45], v[204:207], v[164:167], v[42:45]
	v_mfma_f32_16x16x32_bf16 v[30:33], v[196:199], v[172:175], v[30:33]
	v_mfma_f32_16x16x32_bf16 v[26:29], v[204:207], v[172:175], v[26:29]
	v_mfma_f32_16x16x32_bf16 v[14:17], v[196:199], v[180:183], v[14:17]
	v_mfma_f32_16x16x32_bf16 v[10:13], v[204:207], v[180:183], v[10:13]
	v_mfma_f32_16x16x32_bf16 v[6:9], v[196:199], v[188:191], v[6:9]
	v_mfma_f32_16x16x32_bf16 v[2:5], v[204:207], v[188:191], v[2:5]
	s_add_i32 s71, s71, 2
	s_add_u32 s69, s69, 0x100
	s_addc_u32 s70, s70, 0
	s_cmp_gt_u32 s71, 29
	s_mov_b64 s[50:51], s[52:53]
	s_barrier
	s_cbranch_scc0 .LBB0_58
	s_ashr_i32 s11, s10, 31
	s_lshl_b64 s[10:11], s[10:11], 24
	v_lshl_or_b32 v140, s26, 8, v138
	s_add_u32 s10, s8, s10
	v_lshl_add_u32 v142, s24, 8, v136
	s_addc_u32 s11, s9, s11
	v_ashrrev_i32_e32 v141, 31, v140
	v_ashrrev_i32_e32 v143, 31, v142
	v_lshl_add_u64 v[140:141], v[140:141], 2, s[10:11]
	v_lshlrev_b64 v[144:145], 13, v[142:143]
	v_lshl_add_u64 v[144:145], v[140:141], 0, v[144:145]
	global_store_dwordx4 v[144:145], v[126:129], off
	global_store_dwordx4 v[144:145], v[122:125], off offset:64
	global_store_dwordx4 v[144:145], v[110:113], off offset:512
	global_store_dwordx4 v[144:145], v[102:105], off offset:576
	s_mov_b64 s[10:11], 0x100000
	s_mov_b32 s26, s40
	v_or_b32_e32 v102, 16, v142
	v_ashrrev_i32_e32 v103, 31, v102
	v_lshlrev_b64 v[102:103], 13, v[102:103]
	v_lshl_add_u64 v[102:103], v[140:141], 0, v[102:103]
	global_store_dwordx4 v[102:103], v[118:121], off
	global_store_dwordx4 v[102:103], v[114:117], off offset:64
	global_store_dwordx4 v[102:103], v[94:97], off offset:512
	global_store_dwordx4 v[102:103], v[86:89], off offset:576
	s_mov_b32 s24, s42
	s_mov_b64 s[52:53], s[48:49]
	v_or_b32_e32 v86, 32, v142
	v_ashrrev_i32_e32 v87, 31, v86
	v_lshlrev_b64 v[86:87], 13, v[86:87]
	v_lshl_add_u64 v[86:87], v[140:141], 0, v[86:87]
	global_store_dwordx4 v[86:87], v[106:109], off
	global_store_dwordx4 v[86:87], v[98:101], off offset:64
	global_store_dwordx4 v[86:87], v[78:81], off offset:512
	global_store_dwordx4 v[86:87], v[74:77], off offset:576
	s_mov_b64 s[50:51], s[46:47]
	s_nop 0
	v_or_b32_e32 v74, 48, v142
	v_ashrrev_i32_e32 v75, 31, v74
	v_lshlrev_b64 v[74:75], 13, v[74:75]
	v_lshl_add_u64 v[74:75], v[140:141], 0, v[74:75]
	global_store_dwordx4 v[74:75], v[90:93], off
	global_store_dwordx4 v[74:75], v[82:85], off offset:64
	global_store_dwordx4 v[74:75], v[70:73], off offset:512
	global_store_dwordx4 v[74:75], v[66:69], off offset:576
	s_nop 1
	v_add_co_u32_e32 v68, vcc, s93, v144
	v_lshl_add_u64 v[66:67], v[144:145], 0, s[10:11]
	s_nop 0
	v_addc_co_u32_e32 v69, vcc, 0, v145, vcc
	s_mov_b64 s[10:11], 0x120000
	global_store_dwordx4 v[68:69], v[62:65], off
	global_store_dwordx4 v[66:67], v[58:61], off offset:64
	global_store_dwordx4 v[66:67], v[46:49], off offset:512
	global_store_dwordx4 v[66:67], v[42:45], off offset:576
	s_nop 1
	v_lshl_add_u64 v[42:43], v[144:145], 0, s[10:11]
	s_mov_b32 s10, 0x120000
	v_add_co_u32_e32 v44, vcc, s10, v144
	s_mov_b64 s[10:11], 0x140000
	s_nop 0
	v_addc_co_u32_e32 v45, vcc, 0, v145, vcc
	global_store_dwordx4 v[44:45], v[54:57], off
	global_store_dwordx4 v[42:43], v[50:53], off offset:64
	global_store_dwordx4 v[42:43], v[30:33], off offset:512
	global_store_dwordx4 v[42:43], v[26:29], off offset:576
	s_nop 1
	v_lshl_add_u64 v[26:27], v[144:145], 0, s[10:11]
	s_mov_b32 s10, 0x140000
	v_add_co_u32_e32 v28, vcc, s10, v144
	s_mov_b64 s[10:11], 0x160000
	s_nop 0
	v_addc_co_u32_e32 v29, vcc, 0, v145, vcc
	global_store_dwordx4 v[28:29], v[38:41], off
	global_store_dwordx4 v[26:27], v[34:37], off offset:64
	global_store_dwordx4 v[26:27], v[14:17], off offset:512
	global_store_dwordx4 v[26:27], v[10:13], off offset:576
	s_nop 1
	v_add_co_u32_e32 v12, vcc, 0x160000, v144
	v_lshl_add_u64 v[10:11], v[144:145], 0, s[10:11]
	s_nop 0
	v_addc_co_u32_e32 v13, vcc, 0, v145, vcc
	s_and_b64 vcc, exec, s[44:45]
	s_mov_b32 s10, s28
	global_store_dwordx4 v[12:13], v[22:25], off
	global_store_dwordx4 v[10:11], v[18:21], off offset:64
	global_store_dwordx4 v[10:11], v[6:9], off offset:512
	global_store_dwordx4 v[10:11], v[2:5], off offset:576
	s_cbranch_vccz .LBB0_55
	s_waitcnt vmcnt(0)
	s_cmpk_gt_u32 s60, 0xff
	s_cbranch_scc1 .LBB0_62
	s_barrier

; #define PG8_STAGE(bufoff, gbase, voff) do { _Pragma("unroll") for (int _i = 0; _i < 2; ++_i) \
;         __builtin_amdgcn_global_load_lds((const unsigned*)((const char*)(gbase) + (voff)[_i]), (LAS unsigned*)(lds + (bufoff) + ldsw + _i * 8192), 16, 0, 0); } while (0)
; #define PG8_LDA(dst, b, h) do { _Pragma("unroll") for (int m = 0; m < 4; ++m) _Pragma("unroll") for (int k = 0; k < 2; ++k) dst[m][k] = *(const LAS bf16x8*)(lds + PG8_SA(b, h) + aoff + m * 2048 + k * 1024); } while (0)
; #define PG8_LDB(dst, b, h) do { _Pragma("unroll") for (int n = 0; n < 2; ++n) _Pragma("unroll") for (int k = 0; k < 2; ++k) dst[n][k] = *(const LAS bf16x8*)(lds + PG8_SB(b, h) + boff + n * 2048 + k * 1024); } while (0)
; #define PG8_MMA(ai, bj, At, Bt) do { __builtin_amdgcn_s_setprio(1); _Pragma("unroll") for (int m = 0; m < 4; ++m) _Pragma("unroll") for (int n = 0; n < 2; ++n) _Pragma("unroll") for (int k = 0; k < 2; ++k) \
;         acc[ai][bj][m][n] = __builtin_amdgcn_mfma_f32_16x16x32_bf16(Bt[n][k], At[m][k], acc[ai][bj][m][n], 0, 0, 0); __builtin_amdgcn_s_setprio(0); } while (0)
; #define PG8_WAIT_V(n) asm volatile("s_waitcnt vmcnt(" #n ")" ::: "memory")
; #define PG8_WAIT_L(n) asm volatile("s_waitcnt lgkmcnt(" #n ")" ::: "memory")
; #define PG8_BAR __builtin_amdgcn_s_barrier()
; #define PG8_SCHED __builtin_amdgcn_sched_barrier(0)
; template <class Epi, class Sched>
; __device__ __forceinline__ void gemm_phase(LAS unsigned char* lds, const Gemm g, const Sched& S, const Epi& E) {
;     ...
;             PG8_LDB(B0, 0, 0); PG8_SCHED; PG8_LDA(At, 0, 0); PG8_STAGE(PG8_SA(1, 1), a1 + hstep, voffA);
;             PG8_WAIT_L(8); PG8_BAR; PG8_WAIT_L(0); PG8_MMA(0, 0, At, B0); PG8_BAR; PG8_SCHED;
;             PG8_LDB(B1, 0, 1); PG8_STAGE(PG8_SB(0, 0), b2, voffB);
;             PG8_BAR; PG8_WAIT_L(0); PG8_MMA(0, 1, At, B1); PG8_BAR;
;             PG8_LDA(At, 0, 1); PG8_STAGE(PG8_SA(0, 0), a2, voffA);
;             PG8_BAR; PG8_WAIT_L(0); PG8_MMA(1, 0, At, B0); PG8_BAR; PG8_SCHED;
;             PG8_STAGE(PG8_SB(0, 1), b2 + hstep, voffB);
;             PG8_WAIT_V(6); PG8_BAR; PG8_MMA(1, 1, At, B1); PG8_BAR;
.LBB0_73:
	s_add_u32 s38, s46, 0xfff80080
	s_addc_u32 s39, s47, -1
	s_cmp_eq_u32 s73, 28
	s_cselect_b32 s51, s29, s39
	s_cselect_b32 s50, s69, s38
	s_cselect_b32 s49, s27, s72
	s_cselect_b32 s48, s70, s71
	s_add_i32 m0, s9, 0xc000
	s_nop 0
	global_load_lds_dwordx4 v138, s[46:47]
	s_add_i32 m0, s9, 0xe000
	s_nop 0
	global_load_lds_dwordx4 v136, s[46:47]
	s_add_i32 s74, 0, 0x10000
	v_add_u32_e32 v140, s74, v143
	ds_read_b128 v[146:149], v140
	ds_read_b128 v[150:153], v140 offset:1024
	ds_read_b128 v[154:157], v140 offset:2048
	ds_read_b128 v[160:163], v140 offset:3072
	ds_read_b128 v[164:167], v145
	ds_read_b128 v[168:171], v145 offset:1024
	ds_read_b128 v[172:175], v145 offset:2048
	ds_read_b128 v[176:179], v145 offset:3072
	ds_read_b128 v[180:183], v145 offset:4096
	ds_read_b128 v[184:187], v145 offset:5120
	ds_read_b128 v[188:191], v145 offset:6144
	ds_read_b128 v[192:195], v145 offset:7168
	s_add_i32 s75, 0, 0x14000
	v_add_u32_e32 v140, s75, v143
	ds_read_b128 v[196:199], v140
	ds_read_b128 v[200:203], v140 offset:1024
	ds_read_b128 v[204:207], v140 offset:2048
	ds_read_b128 v[210:213], v140 offset:3072
	s_waitcnt lgkmcnt(4)
	s_barrier
	s_waitcnt lgkmcnt(0)
	v_mfma_f32_16x16x32_bf16 v[126:129], v[146:149], v[164:167], v[126:129]
	v_mfma_f32_16x16x32_bf16 v[122:125], v[154:157], v[164:167], v[122:125]
	v_mfma_f32_16x16x32_bf16 v[110:113], v[146:149], v[172:175], v[110:113]
	v_mfma_f32_16x16x32_bf16 v[106:109], v[154:157], v[172:175], v[106:109]
	v_mfma_f32_16x16x32_bf16 v[94:97], v[146:149], v[180:183], v[94:97]
	v_mfma_f32_16x16x32_bf16 v[90:93], v[154:157], v[180:183], v[90:93]
	v_mfma_f32_16x16x32_bf16 v[78:81], v[146:149], v[188:191], v[78:81]
	v_mfma_f32_16x16x32_bf16 v[74:77], v[154:157], v[188:191], v[74:77]
	v_mfma_f32_16x16x32_bf16 v[126:129], v[150:153], v[168:171], v[126:129]
	v_mfma_f32_16x16x32_bf16 v[122:125], v[160:163], v[168:171], v[122:125]
	v_mfma_f32_16x16x32_bf16 v[110:113], v[150:153], v[176:179], v[110:113]
	v_mfma_f32_16x16x32_bf16 v[106:109], v[160:163], v[176:179], v[106:109]
	v_mfma_f32_16x16x32_bf16 v[94:97], v[150:153], v[184:187], v[94:97]
	v_mfma_f32_16x16x32_bf16 v[90:93], v[160:163], v[184:187], v[90:93]
	v_mfma_f32_16x16x32_bf16 v[78:81], v[150:153], v[192:195], v[78:81]
	v_mfma_f32_16x16x32_bf16 v[74:77], v[160:163], v[192:195], v[74:77]
	v_mfma_f32_16x16x32_bf16 v[118:121], v[196:199], v[164:167], v[118:121]
	v_mfma_f32_16x16x32_bf16 v[114:117], v[204:207], v[164:167], v[114:117]
	v_mfma_f32_16x16x32_bf16 v[102:105], v[196:199], v[172:175], v[102:105]
	v_mfma_f32_16x16x32_bf16 v[98:101], v[204:207], v[172:175], v[98:101]
	v_mfma_f32_16x16x32_bf16 v[86:89], v[196:199], v[180:183], v[86:89]
	v_mfma_f32_16x16x32_bf16 v[82:85], v[204:207], v[180:183], v[82:85]
	v_mfma_f32_16x16x32_bf16 v[70:73], v[196:199], v[188:191], v[70:73]
	v_mfma_f32_16x16x32_bf16 v[66:69], v[204:207], v[188:191], v[66:69]
	v_mfma_f32_16x16x32_bf16 v[118:121], v[200:203], v[168:171], v[118:121]
	v_mfma_f32_16x16x32_bf16 v[114:117], v[210:213], v[168:171], v[114:117]
	v_mfma_f32_16x16x32_bf16 v[102:105], v[200:203], v[176:179], v[102:105]
	v_mfma_f32_16x16x32_bf16 v[98:101], v[210:213], v[176:179], v[98:101]
	v_mfma_f32_16x16x32_bf16 v[86:89], v[200:203], v[184:187], v[86:89]
	v_mfma_f32_16x16x32_bf16 v[82:85], v[210:213], v[184:187], v[82:85]
	v_mfma_f32_16x16x32_bf16 v[70:73], v[200:203], v[192:195], v[70:73]
	v_mfma_f32_16x16x32_bf16 v[66:69], v[210:213], v[192:195], v[66:69]
	s_barrier
	s_add_i32 s38, s74, s56
	s_mov_b32 m0, s38
	s_nop 0
	global_load_lds_dwordx4 v0, s[48:49]
	s_add_i32 m0, s38, 0x2000
	s_nop 0
	global_load_lds_dwordx4 v130, s[48:49]
	s_mov_b32 m0, s9
	s_nop 0
	global_load_lds_dwordx4 v134, s[50:51]
	s_mov_b32 m0, s60
	s_nop 0
	global_load_lds_dwordx4 v132, s[50:51]
	ds_read_b128 v[164:167], v145 offset:16384
	ds_read_b128 v[168:171], v145 offset:17408
	ds_read_b128 v[172:175], v145 offset:18432
	ds_read_b128 v[176:179], v145 offset:19456
	ds_read_b128 v[180:183], v145 offset:20480
	ds_read_b128 v[184:187], v145 offset:21504
	ds_read_b128 v[188:191], v145 offset:22528
	ds_read_b128 v[192:195], v145 offset:23552
	s_waitcnt vmcnt(4)
	s_waitcnt lgkmcnt(0)
	s_barrier
	v_mfma_f32_16x16x32_bf16 v[62:65], v[146:149], v[164:167], v[62:65]
	v_mfma_f32_16x16x32_bf16 v[58:61], v[154:157], v[164:167], v[58:61]
	v_mfma_f32_16x16x32_bf16 v[46:49], v[146:149], v[172:175], v[46:49]
	v_mfma_f32_16x16x32_bf16 v[42:45], v[154:157], v[172:175], v[42:45]
	v_mfma_f32_16x16x32_bf16 v[30:33], v[146:149], v[180:183], v[30:33]
	v_mfma_f32_16x16x32_bf16 v[26:29], v[154:157], v[180:183], v[26:29]
	v_mfma_f32_16x16x32_bf16 v[14:17], v[146:149], v[188:191], v[14:17]
	v_mfma_f32_16x16x32_bf16 v[10:13], v[154:157], v[188:191], v[10:13]
	v_mfma_f32_16x16x32_bf16 v[62:65], v[150:153], v[168:171], v[62:65]
	v_mfma_f32_16x16x32_bf16 v[58:61], v[160:163], v[168:171], v[58:61]
	v_mfma_f32_16x16x32_bf16 v[46:49], v[150:153], v[176:179], v[46:49]
	v_mfma_f32_16x16x32_bf16 v[42:45], v[160:163], v[176:179], v[42:45]
	v_mfma_f32_16x16x32_bf16 v[30:33], v[150:153], v[184:187], v[30:33]
	v_mfma_f32_16x16x32_bf16 v[26:29], v[160:163], v[184:187], v[26:29]
	v_mfma_f32_16x16x32_bf16 v[14:17], v[150:153], v[192:195], v[14:17]
	v_mfma_f32_16x16x32_bf16 v[10:13], v[160:163], v[192:195], v[10:13]
	v_mfma_f32_16x16x32_bf16 v[54:57], v[196:199], v[164:167], v[54:57]
	v_mfma_f32_16x16x32_bf16 v[50:53], v[204:207], v[164:167], v[50:53]
	v_mfma_f32_16x16x32_bf16 v[38:41], v[196:199], v[172:175], v[38:41]
	v_mfma_f32_16x16x32_bf16 v[34:37], v[204:207], v[172:175], v[34:37]
	v_mfma_f32_16x16x32_bf16 v[22:25], v[196:199], v[180:183], v[22:25]
	v_mfma_f32_16x16x32_bf16 v[18:21], v[204:207], v[180:183], v[18:21]
	v_mfma_f32_16x16x32_bf16 v[6:9], v[196:199], v[188:191], v[6:9]
	v_mfma_f32_16x16x32_bf16 v[2:5], v[204:207], v[188:191], v[2:5]
	v_mfma_f32_16x16x32_bf16 v[54:57], v[200:203], v[168:171], v[54:57]
	v_mfma_f32_16x16x32_bf16 v[50:53], v[210:213], v[168:171], v[50:53]
	v_mfma_f32_16x16x32_bf16 v[38:41], v[200:203], v[176:179], v[38:41]
	v_mfma_f32_16x16x32_bf16 v[34:37], v[210:213], v[176:179], v[34:37]
	v_mfma_f32_16x16x32_bf16 v[22:25], v[200:203], v[184:187], v[22:25]
	v_mfma_f32_16x16x32_bf16 v[18:21], v[210:213], v[184:187], v[18:21]
	v_mfma_f32_16x16x32_bf16 v[6:9], v[200:203], v[192:195], v[6:9]
	v_mfma_f32_16x16x32_bf16 v[2:5], v[210:213], v[192:195], v[2:5]
	s_barrier
; #define PG8_STAGE(bufoff, gbase, voff) do { _Pragma("unroll") for (int _i = 0; _i < 2; ++_i) \
;         __builtin_amdgcn_global_load_lds((const unsigned*)((const char*)(gbase) + (voff)[_i]), (LAS unsigned*)(lds + (bufoff) + ldsw + _i * 8192), 16, 0, 0); } while (0)
; #define PG8_LDA(dst, b, h) do { _Pragma("unroll") for (int m = 0; m < 4; ++m) _Pragma("unroll") for (int k = 0; k < 2; ++k) dst[m][k] = *(const LAS bf16x8*)(lds + PG8_SA(b, h) + aoff + m * 2048 + k * 1024); } while (0)
; #define PG8_LDB(dst, b, h) do { _Pragma("unroll") for (int n = 0; n < 2; ++n) _Pragma("unroll") for (int k = 0; k < 2; ++k) dst[n][k] = *(const LAS bf16x8*)(lds + PG8_SB(b, h) + boff + n * 2048 + k * 1024); } while (0)
; #define PG8_MMA(ai, bj, At, Bt) do { __builtin_amdgcn_s_setprio(1); _Pragma("unroll") for (int m = 0; m < 4; ++m) _Pragma("unroll") for (int n = 0; n < 2; ++n) _Pragma("unroll") for (int k = 0; k < 2; ++k) \
;         acc[ai][bj][m][n] = __builtin_amdgcn_mfma_f32_16x16x32_bf16(Bt[n][k], At[m][k], acc[ai][bj][m][n], 0, 0, 0); __builtin_amdgcn_s_setprio(0); } while (0)
; #define PG8_WAIT_V(n) asm volatile("s_waitcnt vmcnt(" #n ")" ::: "memory")
; #define PG8_WAIT_L(n) asm volatile("s_waitcnt lgkmcnt(" #n ")" ::: "memory")
; #define PG8_BAR __builtin_amdgcn_s_barrier()
; #define PG8_SCHED __builtin_amdgcn_sched_barrier(0)
; template <class Epi, class Sched>
; __device__ __forceinline__ void gemm_phase(LAS unsigned char* lds, const Gemm g, const Sched& S, const Epi& E) {
;     ...
;             PG8_STAGE(PG8_SB(0, 1), b2 + hstep, voffB);
;             PG8_WAIT_V(6); PG8_BAR; PG8_MMA(1, 1, At, B1); PG8_BAR;
;             PG8_LDB(B0, 1, 0); PG8_SCHED; PG8_LDA(At, 1, 0); PG8_STAGE(PG8_SA(0, 1), a2 + hstep, voffA);
;             PG8_WAIT_L(8); PG8_BAR; PG8_WAIT_L(0); PG8_MMA(0, 0, At, B0); PG8_BAR; PG8_SCHED;
;             PG8_LDB(B1, 1, 1); PG8_STAGE(PG8_SB(1, 0), b3, voffB);
;             PG8_BAR; PG8_WAIT_L(0); PG8_MMA(0, 1, At, B1); PG8_BAR;
;             PG8_LDA(At, 1, 1); PG8_STAGE(PG8_SA(1, 0), a3, voffA);
;             PG8_BAR; PG8_WAIT_L(0); PG8_MMA(1, 0, At, B0); PG8_BAR; PG8_SCHED;
;             PG8_STAGE(PG8_SB(1, 1), b3 + hstep, voffB);
;             PG8_WAIT_V(6); PG8_BAR; PG8_MMA(1, 1, At, B1); PG8_BAR;
;         }
	s_add_u32 s38, s48, 0x80000
	s_addc_u32 s39, s49, 0
	s_add_i32 s74, s75, s56
	s_mov_b32 m0, s74
	s_nop 0
	global_load_lds_dwordx4 v0, s[38:39]
	s_add_i32 m0, s74, 0x2000
	s_nop 0
	global_load_lds_dwordx4 v130, s[38:39]
	s_add_u32 s38, s50, 0x80000
	s_addc_u32 s39, s51, 0
	s_mov_b32 m0, s61
	s_nop 0
	global_load_lds_dwordx4 v134, s[38:39]
	s_mov_b32 m0, s62
	s_nop 0
	global_load_lds_dwordx4 v132, s[38:39]
	s_add_i32 s74, 0, 0x18000
	v_add_u32_e32 v160, s74, v143
	ds_read_b128 v[146:149], v160
	ds_read_b128 v[150:153], v160 offset:1024
	ds_read_b128 v[154:157], v160 offset:2048
	ds_read_b128 v[160:163], v160 offset:3072
	ds_read_b128 v[164:167], v145 offset:32768
	ds_read_b128 v[168:171], v145 offset:33792
	ds_read_b128 v[172:175], v145 offset:34816
	ds_read_b128 v[176:179], v145 offset:35840
	ds_read_b128 v[180:183], v145 offset:36864
	ds_read_b128 v[184:187], v145 offset:37888
	ds_read_b128 v[188:191], v145 offset:38912
	ds_read_b128 v[192:195], v145 offset:39936
	s_nop 0
	v_add_u32_e32 v210, 0x1c000, v143
	ds_read_b128 v[196:199], v210
	ds_read_b128 v[200:203], v210 offset:1024
	ds_read_b128 v[204:207], v210 offset:2048
	ds_read_b128 v[210:213], v210 offset:3072
	s_waitcnt lgkmcnt(4)
	s_barrier
	s_waitcnt lgkmcnt(0)
	v_mfma_f32_16x16x32_bf16 v[126:129], v[146:149], v[164:167], v[126:129]
	v_mfma_f32_16x16x32_bf16 v[122:125], v[154:157], v[164:167], v[122:125]
	v_mfma_f32_16x16x32_bf16 v[110:113], v[146:149], v[172:175], v[110:113]
	v_mfma_f32_16x16x32_bf16 v[106:109], v[154:157], v[172:175], v[106:109]
	v_mfma_f32_16x16x32_bf16 v[94:97], v[146:149], v[180:183], v[94:97]
	v_mfma_f32_16x16x32_bf16 v[90:93], v[154:157], v[180:183], v[90:93]
	v_mfma_f32_16x16x32_bf16 v[78:81], v[146:149], v[188:191], v[78:81]
	v_mfma_f32_16x16x32_bf16 v[74:77], v[154:157], v[188:191], v[74:77]
	v_mfma_f32_16x16x32_bf16 v[126:129], v[150:153], v[168:171], v[126:129]
	v_mfma_f32_16x16x32_bf16 v[122:125], v[160:163], v[168:171], v[122:125]
	v_mfma_f32_16x16x32_bf16 v[110:113], v[150:153], v[176:179], v[110:113]
	v_mfma_f32_16x16x32_bf16 v[106:109], v[160:163], v[176:179], v[106:109]
	v_mfma_f32_16x16x32_bf16 v[94:97], v[150:153], v[184:187], v[94:97]
	v_mfma_f32_16x16x32_bf16 v[90:93], v[160:163], v[184:187], v[90:93]
	v_mfma_f32_16x16x32_bf16 v[78:81], v[150:153], v[192:195], v[78:81]
	v_mfma_f32_16x16x32_bf16 v[74:77], v[160:163], v[192:195], v[74:77]
	v_mfma_f32_16x16x32_bf16 v[118:121], v[196:199], v[164:167], v[118:121]
	v_mfma_f32_16x16x32_bf16 v[114:117], v[204:207], v[164:167], v[114:117]
	v_mfma_f32_16x16x32_bf16 v[102:105], v[196:199], v[172:175], v[102:105]
	v_mfma_f32_16x16x32_bf16 v[98:101], v[204:207], v[172:175], v[98:101]
	v_mfma_f32_16x16x32_bf16 v[86:89], v[196:199], v[180:183], v[86:89]
	v_mfma_f32_16x16x32_bf16 v[82:85], v[204:207], v[180:183], v[82:85]
	v_mfma_f32_16x16x32_bf16 v[70:73], v[196:199], v[188:191], v[70:73]
	v_mfma_f32_16x16x32_bf16 v[66:69], v[204:207], v[188:191], v[66:69]
	v_mfma_f32_16x16x32_bf16 v[118:121], v[200:203], v[168:171], v[118:121]
	v_mfma_f32_16x16x32_bf16 v[114:117], v[210:213], v[168:171], v[114:117]
	v_mfma_f32_16x16x32_bf16 v[102:105], v[200:203], v[176:179], v[102:105]
	v_mfma_f32_16x16x32_bf16 v[98:101], v[210:213], v[176:179], v[98:101]
	v_mfma_f32_16x16x32_bf16 v[86:89], v[200:203], v[184:187], v[86:89]
	v_mfma_f32_16x16x32_bf16 v[82:85], v[210:213], v[184:187], v[82:85]
	v_mfma_f32_16x16x32_bf16 v[70:73], v[200:203], v[192:195], v[70:73]
	v_mfma_f32_16x16x32_bf16 v[66:69], v[210:213], v[192:195], v[66:69]
	s_barrier
	s_add_i32 s38, s74, s56
	s_add_u32 s100, s48, s36
	s_addc_u32 s101, s49, s37
	s_mov_b32 m0, s38
	s_nop 0
	global_load_lds_dwordx4 v0, s[100:101]
	s_add_i32 m0, s38, 0x2000
	s_nop 0
	global_load_lds_dwordx4 v130, s[100:101]
	s_mov_b32 m0, s64
	s_add_u32 s100, s50, s36
	s_addc_u32 s101, s51, s37
	global_load_lds_dwordx4 v134, s[100:101]
	s_mov_b32 m0, s65
	s_nop 0
	global_load_lds_dwordx4 v132, s[100:101]
	ds_read_b128 v[164:167], v145 offset:49152
	ds_read_b128 v[168:171], v145 offset:50176
	ds_read_b128 v[172:175], v145 offset:51200
	ds_read_b128 v[176:179], v145 offset:52224
	ds_read_b128 v[180:183], v145 offset:53248
	ds_read_b128 v[184:187], v145 offset:54272
	ds_read_b128 v[188:191], v145 offset:55296
	ds_read_b128 v[192:195], v145 offset:56320
	s_waitcnt vmcnt(4)
	s_waitcnt lgkmcnt(0)
	s_barrier
	v_mfma_f32_16x16x32_bf16 v[62:65], v[146:149], v[164:167], v[62:65]
	v_mfma_f32_16x16x32_bf16 v[58:61], v[154:157], v[164:167], v[58:61]
	v_mfma_f32_16x16x32_bf16 v[46:49], v[146:149], v[172:175], v[46:49]
	v_mfma_f32_16x16x32_bf16 v[42:45], v[154:157], v[172:175], v[42:45]
	v_mfma_f32_16x16x32_bf16 v[30:33], v[146:149], v[180:183], v[30:33]
	v_mfma_f32_16x16x32_bf16 v[26:29], v[154:157], v[180:183], v[26:29]
	v_mfma_f32_16x16x32_bf16 v[14:17], v[146:149], v[188:191], v[14:17]
	v_mfma_f32_16x16x32_bf16 v[10:13], v[154:157], v[188:191], v[10:13]
	v_mfma_f32_16x16x32_bf16 v[62:65], v[150:153], v[168:171], v[62:65]
	v_mfma_f32_16x16x32_bf16 v[58:61], v[160:163], v[168:171], v[58:61]
	v_mfma_f32_16x16x32_bf16 v[46:49], v[150:153], v[176:179], v[46:49]
	v_mfma_f32_16x16x32_bf16 v[42:45], v[160:163], v[176:179], v[42:45]
	v_mfma_f32_16x16x32_bf16 v[30:33], v[150:153], v[184:187], v[30:33]
	v_mfma_f32_16x16x32_bf16 v[26:29], v[160:163], v[184:187], v[26:29]
	v_mfma_f32_16x16x32_bf16 v[14:17], v[150:153], v[192:195], v[14:17]
	v_mfma_f32_16x16x32_bf16 v[10:13], v[160:163], v[192:195], v[10:13]
	s_add_u32 s38, s48, 0x80080
	s_addc_u32 s39, s49, 0
	s_add_i32 s48, s56, 0x1c000
	s_mov_b32 m0, s48
	s_nop 0
	global_load_lds_dwordx4 v0, s[38:39]
	s_add_i32 m0, s48, 0x2000
	s_nop 0
	global_load_lds_dwordx4 v130, s[38:39]
	v_mfma_f32_16x16x32_bf16 v[54:57], v[196:199], v[164:167], v[54:57]
	v_mfma_f32_16x16x32_bf16 v[50:53], v[204:207], v[164:167], v[50:53]
	v_mfma_f32_16x16x32_bf16 v[38:41], v[196:199], v[172:175], v[38:41]
	v_mfma_f32_16x16x32_bf16 v[34:37], v[204:207], v[172:175], v[34:37]
	v_mfma_f32_16x16x32_bf16 v[22:25], v[196:199], v[180:183], v[22:25]
	v_mfma_f32_16x16x32_bf16 v[18:21], v[204:207], v[180:183], v[18:21]
	v_mfma_f32_16x16x32_bf16 v[6:9], v[196:199], v[188:191], v[6:9]
	v_mfma_f32_16x16x32_bf16 v[2:5], v[204:207], v[188:191], v[2:5]
	v_mfma_f32_16x16x32_bf16 v[54:57], v[200:203], v[168:171], v[54:57]
	v_mfma_f32_16x16x32_bf16 v[50:53], v[210:213], v[168:171], v[50:53]
	v_mfma_f32_16x16x32_bf16 v[38:41], v[200:203], v[176:179], v[38:41]
	v_mfma_f32_16x16x32_bf16 v[34:37], v[210:213], v[176:179], v[34:37]
	v_mfma_f32_16x16x32_bf16 v[22:25], v[200:203], v[184:187], v[22:25]
	v_mfma_f32_16x16x32_bf16 v[18:21], v[210:213], v[184:187], v[18:21]
	v_mfma_f32_16x16x32_bf16 v[6:9], v[200:203], v[192:195], v[6:9]
	v_mfma_f32_16x16x32_bf16 v[2:5], v[210:213], v[192:195], v[2:5]
	s_add_i32 s73, s73, 2
	s_add_u32 s71, s71, 0x100
	s_addc_u32 s72, s72, 0
	s_add_u32 s46, s46, 0x100
	s_addc_u32 s47, s47, 0
	s_cmp_gt_u32 s73, 29
	s_barrier
; __device__ __forceinline__ unsigned cvt_pk_bf16(float lo, float hi) { unsigned r; asm("v_cvt_pk_bf16_f32 %0, %1, %2" : "=v"(r) : "v"(lo), "v"(hi)); return r; }
;     __device__ __forceinline__ void operator()(const f32x4 (&acc)[2][2][4][2], const Unit& u, int wr, int wc, int fr, int fq) const {
;         const int row0 = u.pm * BM + wr * 64 + fr, col0 = u.pn * BM + wc * 32 + 8 * fq;
; #pragma unroll
;         for (int ai = 0; ai < 2; ++ai)
; #pragma unroll
;             for (int m = 0; m < 4; ++m) { bf16_t* rowp = O + (size_t)(row0 + ai * HALF + m * 16) * ldc + col0;
; #pragma unroll
;                 for (int bj = 0; bj < 2; ++bj) { f32x4 v0 = acc[ai][bj][m][0], v1 = acc[ai][bj][m][1];
;                     if (ACT == 1) {
; #pragma unroll
;                         for (int j = 0; j < 4; ++j) { float a = fmaxf(v0[j], 0.f), b = fmaxf(v1[j], 0.f); v0[j] = a * a; v1[j] = b * b; } }
;                     u32x4 w; w.x = cvt_pk_bf16(v0[0], v0[1]); w.y = cvt_pk_bf16(v0[2], v0[3]); w.z = cvt_pk_bf16(v1[0], v1[1]); w.w = cvt_pk_bf16(v1[2], v1[3]);
;                     if (ACT == 1) __builtin_nontemporal_store(w, (u32x4*)(rowp + bj * HALF));
;                     else *(u32x4*)(rowp + bj * HALF) = w; } }
	s_cbranch_scc0 .LBB0_73
	v_lshl_add_u32 v146, s8, 8, v142
	v_max_f32_e32 v122, v122, v122
	v_ashrrev_i32_e32 v147, 31, v146
	v_max_f32_e32 v122, 0, v122
	v_max_f32_e32 v123, v123, v123
	v_max_f32_e32 v124, v124, v124
	v_lshl_or_b32 v140, s68, 8, v144
	v_lshlrev_b64 v[148:149], 14, v[146:147]
	v_mul_f32_e32 v147, v122, v122
	v_max_f32_e32 v122, v127, v127
	v_max_f32_e32 v123, 0, v123
	v_max_f32_e32 v124, 0, v124
	v_ashrrev_i32_e32 v141, 31, v140
	v_max_f32_e32 v126, v126, v126
	v_max_f32_e32 v122, 0, v122
	v_mul_f32_e32 v127, v123, v123
	v_max_f32_e32 v123, v128, v128
	v_mul_f32_e32 v128, v124, v124
	v_max_f32_e32 v124, v129, v129
	v_max_f32_e32 v125, v125, v125
	v_lshl_add_u64 v[148:149], s[24:25], 0, v[148:149]
	v_lshlrev_b64 v[150:151], 1, v[140:141]
	v_max_f32_e32 v126, 0, v126
	v_mul_f32_e32 v122, v122, v122
	v_max_f32_e32 v123, 0, v123
	v_max_f32_e32 v124, 0, v124
	v_max_f32_e32 v125, 0, v125
	v_max_f32_e32 v114, v114, v114
	v_lshl_add_u64 v[140:141], v[148:149], 0, v[150:151]
	v_mul_f32_e32 v126, v126, v126
	v_mul_f32_e32 v123, v123, v123
	v_mul_f32_e32 v124, v124, v124
	v_mul_f32_e32 v125, v125, v125
	v_cvt_pk_bf16_f32 v122, v126, v122
	v_max_f32_e32 v114, 0, v114
	v_max_f32_e32 v115, v115, v115
	v_max_f32_e32 v116, v116, v116
	v_cvt_pk_bf16_f32 v123, v123, v124
	v_cvt_pk_bf16_f32 v124, v147, v127
	v_cvt_pk_bf16_f32 v125, v128, v125
	global_store_dwordx4 v[140:141], v[122:125], off nt
	v_max_f32_e32 v115, 0, v115
	v_max_f32_e32 v116, 0, v116
	v_mul_f32_e32 v122, v114, v114
	v_max_f32_e32 v114, v119, v119
	v_max_f32_e32 v118, v118, v118
	v_max_f32_e32 v114, 0, v114
	v_mul_f32_e32 v119, v115, v115
	v_max_f32_e32 v115, v120, v120
	v_mul_f32_e32 v120, v116, v116
	v_max_f32_e32 v116, v121, v121
	v_max_f32_e32 v117, v117, v117
	v_max_f32_e32 v118, 0, v118
	v_mul_f32_e32 v114, v114, v114
	v_max_f32_e32 v115, 0, v115
	v_max_f32_e32 v116, 0, v116
	v_max_f32_e32 v117, 0, v117
	v_mul_f32_e32 v118, v118, v118
	v_mul_f32_e32 v115, v115, v115
	v_mul_f32_e32 v116, v116, v116
	v_mul_f32_e32 v117, v117, v117
	v_cvt_pk_bf16_f32 v114, v118, v114
	v_max_f32_e32 v106, v106, v106
	v_cvt_pk_bf16_f32 v115, v115, v116
	v_cvt_pk_bf16_f32 v116, v122, v119
	v_cvt_pk_bf16_f32 v117, v120, v117
	global_store_dwordx4 v[140:141], v[114:117], off offset:256 nt
	v_max_f32_e32 v106, 0, v106
	v_max_f32_e32 v107, v107, v107
	v_or_b32_e32 v114, 16, v146
	v_max_f32_e32 v108, v108, v108
	v_ashrrev_i32_e32 v115, 31, v114
	v_mul_f32_e32 v116, v106, v106
	v_max_f32_e32 v106, v111, v111
	v_max_f32_e32 v107, 0, v107
	v_max_f32_e32 v108, 0, v108
	v_lshlrev_b64 v[114:115], 14, v[114:115]
	v_max_f32_e32 v110, v110, v110
	v_max_f32_e32 v106, 0, v106
	v_mul_f32_e32 v111, v107, v107
	v_max_f32_e32 v107, v112, v112
	v_mul_f32_e32 v112, v108, v108
	v_max_f32_e32 v108, v113, v113
	v_max_f32_e32 v109, v109, v109
	v_lshl_add_u64 v[114:115], s[24:25], 0, v[114:115]
	v_max_f32_e32 v110, 0, v110
	v_mul_f32_e32 v106, v106, v106
	v_max_f32_e32 v107, 0, v107
	v_max_f32_e32 v108, 0, v108
	v_max_f32_e32 v109, 0, v109
	v_max_f32_e32 v98, v98, v98
	v_lshl_add_u64 v[114:115], v[114:115], 0, v[150:151]
	v_mul_f32_e32 v110, v110, v110
	v_mul_f32_e32 v107, v107, v107
	v_mul_f32_e32 v108, v108, v108
	v_mul_f32_e32 v109, v109, v109
	v_cvt_pk_bf16_f32 v106, v110, v106
	v_max_f32_e32 v98, 0, v98
	v_max_f32_e32 v99, v99, v99
	v_max_f32_e32 v100, v100, v100
	v_cvt_pk_bf16_f32 v107, v107, v108
	v_cvt_pk_bf16_f32 v108, v116, v111
	v_cvt_pk_bf16_f32 v109, v112, v109
	global_store_dwordx4 v[114:115], v[106:109], off nt
	v_max_f32_e32 v99, 0, v99
	v_max_f32_e32 v100, 0, v100
	v_mul_f32_e32 v106, v98, v98
	v_max_f32_e32 v98, v103, v103
	v_max_f32_e32 v102, v102, v102
	v_max_f32_e32 v98, 0, v98
	v_mul_f32_e32 v103, v99, v99
	v_max_f32_e32 v99, v104, v104
	v_mul_f32_e32 v104, v100, v100
	v_max_f32_e32 v100, v105, v105
	v_max_f32_e32 v101, v101, v101
	v_max_f32_e32 v102, 0, v102
	v_mul_f32_e32 v98, v98, v98
	v_max_f32_e32 v99, 0, v99
	v_max_f32_e32 v100, 0, v100
	v_max_f32_e32 v101, 0, v101
	v_mul_f32_e32 v102, v102, v102
	v_mul_f32_e32 v99, v99, v99
	v_mul_f32_e32 v100, v100, v100
	v_mul_f32_e32 v101, v101, v101
	v_cvt_pk_bf16_f32 v98, v102, v98
	v_max_f32_e32 v90, v90, v90
	v_cvt_pk_bf16_f32 v99, v99, v100
	v_cvt_pk_bf16_f32 v100, v106, v103
	v_cvt_pk_bf16_f32 v101, v104, v101
	global_store_dwordx4 v[114:115], v[98:101], off offset:256 nt
	v_max_f32_e32 v90, 0, v90
	v_max_f32_e32 v91, v91, v91
	v_or_b32_e32 v98, 32, v146
	v_max_f32_e32 v92, v92, v92
	v_ashrrev_i32_e32 v99, 31, v98
	v_mul_f32_e32 v100, v90, v90
	v_max_f32_e32 v90, v95, v95
	v_max_f32_e32 v91, 0, v91
	v_max_f32_e32 v92, 0, v92
	v_lshlrev_b64 v[98:99], 14, v[98:99]
	v_max_f32_e32 v94, v94, v94
	v_max_f32_e32 v90, 0, v90
	v_mul_f32_e32 v95, v91, v91
	v_max_f32_e32 v91, v96, v96
	v_mul_f32_e32 v96, v92, v92
	v_max_f32_e32 v92, v97, v97
	v_max_f32_e32 v93, v93, v93
	v_lshl_add_u64 v[98:99], s[24:25], 0, v[98:99]
	v_max_f32_e32 v94, 0, v94
	v_mul_f32_e32 v90, v90, v90
	v_max_f32_e32 v91, 0, v91
	v_max_f32_e32 v92, 0, v92
	v_max_f32_e32 v93, 0, v93
	v_max_f32_e32 v82, v82, v82
	v_lshl_add_u64 v[98:99], v[98:99], 0, v[150:151]
	v_mul_f32_e32 v94, v94, v94
	v_mul_f32_e32 v91, v91, v91
	v_mul_f32_e32 v92, v92, v92
	v_mul_f32_e32 v93, v93, v93
	v_cvt_pk_bf16_f32 v90, v94, v90
	v_max_f32_e32 v82, 0, v82
	v_max_f32_e32 v83, v83, v83
	v_max_f32_e32 v84, v84, v84
	v_cvt_pk_bf16_f32 v91, v91, v92
	v_cvt_pk_bf16_f32 v92, v100, v95
	v_cvt_pk_bf16_f32 v93, v96, v93
	global_store_dwordx4 v[98:99], v[90:93], off nt
	v_max_f32_e32 v83, 0, v83
	v_max_f32_e32 v84, 0, v84
	v_mul_f32_e32 v90, v82, v82
	v_max_f32_e32 v82, v87, v87
	v_max_f32_e32 v86, v86, v86
; __device__ __forceinline__ unsigned cvt_pk_bf16(float lo, float hi) { unsigned r; asm("v_cvt_pk_bf16_f32 %0, %1, %2" : "=v"(r) : "v"(lo), "v"(hi)); return r; }
;     __device__ __forceinline__ void operator()(const f32x4 (&acc)[2][2][4][2], const Unit& u, int wr, int wc, int fr, int fq) const {
;     ...
;                 for (int bj = 0; bj < 2; ++bj) { f32x4 v0 = acc[ai][bj][m][0], v1 = acc[ai][bj][m][1];
;                     if (ACT == 1) {
; #pragma unroll
;                         for (int j = 0; j < 4; ++j) { float a = fmaxf(v0[j], 0.f), b = fmaxf(v1[j], 0.f); v0[j] = a * a; v1[j] = b * b; } }
;                     u32x4 w; w.x = cvt_pk_bf16(v0[0], v0[1]); w.y = cvt_pk_bf16(v0[2], v0[3]); w.z = cvt_pk_bf16(v1[0], v1[1]); w.w = cvt_pk_bf16(v1[2], v1[3]);
;                     if (ACT == 1) __builtin_nontemporal_store(w, (u32x4*)(rowp + bj * HALF));
;                     else *(u32x4*)(rowp + bj * HALF) = w; } }
	v_max_f32_e32 v82, 0, v82
	v_mul_f32_e32 v87, v83, v83
	v_max_f32_e32 v83, v88, v88
	v_mul_f32_e32 v88, v84, v84
	v_max_f32_e32 v84, v89, v89
	v_max_f32_e32 v85, v85, v85
	v_max_f32_e32 v86, 0, v86
	v_mul_f32_e32 v82, v82, v82
	v_max_f32_e32 v83, 0, v83
	v_max_f32_e32 v84, 0, v84
	v_max_f32_e32 v85, 0, v85
	v_mul_f32_e32 v86, v86, v86
	v_mul_f32_e32 v83, v83, v83
	v_mul_f32_e32 v84, v84, v84
	v_mul_f32_e32 v85, v85, v85
	v_cvt_pk_bf16_f32 v82, v86, v82
	v_max_f32_e32 v74, v74, v74
	v_cvt_pk_bf16_f32 v83, v83, v84
	v_cvt_pk_bf16_f32 v84, v90, v87
	v_cvt_pk_bf16_f32 v85, v88, v85
	global_store_dwordx4 v[98:99], v[82:85], off offset:256 nt
	v_max_f32_e32 v74, 0, v74
	v_max_f32_e32 v75, v75, v75
	v_or_b32_e32 v82, 48, v146
	v_max_f32_e32 v76, v76, v76
	v_ashrrev_i32_e32 v83, 31, v82
	v_mul_f32_e32 v84, v74, v74
	v_max_f32_e32 v74, v79, v79
	v_max_f32_e32 v75, 0, v75
	v_max_f32_e32 v76, 0, v76
	v_lshlrev_b64 v[82:83], 14, v[82:83]
	v_max_f32_e32 v78, v78, v78
	v_max_f32_e32 v74, 0, v74
	v_mul_f32_e32 v79, v75, v75
	v_max_f32_e32 v75, v80, v80
	v_mul_f32_e32 v80, v76, v76
	v_max_f32_e32 v76, v81, v81
	v_max_f32_e32 v77, v77, v77
	v_lshl_add_u64 v[82:83], s[24:25], 0, v[82:83]
	v_max_f32_e32 v78, 0, v78
	v_mul_f32_e32 v74, v74, v74
	v_max_f32_e32 v75, 0, v75
	v_max_f32_e32 v76, 0, v76
	v_max_f32_e32 v77, 0, v77
	v_max_f32_e32 v66, v66, v66
	v_max_f32_e32 v67, v67, v67
	v_max_f32_e32 v68, v68, v68
	v_lshl_add_u64 v[82:83], v[82:83], 0, v[150:151]
	v_mul_f32_e32 v78, v78, v78
	v_mul_f32_e32 v75, v75, v75
	v_mul_f32_e32 v76, v76, v76
	v_mul_f32_e32 v77, v77, v77
	v_cvt_pk_bf16_f32 v74, v78, v74
	v_max_f32_e32 v66, 0, v66
	v_max_f32_e32 v67, 0, v67
	v_max_f32_e32 v68, 0, v68
	v_cvt_pk_bf16_f32 v75, v75, v76
	v_cvt_pk_bf16_f32 v76, v84, v79
	v_cvt_pk_bf16_f32 v77, v80, v77
	global_store_dwordx4 v[82:83], v[74:77], off nt
	v_max_f32_e32 v69, v69, v69
	v_max_f32_e32 v70, v70, v70
	v_mul_f32_e32 v74, v66, v66
	v_max_f32_e32 v66, v71, v71
	v_mul_f32_e32 v71, v67, v67
	v_max_f32_e32 v67, v72, v72
	v_mul_f32_e32 v72, v68, v68
	v_max_f32_e32 v68, v73, v73
	v_max_f32_e32 v67, 0, v67
	v_max_f32_e32 v68, 0, v68
	v_max_f32_e32 v66, 0, v66
	v_mul_f32_e32 v67, v67, v67
	v_max_f32_e32 v69, 0, v69
	v_mul_f32_e32 v68, v68, v68
	v_max_f32_e32 v58, v58, v58
	v_max_f32_e32 v70, 0, v70
	v_mul_f32_e32 v66, v66, v66
	v_mul_f32_e32 v69, v69, v69
	v_cvt_pk_bf16_f32 v67, v67, v68
	v_cvt_pk_bf16_f32 v68, v74, v71
	v_max_f32_e32 v58, 0, v58
	v_max_f32_e32 v59, v59, v59
	v_max_f32_e32 v60, v60, v60
	v_mul_f32_e32 v70, v70, v70
	v_cvt_pk_bf16_f32 v66, v70, v66
	v_cvt_pk_bf16_f32 v69, v72, v69
	global_store_dwordx4 v[82:83], v[66:69], off offset:256 nt
	v_max_f32_e32 v62, v62, v62
	v_max_f32_e32 v59, 0, v59
	v_mul_f32_e32 v68, v58, v58
	v_max_f32_e32 v58, v63, v63
	v_max_f32_e32 v60, 0, v60
	v_max_f32_e32 v62, 0, v62
	v_max_f32_e32 v58, 0, v58
	v_mul_f32_e32 v63, v59, v59
	v_max_f32_e32 v59, v64, v64
	v_mul_f32_e32 v64, v60, v60
	v_max_f32_e32 v60, v65, v65
	v_mul_f32_e32 v62, v62, v62
	v_mul_f32_e32 v58, v58, v58
	v_max_f32_e32 v59, 0, v59
	v_max_f32_e32 v60, 0, v60
	v_max_f32_e32 v61, v61, v61
	s_mov_b32 s8, 0x200000
	v_mul_f32_e32 v59, v59, v59
	v_max_f32_e32 v61, 0, v61
	v_mul_f32_e32 v60, v60, v60
	v_cvt_pk_bf16_f32 v58, v62, v58
	v_add_co_u32_e32 v62, vcc, s8, v140
	v_max_f32_e32 v50, v50, v50
	v_max_f32_e32 v51, v51, v51
	v_max_f32_e32 v52, v52, v52
	v_mul_f32_e32 v61, v61, v61
	v_cvt_pk_bf16_f32 v59, v59, v60
	v_cvt_pk_bf16_f32 v60, v68, v63
	v_addc_co_u32_e32 v63, vcc, 0, v141, vcc
	v_max_f32_e32 v50, 0, v50
	v_max_f32_e32 v51, 0, v51
	v_max_f32_e32 v52, 0, v52
	v_cvt_pk_bf16_f32 v61, v64, v61
	global_store_dwordx4 v[62:63], v[58:61], off nt
	v_max_f32_e32 v53, v53, v53
	s_mov_b64 s[38:39], 0x200000
	v_mul_f32_e32 v58, v50, v50
	v_max_f32_e32 v50, v55, v55
	v_mul_f32_e32 v55, v51, v51
	v_max_f32_e32 v51, v56, v56
	v_mul_f32_e32 v56, v52, v52
	v_max_f32_e32 v52, v57, v57
	v_max_f32_e32 v51, 0, v51
	v_max_f32_e32 v52, 0, v52
	v_max_f32_e32 v54, v54, v54
	v_max_f32_e32 v50, 0, v50
	v_mul_f32_e32 v51, v51, v51
	v_max_f32_e32 v53, 0, v53
	v_mul_f32_e32 v52, v52, v52
	v_max_f32_e32 v42, v42, v42
	v_lshl_add_u64 v[66:67], v[140:141], 0, s[38:39]
	v_max_f32_e32 v54, 0, v54
	v_mul_f32_e32 v50, v50, v50
	v_mul_f32_e32 v53, v53, v53
	v_cvt_pk_bf16_f32 v51, v51, v52
	v_cvt_pk_bf16_f32 v52, v58, v55
	v_max_f32_e32 v42, 0, v42
	v_max_f32_e32 v43, v43, v43
	v_max_f32_e32 v44, v44, v44
	v_mul_f32_e32 v54, v54, v54
	v_cvt_pk_bf16_f32 v50, v54, v50
	v_cvt_pk_bf16_f32 v53, v56, v53
	global_store_dwordx4 v[66:67], v[50:53], off offset:256 nt
	v_max_f32_e32 v46, v46, v46
	v_max_f32_e32 v43, 0, v43
	v_mul_f32_e32 v52, v42, v42
	v_max_f32_e32 v42, v47, v47
	v_max_f32_e32 v44, 0, v44
	v_max_f32_e32 v46, 0, v46
	v_max_f32_e32 v42, 0, v42
	v_mul_f32_e32 v47, v43, v43
	v_max_f32_e32 v43, v48, v48
	v_mul_f32_e32 v48, v44, v44
	v_max_f32_e32 v44, v49, v49
	v_mul_f32_e32 v46, v46, v46
	v_mul_f32_e32 v42, v42, v42
	v_max_f32_e32 v43, 0, v43
	v_max_f32_e32 v44, 0, v44
	v_max_f32_e32 v45, v45, v45
	s_mov_b32 s8, 0x240000
	v_mul_f32_e32 v43, v43, v43
	v_max_f32_e32 v45, 0, v45
	v_mul_f32_e32 v44, v44, v44
	v_cvt_pk_bf16_f32 v42, v46, v42
; __device__ __forceinline__ unsigned cvt_pk_bf16(float lo, float hi) { unsigned r; asm("v_cvt_pk_bf16_f32 %0, %1, %2" : "=v"(r) : "v"(lo), "v"(hi)); return r; }
; #define PG8_WAIT_V(n) asm volatile("s_waitcnt vmcnt(" #n ")" ::: "memory")
; #define PG8_BAR __builtin_amdgcn_s_barrier()
;     __device__ __forceinline__ void operator()(const f32x4 (&acc)[2][2][4][2], const Unit& u, int wr, int wc, int fr, int fq) const {
;     ...
;                 for (int bj = 0; bj < 2; ++bj) { f32x4 v0 = acc[ai][bj][m][0], v1 = acc[ai][bj][m][1];
;                     if (ACT == 1) {
; #pragma unroll
;                         for (int j = 0; j < 4; ++j) { float a = fmaxf(v0[j], 0.f), b = fmaxf(v1[j], 0.f); v0[j] = a * a; v1[j] = b * b; } }
;                     u32x4 w; w.x = cvt_pk_bf16(v0[0], v0[1]); w.y = cvt_pk_bf16(v0[2], v0[3]); w.z = cvt_pk_bf16(v1[0], v1[1]); w.w = cvt_pk_bf16(v1[2], v1[3]);
;                     if (ACT == 1) __builtin_nontemporal_store(w, (u32x4*)(rowp + bj * HALF));
;                     else *(u32x4*)(rowp + bj * HALF) = w; } }
; template <class Epi, class Sched>
; __device__ __forceinline__ void gemm_phase(LAS unsigned char* lds, const Gemm g, const Sched& S, const Epi& E) {
;     ...
;         E(acc, cur, wr, wc, fr, fq);
;         if (!has_next) break;
; #pragma unroll
;         for (int a = 0; a < 2; ++a)
; #pragma unroll
;             for (int b = 0; b < 2; ++b)
; #pragma unroll
;                 for (int m = 0; m < 4; ++m)
; #pragma unroll
;                     for (int n = 0; n < 2; ++n) acc[a][b][m][n] = (f32x4){0.f, 0.f, 0.f, 0.f};
;         cur = nxt; cA = nA; cB = nB; ++ui;
;     }
;     PG8_WAIT_V(0);
;     if (wr == 0) PG8_BAR;
;     PG8_BAR;
	v_add_co_u32_e32 v46, vcc, s8, v140
	v_max_f32_e32 v34, v34, v34
	v_max_f32_e32 v35, v35, v35
	v_max_f32_e32 v36, v36, v36
	v_mul_f32_e32 v45, v45, v45
	v_cvt_pk_bf16_f32 v43, v43, v44
	v_cvt_pk_bf16_f32 v44, v52, v47
	v_addc_co_u32_e32 v47, vcc, 0, v141, vcc
	v_max_f32_e32 v34, 0, v34
	v_max_f32_e32 v35, 0, v35
	v_max_f32_e32 v36, 0, v36
	v_cvt_pk_bf16_f32 v45, v48, v45
	global_store_dwordx4 v[46:47], v[42:45], off nt
	v_max_f32_e32 v37, v37, v37
	s_mov_b64 s[38:39], 0x240000
	v_mul_f32_e32 v42, v34, v34
	v_max_f32_e32 v34, v39, v39
	v_mul_f32_e32 v39, v35, v35
	v_max_f32_e32 v35, v40, v40
	v_mul_f32_e32 v40, v36, v36
	v_max_f32_e32 v36, v41, v41
	v_max_f32_e32 v35, 0, v35
	v_max_f32_e32 v36, 0, v36
	v_max_f32_e32 v38, v38, v38
	v_max_f32_e32 v34, 0, v34
	v_mul_f32_e32 v35, v35, v35
	v_max_f32_e32 v37, 0, v37
	v_mul_f32_e32 v36, v36, v36
	v_max_f32_e32 v26, v26, v26
	v_lshl_add_u64 v[50:51], v[140:141], 0, s[38:39]
	v_max_f32_e32 v38, 0, v38
	v_mul_f32_e32 v34, v34, v34
	v_mul_f32_e32 v37, v37, v37
	v_cvt_pk_bf16_f32 v35, v35, v36
	v_cvt_pk_bf16_f32 v36, v42, v39
	v_max_f32_e32 v26, 0, v26
	v_max_f32_e32 v27, v27, v27
	v_max_f32_e32 v28, v28, v28
	v_mul_f32_e32 v38, v38, v38
	v_cvt_pk_bf16_f32 v34, v38, v34
	v_cvt_pk_bf16_f32 v37, v40, v37
	global_store_dwordx4 v[50:51], v[34:37], off offset:256 nt
	v_max_f32_e32 v30, v30, v30
	v_max_f32_e32 v27, 0, v27
	v_mul_f32_e32 v36, v26, v26
	v_max_f32_e32 v26, v31, v31
	v_max_f32_e32 v28, 0, v28
	v_max_f32_e32 v30, 0, v30
	v_max_f32_e32 v26, 0, v26
	v_mul_f32_e32 v31, v27, v27
	v_max_f32_e32 v27, v32, v32
	v_mul_f32_e32 v32, v28, v28
	v_max_f32_e32 v28, v33, v33
	v_mul_f32_e32 v30, v30, v30
	v_mul_f32_e32 v26, v26, v26
	v_max_f32_e32 v27, 0, v27
	v_max_f32_e32 v28, 0, v28
	v_max_f32_e32 v29, v29, v29
	s_mov_b32 s8, 0x280000
	v_mul_f32_e32 v27, v27, v27
	v_max_f32_e32 v29, 0, v29
	v_mul_f32_e32 v28, v28, v28
	v_cvt_pk_bf16_f32 v26, v30, v26
	v_add_co_u32_e32 v30, vcc, s8, v140
	v_max_f32_e32 v18, v18, v18
	v_max_f32_e32 v19, v19, v19
	v_max_f32_e32 v20, v20, v20
	v_mul_f32_e32 v29, v29, v29
	v_cvt_pk_bf16_f32 v27, v27, v28
	v_cvt_pk_bf16_f32 v28, v36, v31
	v_addc_co_u32_e32 v31, vcc, 0, v141, vcc
	v_max_f32_e32 v18, 0, v18
	v_max_f32_e32 v19, 0, v19
	v_max_f32_e32 v20, 0, v20
	v_cvt_pk_bf16_f32 v29, v32, v29
	global_store_dwordx4 v[30:31], v[26:29], off nt
	v_max_f32_e32 v21, v21, v21
	s_mov_b64 s[38:39], 0x280000
	v_mul_f32_e32 v26, v18, v18
	v_max_f32_e32 v18, v23, v23
	v_mul_f32_e32 v23, v19, v19
	v_max_f32_e32 v19, v24, v24
	v_mul_f32_e32 v24, v20, v20
	v_max_f32_e32 v20, v25, v25
	v_max_f32_e32 v19, 0, v19
	v_max_f32_e32 v20, 0, v20
	v_max_f32_e32 v22, v22, v22
	v_max_f32_e32 v18, 0, v18
	v_mul_f32_e32 v19, v19, v19
	v_max_f32_e32 v21, 0, v21
	v_mul_f32_e32 v20, v20, v20
	v_max_f32_e32 v10, v10, v10
	v_lshl_add_u64 v[34:35], v[140:141], 0, s[38:39]
	v_max_f32_e32 v22, 0, v22
	v_mul_f32_e32 v18, v18, v18
	v_mul_f32_e32 v21, v21, v21
	v_cvt_pk_bf16_f32 v19, v19, v20
	v_cvt_pk_bf16_f32 v20, v26, v23
	v_max_f32_e32 v10, 0, v10
	v_max_f32_e32 v11, v11, v11
	v_max_f32_e32 v12, v12, v12
	v_mul_f32_e32 v22, v22, v22
	v_cvt_pk_bf16_f32 v18, v22, v18
	v_cvt_pk_bf16_f32 v21, v24, v21
	global_store_dwordx4 v[34:35], v[18:21], off offset:256 nt
	v_max_f32_e32 v14, v14, v14
	v_max_f32_e32 v11, 0, v11
	v_mul_f32_e32 v20, v10, v10
	v_max_f32_e32 v10, v15, v15
	v_max_f32_e32 v12, 0, v12
	v_max_f32_e32 v14, 0, v14
	v_max_f32_e32 v10, 0, v10
	v_mul_f32_e32 v15, v11, v11
	v_max_f32_e32 v11, v16, v16
	v_mul_f32_e32 v16, v12, v12
	v_max_f32_e32 v12, v17, v17
	v_mul_f32_e32 v14, v14, v14
	v_mul_f32_e32 v10, v10, v10
	v_max_f32_e32 v11, 0, v11
	v_max_f32_e32 v12, 0, v12
	v_max_f32_e32 v13, v13, v13
	s_mov_b32 s8, 0x2c0000
	v_mul_f32_e32 v11, v11, v11
	v_max_f32_e32 v13, 0, v13
	v_mul_f32_e32 v12, v12, v12
	v_cvt_pk_bf16_f32 v10, v14, v10
	v_add_co_u32_e32 v14, vcc, s8, v140
	v_max_f32_e32 v2, v2, v2
	v_max_f32_e32 v3, v3, v3
	v_max_f32_e32 v4, v4, v4
	v_mul_f32_e32 v13, v13, v13
	v_cvt_pk_bf16_f32 v11, v11, v12
	v_cvt_pk_bf16_f32 v12, v20, v15
	v_addc_co_u32_e32 v15, vcc, 0, v141, vcc
	v_max_f32_e32 v2, 0, v2
	v_max_f32_e32 v3, 0, v3
	v_max_f32_e32 v4, 0, v4
	v_cvt_pk_bf16_f32 v13, v16, v13
	global_store_dwordx4 v[14:15], v[10:13], off nt
	v_max_f32_e32 v5, v5, v5
	s_mov_b64 s[38:39], 0x2c0000
	v_mul_f32_e32 v10, v2, v2
	v_max_f32_e32 v2, v7, v7
	v_mul_f32_e32 v7, v3, v3
	v_max_f32_e32 v3, v8, v8
	v_mul_f32_e32 v8, v4, v4
	v_max_f32_e32 v4, v9, v9
	v_max_f32_e32 v6, v6, v6
	v_max_f32_e32 v2, 0, v2
	v_max_f32_e32 v3, 0, v3
	v_max_f32_e32 v4, 0, v4
	v_max_f32_e32 v5, 0, v5
	v_lshl_add_u64 v[18:19], v[140:141], 0, s[38:39]
	v_max_f32_e32 v6, 0, v6
	v_mul_f32_e32 v2, v2, v2
	v_mul_f32_e32 v3, v3, v3
	v_mul_f32_e32 v4, v4, v4
	v_mul_f32_e32 v5, v5, v5
	s_and_b64 vcc, exec, s[40:41]
	s_mov_b32 s68, s26
	s_mov_b32 s8, s28
	s_mov_b64 s[46:47], s[44:45]
	s_mov_b64 s[48:49], s[42:43]
	v_mul_f32_e32 v6, v6, v6
	v_cvt_pk_bf16_f32 v2, v6, v2
	v_cvt_pk_bf16_f32 v3, v3, v4
	v_cvt_pk_bf16_f32 v4, v10, v7
	v_cvt_pk_bf16_f32 v5, v8, v5
	global_store_dwordx4 v[18:19], v[2:5], off offset:256 nt
	s_cbranch_vccz .LBB0_70
	s_waitcnt vmcnt(0)
	s_cmpk_gt_u32 s52, 0xff
	s_cbranch_scc1 .LBB0_77
	s_barrier

; #define PG8_STAGE(bufoff, gbase, voff) do { _Pragma("unroll") for (int _i = 0; _i < 2; ++_i) \
;         __builtin_amdgcn_global_load_lds((const unsigned*)((const char*)(gbase) + (voff)[_i]), (LAS unsigned*)(lds + (bufoff) + ldsw + _i * 8192), 16, 0, 0); } while (0)
; #define PG8_LDA(dst, b, h) do { _Pragma("unroll") for (int m = 0; m < 4; ++m) _Pragma("unroll") for (int k = 0; k < 2; ++k) dst[m][k] = *(const LAS bf16x8*)(lds + PG8_SA(b, h) + aoff + m * 2048 + k * 1024); } while (0)
; #define PG8_LDB(dst, b, h) do { _Pragma("unroll") for (int n = 0; n < 2; ++n) _Pragma("unroll") for (int k = 0; k < 2; ++k) dst[n][k] = *(const LAS bf16x8*)(lds + PG8_SB(b, h) + boff + n * 2048 + k * 1024); } while (0)
; #define PG8_MMA(ai, bj, At, Bt) do { __builtin_amdgcn_s_setprio(1); _Pragma("unroll") for (int m = 0; m < 4; ++m) _Pragma("unroll") for (int n = 0; n < 2; ++n) _Pragma("unroll") for (int k = 0; k < 2; ++k) \
;         acc[ai][bj][m][n] = __builtin_amdgcn_mfma_f32_16x16x32_bf16(Bt[n][k], At[m][k], acc[ai][bj][m][n], 0, 0, 0); __builtin_amdgcn_s_setprio(0); } while (0)
; #define PG8_WAIT_V(n) asm volatile("s_waitcnt vmcnt(" #n ")" ::: "memory")
; #define PG8_WAIT_L(n) asm volatile("s_waitcnt lgkmcnt(" #n ")" ::: "memory")
; #define PG8_BAR __builtin_amdgcn_s_barrier()
; #define PG8_SCHED __builtin_amdgcn_sched_barrier(0)
; template <class Epi, class Sched>
; __device__ __forceinline__ void gemm_phase(LAS unsigned char* lds, const Gemm g, const Sched& S, const Epi& E) {
;     ...
;             PG8_LDB(B0, 0, 0); PG8_SCHED; PG8_LDA(At, 0, 0); PG8_STAGE(PG8_SA(1, 1), a1 + hstep, voffA);
;             PG8_WAIT_L(8); PG8_BAR; PG8_WAIT_L(0); PG8_MMA(0, 0, At, B0); PG8_BAR; PG8_SCHED;
;             PG8_LDB(B1, 0, 1); PG8_STAGE(PG8_SB(0, 0), b2, voffB);
;             PG8_BAR; PG8_WAIT_L(0); PG8_MMA(0, 1, At, B1); PG8_BAR;
;             PG8_LDA(At, 0, 1); PG8_STAGE(PG8_SA(0, 0), a2, voffA);
;             PG8_BAR; PG8_WAIT_L(0); PG8_MMA(1, 0, At, B0); PG8_BAR; PG8_SCHED;
;             PG8_STAGE(PG8_SB(0, 1), b2 + hstep, voffB);
;             PG8_WAIT_V(6); PG8_BAR; PG8_MMA(1, 1, At, B1); PG8_BAR;
.LBB0_99:
	s_add_u32 s56, s28, 0x100
	s_addc_u32 s57, s29, 0
	s_cmp_eq_u32 s81, 28
	s_cselect_b32 s61, s51, s57
	s_cselect_b32 s60, s77, s56
	s_cselect_b32 s59, s49, s80
	s_cselect_b32 s58, s78, s79
	v_lshl_add_u64 v[156:157], s[28:29], 0, v[150:151]
	s_add_i32 m0, s9, 0xc000
	s_nop 0
	global_load_lds_dwordx4 v[156:157], off
	v_lshl_add_u64 v[156:157], s[28:29], 0, v[148:149]
	s_add_i32 m0, s9, 0xe000
	s_nop 0
	global_load_lds_dwordx4 v[156:157], off
	s_add_i32 s38, 0, 0x10000
	v_add_u32_e32 v110, s38, v169
	ds_read_b128 v[98:101], v110
	ds_read_b128 v[102:105], v110 offset:1024
	ds_read_b128 v[106:109], v110 offset:2048
	ds_read_b128 v[110:113], v110 offset:3072
	ds_read_b128 v[152:155], v171
	ds_read_b128 v[160:163], v171 offset:1024
	ds_read_b128 v[164:167], v171 offset:2048
	ds_read_b128 v[172:175], v171 offset:3072
	ds_read_b128 v[176:179], v171 offset:4096
	ds_read_b128 v[180:183], v171 offset:5120
	ds_read_b128 v[184:187], v171 offset:6144
	ds_read_b128 v[188:191], v171 offset:7168
	s_add_i32 s39, 0, 0x14000
	v_add_u32_e32 v156, s39, v169
	ds_read_b128 v[192:195], v156
	ds_read_b128 v[196:199], v156 offset:1024
	ds_read_b128 v[200:203], v156 offset:2048
	ds_read_b128 v[204:207], v156 offset:3072
	s_waitcnt lgkmcnt(4)
	s_barrier
	s_waitcnt lgkmcnt(0)
	v_mfma_f32_16x16x32_bf16 v[142:145], v[98:101], v[152:155], v[142:145]
	v_mfma_f32_16x16x32_bf16 v[138:141], v[106:109], v[152:155], v[138:141]
	v_mfma_f32_16x16x32_bf16 v[126:129], v[98:101], v[164:167], v[126:129]
	v_mfma_f32_16x16x32_bf16 v[122:125], v[106:109], v[164:167], v[122:125]
	v_mfma_f32_16x16x32_bf16 v[94:97], v[98:101], v[176:179], v[94:97]
	v_mfma_f32_16x16x32_bf16 v[90:93], v[106:109], v[176:179], v[90:93]
	v_mfma_f32_16x16x32_bf16 v[86:89], v[98:101], v[184:187], v[86:89]
	v_mfma_f32_16x16x32_bf16 v[82:85], v[106:109], v[184:187], v[82:85]
	v_mfma_f32_16x16x32_bf16 v[142:145], v[102:105], v[160:163], v[142:145]
	v_mfma_f32_16x16x32_bf16 v[138:141], v[110:113], v[160:163], v[138:141]
	v_mfma_f32_16x16x32_bf16 v[126:129], v[102:105], v[172:175], v[126:129]
	v_mfma_f32_16x16x32_bf16 v[122:125], v[110:113], v[172:175], v[122:125]
	v_mfma_f32_16x16x32_bf16 v[94:97], v[102:105], v[180:183], v[94:97]
	v_mfma_f32_16x16x32_bf16 v[90:93], v[110:113], v[180:183], v[90:93]
	v_mfma_f32_16x16x32_bf16 v[86:89], v[102:105], v[188:191], v[86:89]
	v_mfma_f32_16x16x32_bf16 v[82:85], v[110:113], v[188:191], v[82:85]
	v_mfma_f32_16x16x32_bf16 v[134:137], v[192:195], v[152:155], v[134:137]
	v_mfma_f32_16x16x32_bf16 v[130:133], v[200:203], v[152:155], v[130:133]
	v_mfma_f32_16x16x32_bf16 v[118:121], v[192:195], v[164:167], v[118:121]
	v_mfma_f32_16x16x32_bf16 v[114:117], v[200:203], v[164:167], v[114:117]
	v_mfma_f32_16x16x32_bf16 v[78:81], v[192:195], v[176:179], v[78:81]
	v_mfma_f32_16x16x32_bf16 v[74:77], v[200:203], v[176:179], v[74:77]
	v_mfma_f32_16x16x32_bf16 v[70:73], v[192:195], v[184:187], v[70:73]
	v_mfma_f32_16x16x32_bf16 v[66:69], v[200:203], v[184:187], v[66:69]
	v_mfma_f32_16x16x32_bf16 v[134:137], v[196:199], v[160:163], v[134:137]
	v_mfma_f32_16x16x32_bf16 v[130:133], v[204:207], v[160:163], v[130:133]
	v_mfma_f32_16x16x32_bf16 v[118:121], v[196:199], v[172:175], v[118:121]
	v_mfma_f32_16x16x32_bf16 v[114:117], v[204:207], v[172:175], v[114:117]
	v_mfma_f32_16x16x32_bf16 v[78:81], v[196:199], v[180:183], v[78:81]
	v_mfma_f32_16x16x32_bf16 v[74:77], v[204:207], v[180:183], v[74:77]
	v_mfma_f32_16x16x32_bf16 v[70:73], v[196:199], v[188:191], v[70:73]
	v_mfma_f32_16x16x32_bf16 v[66:69], v[204:207], v[188:191], v[66:69]
	s_barrier
	s_add_i32 s28, s38, s67
	s_mov_b32 m0, s28
	s_nop 0
	global_load_lds_dwordx4 v0, s[58:59]
	s_add_i32 m0, s28, 0x2000
	s_nop 0
	global_load_lds_dwordx4 v146, s[58:59]
	s_mov_b32 m0, s9
	s_nop 0
	global_load_lds_dwordx4 v0, s[60:61]
	s_mov_b32 m0, s68
	s_nop 0
	global_load_lds_dwordx4 v146, s[60:61]
	ds_read_b128 v[152:155], v171 offset:16384
	ds_read_b128 v[160:163], v171 offset:17408
	ds_read_b128 v[164:167], v171 offset:18432
	ds_read_b128 v[172:175], v171 offset:19456
	ds_read_b128 v[176:179], v171 offset:20480
	ds_read_b128 v[180:183], v171 offset:21504
	ds_read_b128 v[184:187], v171 offset:22528
	ds_read_b128 v[188:191], v171 offset:23552
	s_waitcnt vmcnt(4)
	s_waitcnt lgkmcnt(0)
	s_barrier
	v_mfma_f32_16x16x32_bf16 v[62:65], v[98:101], v[152:155], v[62:65]
	v_mfma_f32_16x16x32_bf16 v[58:61], v[106:109], v[152:155], v[58:61]
	v_mfma_f32_16x16x32_bf16 v[46:49], v[98:101], v[164:167], v[46:49]
	v_mfma_f32_16x16x32_bf16 v[42:45], v[106:109], v[164:167], v[42:45]
	v_mfma_f32_16x16x32_bf16 v[30:33], v[98:101], v[176:179], v[30:33]
	v_mfma_f32_16x16x32_bf16 v[26:29], v[106:109], v[176:179], v[26:29]
	v_mfma_f32_16x16x32_bf16 v[22:25], v[98:101], v[184:187], v[22:25]
	v_mfma_f32_16x16x32_bf16 v[18:21], v[106:109], v[184:187], v[18:21]
	v_mfma_f32_16x16x32_bf16 v[62:65], v[102:105], v[160:163], v[62:65]
	v_mfma_f32_16x16x32_bf16 v[58:61], v[110:113], v[160:163], v[58:61]
	v_mfma_f32_16x16x32_bf16 v[46:49], v[102:105], v[172:175], v[46:49]
	v_mfma_f32_16x16x32_bf16 v[42:45], v[110:113], v[172:175], v[42:45]
	v_mfma_f32_16x16x32_bf16 v[30:33], v[102:105], v[180:183], v[30:33]
	v_mfma_f32_16x16x32_bf16 v[26:29], v[110:113], v[180:183], v[26:29]
	v_mfma_f32_16x16x32_bf16 v[22:25], v[102:105], v[188:191], v[22:25]
	v_mfma_f32_16x16x32_bf16 v[18:21], v[110:113], v[188:191], v[18:21]
	v_mfma_f32_16x16x32_bf16 v[54:57], v[192:195], v[152:155], v[54:57]
	v_mfma_f32_16x16x32_bf16 v[50:53], v[200:203], v[152:155], v[50:53]
	v_mfma_f32_16x16x32_bf16 v[38:41], v[192:195], v[164:167], v[38:41]
	v_mfma_f32_16x16x32_bf16 v[34:37], v[200:203], v[164:167], v[34:37]
	v_mfma_f32_16x16x32_bf16 v[14:17], v[192:195], v[176:179], v[14:17]
	v_mfma_f32_16x16x32_bf16 v[10:13], v[200:203], v[176:179], v[10:13]
	v_mfma_f32_16x16x32_bf16 v[6:9], v[192:195], v[184:187], v[6:9]
	v_mfma_f32_16x16x32_bf16 v[2:5], v[200:203], v[184:187], v[2:5]
	v_mfma_f32_16x16x32_bf16 v[54:57], v[196:199], v[160:163], v[54:57]
	v_mfma_f32_16x16x32_bf16 v[50:53], v[204:207], v[160:163], v[50:53]
	v_mfma_f32_16x16x32_bf16 v[38:41], v[196:199], v[172:175], v[38:41]
	v_mfma_f32_16x16x32_bf16 v[34:37], v[204:207], v[172:175], v[34:37]
	v_mfma_f32_16x16x32_bf16 v[14:17], v[196:199], v[180:183], v[14:17]
	v_mfma_f32_16x16x32_bf16 v[10:13], v[204:207], v[180:183], v[10:13]
	v_mfma_f32_16x16x32_bf16 v[6:9], v[196:199], v[188:191], v[6:9]
	v_mfma_f32_16x16x32_bf16 v[2:5], v[204:207], v[188:191], v[2:5]
	s_barrier
; #define PG8_STAGE(bufoff, gbase, voff) do { _Pragma("unroll") for (int _i = 0; _i < 2; ++_i) \
;         __builtin_amdgcn_global_load_lds((const unsigned*)((const char*)(gbase) + (voff)[_i]), (LAS unsigned*)(lds + (bufoff) + ldsw + _i * 8192), 16, 0, 0); } while (0)
; #define PG8_LDA(dst, b, h) do { _Pragma("unroll") for (int m = 0; m < 4; ++m) _Pragma("unroll") for (int k = 0; k < 2; ++k) dst[m][k] = *(const LAS bf16x8*)(lds + PG8_SA(b, h) + aoff + m * 2048 + k * 1024); } while (0)
; #define PG8_LDB(dst, b, h) do { _Pragma("unroll") for (int n = 0; n < 2; ++n) _Pragma("unroll") for (int k = 0; k < 2; ++k) dst[n][k] = *(const LAS bf16x8*)(lds + PG8_SB(b, h) + boff + n * 2048 + k * 1024); } while (0)
; #define PG8_MMA(ai, bj, At, Bt) do { __builtin_amdgcn_s_setprio(1); _Pragma("unroll") for (int m = 0; m < 4; ++m) _Pragma("unroll") for (int n = 0; n < 2; ++n) _Pragma("unroll") for (int k = 0; k < 2; ++k) \
;         acc[ai][bj][m][n] = __builtin_amdgcn_mfma_f32_16x16x32_bf16(Bt[n][k], At[m][k], acc[ai][bj][m][n], 0, 0, 0); __builtin_amdgcn_s_setprio(0); } while (0)
; #define PG8_WAIT_V(n) asm volatile("s_waitcnt vmcnt(" #n ")" ::: "memory")
; #define PG8_WAIT_L(n) asm volatile("s_waitcnt lgkmcnt(" #n ")" ::: "memory")
; #define PG8_BAR __builtin_amdgcn_s_barrier()
; #define PG8_SCHED __builtin_amdgcn_sched_barrier(0)
; template <class Epi, class Sched>
; __device__ __forceinline__ void gemm_phase(LAS unsigned char* lds, const Gemm g, const Sched& S, const Epi& E) {
;     ...
;             PG8_STAGE(PG8_SB(0, 1), b2 + hstep, voffB);
;             PG8_WAIT_V(6); PG8_BAR; PG8_MMA(1, 1, At, B1); PG8_BAR;
;             PG8_LDB(B0, 1, 0); PG8_SCHED; PG8_LDA(At, 1, 0); PG8_STAGE(PG8_SA(0, 1), a2 + hstep, voffA);
;             PG8_WAIT_L(8); PG8_BAR; PG8_WAIT_L(0); PG8_MMA(0, 0, At, B0); PG8_BAR; PG8_SCHED;
;             PG8_LDB(B1, 1, 1); PG8_STAGE(PG8_SB(1, 0), b3, voffB);
;             PG8_BAR; PG8_WAIT_L(0); PG8_MMA(0, 1, At, B1); PG8_BAR;
	s_add_u32 s28, s58, 0x80000
	s_addc_u32 s29, s59, 0
	s_add_i32 s38, s39, s67
	s_mov_b32 m0, s38
	s_nop 0
	global_load_lds_dwordx4 v0, s[28:29]
	s_add_i32 m0, s38, 0x2000
	s_nop 0
	global_load_lds_dwordx4 v146, s[28:29]
	s_add_u32 s28, s60, 0x80000
	s_addc_u32 s29, s61, 0
	s_mov_b32 m0, s69
	s_nop 0
	global_load_lds_dwordx4 v0, s[28:29]
	s_mov_b32 m0, s70
	s_nop 0
	global_load_lds_dwordx4 v146, s[28:29]
	s_add_i32 s38, 0, 0x18000
	v_add_u32_e32 v110, s38, v169
	ds_read_b128 v[98:101], v110
	ds_read_b128 v[102:105], v110 offset:1024
	ds_read_b128 v[106:109], v110 offset:2048
	ds_read_b128 v[110:113], v110 offset:3072
	ds_read_b128 v[152:155], v171 offset:32768
	ds_read_b128 v[160:163], v171 offset:33792
	ds_read_b128 v[164:167], v171 offset:34816
	ds_read_b128 v[172:175], v171 offset:35840
	ds_read_b128 v[176:179], v171 offset:36864
	ds_read_b128 v[180:183], v171 offset:37888
	ds_read_b128 v[184:187], v171 offset:38912
	ds_read_b128 v[188:191], v171 offset:39936
	s_add_i32 s39, 0, 0x1c000
	v_add_u32_e32 v204, s39, v169
	ds_read_b128 v[192:195], v204
	ds_read_b128 v[196:199], v204 offset:1024
	ds_read_b128 v[200:203], v204 offset:2048
	ds_read_b128 v[204:207], v204 offset:3072
	s_waitcnt lgkmcnt(4)
	s_barrier
	s_waitcnt lgkmcnt(0)
	v_mfma_f32_16x16x32_bf16 v[142:145], v[98:101], v[152:155], v[142:145]
	v_mfma_f32_16x16x32_bf16 v[138:141], v[106:109], v[152:155], v[138:141]
	v_mfma_f32_16x16x32_bf16 v[126:129], v[98:101], v[164:167], v[126:129]
	v_mfma_f32_16x16x32_bf16 v[122:125], v[106:109], v[164:167], v[122:125]
	v_mfma_f32_16x16x32_bf16 v[94:97], v[98:101], v[176:179], v[94:97]
	v_mfma_f32_16x16x32_bf16 v[90:93], v[106:109], v[176:179], v[90:93]
	v_mfma_f32_16x16x32_bf16 v[86:89], v[98:101], v[184:187], v[86:89]
	v_mfma_f32_16x16x32_bf16 v[82:85], v[106:109], v[184:187], v[82:85]
	v_mfma_f32_16x16x32_bf16 v[142:145], v[102:105], v[160:163], v[142:145]
	v_mfma_f32_16x16x32_bf16 v[138:141], v[110:113], v[160:163], v[138:141]
	v_mfma_f32_16x16x32_bf16 v[126:129], v[102:105], v[172:175], v[126:129]
	v_mfma_f32_16x16x32_bf16 v[122:125], v[110:113], v[172:175], v[122:125]
	v_mfma_f32_16x16x32_bf16 v[94:97], v[102:105], v[180:183], v[94:97]
	v_mfma_f32_16x16x32_bf16 v[90:93], v[110:113], v[180:183], v[90:93]
	v_mfma_f32_16x16x32_bf16 v[86:89], v[102:105], v[188:191], v[86:89]
	v_mfma_f32_16x16x32_bf16 v[82:85], v[110:113], v[188:191], v[82:85]
	v_mfma_f32_16x16x32_bf16 v[134:137], v[192:195], v[152:155], v[134:137]
	v_mfma_f32_16x16x32_bf16 v[130:133], v[200:203], v[152:155], v[130:133]
	v_mfma_f32_16x16x32_bf16 v[118:121], v[192:195], v[164:167], v[118:121]
	v_mfma_f32_16x16x32_bf16 v[114:117], v[200:203], v[164:167], v[114:117]
	v_mfma_f32_16x16x32_bf16 v[78:81], v[192:195], v[176:179], v[78:81]
	v_mfma_f32_16x16x32_bf16 v[74:77], v[200:203], v[176:179], v[74:77]
	v_mfma_f32_16x16x32_bf16 v[70:73], v[192:195], v[184:187], v[70:73]
	v_mfma_f32_16x16x32_bf16 v[66:69], v[200:203], v[184:187], v[66:69]
	v_mfma_f32_16x16x32_bf16 v[134:137], v[196:199], v[160:163], v[134:137]
	v_mfma_f32_16x16x32_bf16 v[130:133], v[204:207], v[160:163], v[130:133]
	v_mfma_f32_16x16x32_bf16 v[118:121], v[196:199], v[172:175], v[118:121]
	v_mfma_f32_16x16x32_bf16 v[114:117], v[204:207], v[172:175], v[114:117]
	v_mfma_f32_16x16x32_bf16 v[78:81], v[196:199], v[180:183], v[78:81]
	v_mfma_f32_16x16x32_bf16 v[74:77], v[204:207], v[180:183], v[74:77]
	v_mfma_f32_16x16x32_bf16 v[70:73], v[196:199], v[188:191], v[70:73]
	v_mfma_f32_16x16x32_bf16 v[66:69], v[204:207], v[188:191], v[66:69]
	s_barrier
; #define PG8_STAGE(bufoff, gbase, voff) do { _Pragma("unroll") for (int _i = 0; _i < 2; ++_i) \
;         __builtin_amdgcn_global_load_lds((const unsigned*)((const char*)(gbase) + (voff)[_i]), (LAS unsigned*)(lds + (bufoff) + ldsw + _i * 8192), 16, 0, 0); } while (0)
; #define PG8_LDA(dst, b, h) do { _Pragma("unroll") for (int m = 0; m < 4; ++m) _Pragma("unroll") for (int k = 0; k < 2; ++k) dst[m][k] = *(const LAS bf16x8*)(lds + PG8_SA(b, h) + aoff + m * 2048 + k * 1024); } while (0)
; #define PG8_LDB(dst, b, h) do { _Pragma("unroll") for (int n = 0; n < 2; ++n) _Pragma("unroll") for (int k = 0; k < 2; ++k) dst[n][k] = *(const LAS bf16x8*)(lds + PG8_SB(b, h) + boff + n * 2048 + k * 1024); } while (0)
; #define PG8_MMA(ai, bj, At, Bt) do { __builtin_amdgcn_s_setprio(1); _Pragma("unroll") for (int m = 0; m < 4; ++m) _Pragma("unroll") for (int n = 0; n < 2; ++n) _Pragma("unroll") for (int k = 0; k < 2; ++k) \
;         acc[ai][bj][m][n] = __builtin_amdgcn_mfma_f32_16x16x32_bf16(Bt[n][k], At[m][k], acc[ai][bj][m][n], 0, 0, 0); __builtin_amdgcn_s_setprio(0); } while (0)
; #define PG8_WAIT_V(n) asm volatile("s_waitcnt vmcnt(" #n ")" ::: "memory")
; #define PG8_WAIT_L(n) asm volatile("s_waitcnt lgkmcnt(" #n ")" ::: "memory")
; #define PG8_BAR __builtin_amdgcn_s_barrier()
; #define PG8_SCHED __builtin_amdgcn_sched_barrier(0)
; template <class Epi, class Sched>
; __device__ __forceinline__ void gemm_phase(LAS unsigned char* lds, const Gemm g, const Sched& S, const Epi& E) {
;     ...
;             PG8_LDB(B1, 1, 1); PG8_STAGE(PG8_SB(1, 0), b3, voffB);
;             PG8_BAR; PG8_WAIT_L(0); PG8_MMA(0, 1, At, B1); PG8_BAR;
;             PG8_LDA(At, 1, 1); PG8_STAGE(PG8_SA(1, 0), a3, voffA);
;             PG8_BAR; PG8_WAIT_L(0); PG8_MMA(1, 0, At, B0); PG8_BAR; PG8_SCHED;
;             PG8_STAGE(PG8_SB(1, 1), b3 + hstep, voffB);
;             PG8_WAIT_V(6); PG8_BAR; PG8_MMA(1, 1, At, B1); PG8_BAR;
;         }
;         E(acc, cur, wr, wc, fr, fq);
;         if (!has_next) break;
	s_add_i32 s28, s38, s67
	s_add_u32 s100, s58, s36
	s_addc_u32 s101, s59, s37
	s_mov_b32 m0, s28
	s_nop 0
	global_load_lds_dwordx4 v0, s[100:101]
	s_add_i32 m0, s28, 0x2000
	s_nop 0
	global_load_lds_dwordx4 v146, s[100:101]
	s_mov_b32 m0, s72
	s_add_u32 s100, s60, s36
	s_addc_u32 s101, s61, s37
	global_load_lds_dwordx4 v0, s[100:101]
	s_mov_b32 m0, s73
	s_nop 0
	global_load_lds_dwordx4 v146, s[100:101]
	ds_read_b128 v[152:155], v171 offset:49152
	ds_read_b128 v[160:163], v171 offset:50176
	ds_read_b128 v[164:167], v171 offset:51200
	ds_read_b128 v[172:175], v171 offset:52224
	ds_read_b128 v[176:179], v171 offset:53248
	ds_read_b128 v[180:183], v171 offset:54272
	ds_read_b128 v[184:187], v171 offset:55296
	ds_read_b128 v[188:191], v171 offset:56320
	s_waitcnt vmcnt(4)
	s_waitcnt lgkmcnt(0)
	s_barrier
	v_mfma_f32_16x16x32_bf16 v[62:65], v[98:101], v[152:155], v[62:65]
	v_mfma_f32_16x16x32_bf16 v[58:61], v[106:109], v[152:155], v[58:61]
	v_mfma_f32_16x16x32_bf16 v[46:49], v[98:101], v[164:167], v[46:49]
	v_mfma_f32_16x16x32_bf16 v[42:45], v[106:109], v[164:167], v[42:45]
	v_mfma_f32_16x16x32_bf16 v[30:33], v[98:101], v[176:179], v[30:33]
	v_mfma_f32_16x16x32_bf16 v[26:29], v[106:109], v[176:179], v[26:29]
	v_mfma_f32_16x16x32_bf16 v[22:25], v[98:101], v[184:187], v[22:25]
	v_mfma_f32_16x16x32_bf16 v[18:21], v[106:109], v[184:187], v[18:21]
	v_mfma_f32_16x16x32_bf16 v[62:65], v[102:105], v[160:163], v[62:65]
	v_mfma_f32_16x16x32_bf16 v[58:61], v[110:113], v[160:163], v[58:61]
	v_mfma_f32_16x16x32_bf16 v[46:49], v[102:105], v[172:175], v[46:49]
	v_mfma_f32_16x16x32_bf16 v[42:45], v[110:113], v[172:175], v[42:45]
	v_mfma_f32_16x16x32_bf16 v[30:33], v[102:105], v[180:183], v[30:33]
	v_mfma_f32_16x16x32_bf16 v[26:29], v[110:113], v[180:183], v[26:29]
	v_mfma_f32_16x16x32_bf16 v[22:25], v[102:105], v[188:191], v[22:25]
	v_mfma_f32_16x16x32_bf16 v[18:21], v[110:113], v[188:191], v[18:21]
	s_add_u32 s28, s58, 0x80080
	s_addc_u32 s29, s59, 0
	s_add_i32 s38, s39, s67
	s_mov_b32 m0, s38
	s_nop 0
	global_load_lds_dwordx4 v0, s[28:29]
	s_add_i32 m0, s38, 0x2000
	s_nop 0
	global_load_lds_dwordx4 v146, s[28:29]
	v_mfma_f32_16x16x32_bf16 v[54:57], v[192:195], v[152:155], v[54:57]
	v_mfma_f32_16x16x32_bf16 v[50:53], v[200:203], v[152:155], v[50:53]
	v_mfma_f32_16x16x32_bf16 v[38:41], v[192:195], v[164:167], v[38:41]
	v_mfma_f32_16x16x32_bf16 v[34:37], v[200:203], v[164:167], v[34:37]
	v_mfma_f32_16x16x32_bf16 v[14:17], v[192:195], v[176:179], v[14:17]
	v_mfma_f32_16x16x32_bf16 v[10:13], v[200:203], v[176:179], v[10:13]
	v_mfma_f32_16x16x32_bf16 v[6:9], v[192:195], v[184:187], v[6:9]
	v_mfma_f32_16x16x32_bf16 v[2:5], v[200:203], v[184:187], v[2:5]
	v_mfma_f32_16x16x32_bf16 v[54:57], v[196:199], v[160:163], v[54:57]
	v_mfma_f32_16x16x32_bf16 v[50:53], v[204:207], v[160:163], v[50:53]
	v_mfma_f32_16x16x32_bf16 v[38:41], v[196:199], v[172:175], v[38:41]
	v_mfma_f32_16x16x32_bf16 v[34:37], v[204:207], v[172:175], v[34:37]
	v_mfma_f32_16x16x32_bf16 v[14:17], v[196:199], v[180:183], v[14:17]
	v_mfma_f32_16x16x32_bf16 v[10:13], v[204:207], v[180:183], v[10:13]
	v_mfma_f32_16x16x32_bf16 v[6:9], v[196:199], v[188:191], v[6:9]
	v_mfma_f32_16x16x32_bf16 v[2:5], v[204:207], v[188:191], v[2:5]
	s_add_i32 s81, s81, 2
	s_add_u32 s79, s79, 0x100
	s_addc_u32 s80, s80, 0
	s_cmp_gt_u32 s81, 29
	s_mov_b64 s[28:29], s[56:57]
	s_barrier
	s_cbranch_scc0 .LBB0_99
	s_cmp_lt_i32 s8, 64
	s_cselect_b64 s[58:59], -1, 0
	s_cmp_gt_i32 s8, 63
	s_cbranch_scc0 .LBB0_90
	s_mov_b64 s[60:61], 0x18000
	s_mov_b64 s[28:29], s[46:47]
	s_mov_b64 s[56:57], s[24:25]
	s_branch .LBB0_91

; #define PG8_STAGE(bufoff, gbase, voff) do { _Pragma("unroll") for (int _i = 0; _i < 2; ++_i) \
;         __builtin_amdgcn_global_load_lds((const unsigned*)((const char*)(gbase) + (voff)[_i]), (LAS unsigned*)(lds + (bufoff) + ldsw + _i * 8192), 16, 0, 0); } while (0)
; #define PG8_LDA(dst, b, h) do { _Pragma("unroll") for (int m = 0; m < 4; ++m) _Pragma("unroll") for (int k = 0; k < 2; ++k) dst[m][k] = *(const LAS bf16x8*)(lds + PG8_SA(b, h) + aoff + m * 2048 + k * 1024); } while (0)
; #define PG8_LDB(dst, b, h) do { _Pragma("unroll") for (int n = 0; n < 2; ++n) _Pragma("unroll") for (int k = 0; k < 2; ++k) dst[n][k] = *(const LAS bf16x8*)(lds + PG8_SB(b, h) + boff + n * 2048 + k * 1024); } while (0)
; #define PG8_MMA(ai, bj, At, Bt) do { __builtin_amdgcn_s_setprio(1); _Pragma("unroll") for (int m = 0; m < 4; ++m) _Pragma("unroll") for (int n = 0; n < 2; ++n) _Pragma("unroll") for (int k = 0; k < 2; ++k) \
;         acc[ai][bj][m][n] = __builtin_amdgcn_mfma_f32_16x16x32_bf16(Bt[n][k], At[m][k], acc[ai][bj][m][n], 0, 0, 0); __builtin_amdgcn_s_setprio(0); } while (0)
; #define PG8_WAIT_V(n) asm volatile("s_waitcnt vmcnt(" #n ")" ::: "memory")
; #define PG8_WAIT_L(n) asm volatile("s_waitcnt lgkmcnt(" #n ")" ::: "memory")
; #define PG8_BAR __builtin_amdgcn_s_barrier()
; #define PG8_SCHED __builtin_amdgcn_sched_barrier(0)
; template <class Epi, class Sched>
; __device__ __forceinline__ void gemm_phase(LAS unsigned char* lds, const Gemm g, const Sched& S, const Epi& E) {
;     ...
;             PG8_LDB(B0, 0, 0); PG8_SCHED; PG8_LDA(At, 0, 0); PG8_STAGE(PG8_SA(1, 1), a1 + hstep, voffA);
;             PG8_WAIT_L(8); PG8_BAR; PG8_WAIT_L(0); PG8_MMA(0, 0, At, B0); PG8_BAR; PG8_SCHED;
;             PG8_LDB(B1, 0, 1); PG8_STAGE(PG8_SB(0, 0), b2, voffB);
;             PG8_BAR; PG8_WAIT_L(0); PG8_MMA(0, 1, At, B1); PG8_BAR;
;             PG8_LDA(At, 0, 1); PG8_STAGE(PG8_SA(0, 0), a2, voffA);
;             PG8_BAR; PG8_WAIT_L(0); PG8_MMA(1, 0, At, B0); PG8_BAR; PG8_SCHED;
;             PG8_STAGE(PG8_SB(0, 1), b2 + hstep, voffB);
;             PG8_WAIT_V(6); PG8_BAR; PG8_MMA(1, 1, At, B1); PG8_BAR;
.LBB0_113:
	s_add_u32 s54, s52, 0x100
	s_addc_u32 s55, s53, 0
	s_cmp_eq_u32 s73, 4
	s_cselect_b32 s59, s11, s55
	s_cselect_b32 s58, s29, s54
	s_cselect_b32 s57, s41, s72
	s_cselect_b32 s56, s45, s71
	v_lshl_add_u64 v[156:157], s[52:53], 0, v[134:135]
	s_add_i32 m0, s25, 0xc000
	s_nop 0
	global_load_lds_dwordx4 v[156:157], off
	v_lshl_add_u64 v[156:157], s[52:53], 0, v[132:133]
	s_add_i32 m0, s25, 0xe000
	s_nop 0
	global_load_lds_dwordx4 v[156:157], off
	s_add_i32 s38, 0, 0x10000
	v_add_u32_e32 v152, s38, v137
	ds_read_b128 v[140:143], v152
	ds_read_b128 v[144:147], v152 offset:1024
	ds_read_b128 v[148:151], v152 offset:2048
	ds_read_b128 v[152:155], v152 offset:3072
	ds_read_b128 v[160:163], v139
	ds_read_b128 v[164:167], v139 offset:1024
	ds_read_b128 v[168:171], v139 offset:2048
	ds_read_b128 v[172:175], v139 offset:3072
	ds_read_b128 v[176:179], v139 offset:4096
	ds_read_b128 v[180:183], v139 offset:5120
	ds_read_b128 v[184:187], v139 offset:6144
	ds_read_b128 v[188:191], v139 offset:7168
	s_add_i32 s52, 0, 0x14000
	v_add_u32_e32 v156, s52, v137
	ds_read_b128 v[192:195], v156
	ds_read_b128 v[196:199], v156 offset:1024
	ds_read_b128 v[200:203], v156 offset:2048
	ds_read_b128 v[204:207], v156 offset:3072
	s_waitcnt lgkmcnt(4)
	s_barrier
	s_waitcnt lgkmcnt(0)
	v_mfma_f32_16x16x32_bf16 v[126:129], v[140:143], v[160:163], v[126:129]
	v_mfma_f32_16x16x32_bf16 v[122:125], v[148:151], v[160:163], v[122:125]
	v_mfma_f32_16x16x32_bf16 v[118:121], v[140:143], v[168:171], v[118:121]
	v_mfma_f32_16x16x32_bf16 v[114:117], v[148:151], v[168:171], v[114:117]
	v_mfma_f32_16x16x32_bf16 v[106:109], v[140:143], v[176:179], v[106:109]
	v_mfma_f32_16x16x32_bf16 v[98:101], v[148:151], v[176:179], v[98:101]
	v_mfma_f32_16x16x32_bf16 v[90:93], v[140:143], v[184:187], v[90:93]
	v_mfma_f32_16x16x32_bf16 v[82:85], v[148:151], v[184:187], v[82:85]
	v_mfma_f32_16x16x32_bf16 v[126:129], v[144:147], v[164:167], v[126:129]
	v_mfma_f32_16x16x32_bf16 v[122:125], v[152:155], v[164:167], v[122:125]
	v_mfma_f32_16x16x32_bf16 v[118:121], v[144:147], v[172:175], v[118:121]
	v_mfma_f32_16x16x32_bf16 v[114:117], v[152:155], v[172:175], v[114:117]
	v_mfma_f32_16x16x32_bf16 v[106:109], v[144:147], v[180:183], v[106:109]
	v_mfma_f32_16x16x32_bf16 v[98:101], v[152:155], v[180:183], v[98:101]
	v_mfma_f32_16x16x32_bf16 v[90:93], v[144:147], v[188:191], v[90:93]
	v_mfma_f32_16x16x32_bf16 v[82:85], v[152:155], v[188:191], v[82:85]
	v_mfma_f32_16x16x32_bf16 v[110:113], v[192:195], v[160:163], v[110:113]
	v_mfma_f32_16x16x32_bf16 v[102:105], v[200:203], v[160:163], v[102:105]
	v_mfma_f32_16x16x32_bf16 v[94:97], v[192:195], v[168:171], v[94:97]
	v_mfma_f32_16x16x32_bf16 v[86:89], v[200:203], v[168:171], v[86:89]
	v_mfma_f32_16x16x32_bf16 v[78:81], v[192:195], v[176:179], v[78:81]
	v_mfma_f32_16x16x32_bf16 v[74:77], v[200:203], v[176:179], v[74:77]
	v_mfma_f32_16x16x32_bf16 v[70:73], v[192:195], v[184:187], v[70:73]
	v_mfma_f32_16x16x32_bf16 v[66:69], v[200:203], v[184:187], v[66:69]
	v_mfma_f32_16x16x32_bf16 v[110:113], v[196:199], v[164:167], v[110:113]
	v_mfma_f32_16x16x32_bf16 v[102:105], v[204:207], v[164:167], v[102:105]
	v_mfma_f32_16x16x32_bf16 v[94:97], v[196:199], v[172:175], v[94:97]
	v_mfma_f32_16x16x32_bf16 v[86:89], v[204:207], v[172:175], v[86:89]
	v_mfma_f32_16x16x32_bf16 v[78:81], v[196:199], v[180:183], v[78:81]
	v_mfma_f32_16x16x32_bf16 v[74:77], v[204:207], v[180:183], v[74:77]
	v_mfma_f32_16x16x32_bf16 v[70:73], v[196:199], v[188:191], v[70:73]
	v_mfma_f32_16x16x32_bf16 v[66:69], v[204:207], v[188:191], v[66:69]
	s_barrier
	s_add_i32 s38, s38, s65
	s_mov_b32 m0, s38
	s_nop 0
	global_load_lds_dwordx4 v0, s[56:57]
	s_add_i32 m0, s38, 0x2000
	s_nop 0
	global_load_lds_dwordx4 v130, s[56:57]
	s_mov_b32 m0, s25
	s_nop 0
	global_load_lds_dwordx4 v0, s[58:59]
	s_mov_b32 m0, s27
	s_nop 0
	global_load_lds_dwordx4 v130, s[58:59]
	ds_read_b128 v[160:163], v139 offset:16384
	ds_read_b128 v[164:167], v139 offset:17408
	ds_read_b128 v[168:171], v139 offset:18432
	ds_read_b128 v[172:175], v139 offset:19456
	ds_read_b128 v[176:179], v139 offset:20480
	ds_read_b128 v[180:183], v139 offset:21504
	ds_read_b128 v[184:187], v139 offset:22528
	ds_read_b128 v[188:191], v139 offset:23552
	s_waitcnt vmcnt(4)
	s_waitcnt lgkmcnt(0)
	s_barrier
	v_mfma_f32_16x16x32_bf16 v[62:65], v[140:143], v[160:163], v[62:65]
	v_mfma_f32_16x16x32_bf16 v[58:61], v[148:151], v[160:163], v[58:61]
	v_mfma_f32_16x16x32_bf16 v[54:57], v[140:143], v[168:171], v[54:57]
	v_mfma_f32_16x16x32_bf16 v[50:53], v[148:151], v[168:171], v[50:53]
	v_mfma_f32_16x16x32_bf16 v[38:41], v[140:143], v[176:179], v[38:41]
	v_mfma_f32_16x16x32_bf16 v[34:37], v[148:151], v[176:179], v[34:37]
	v_mfma_f32_16x16x32_bf16 v[22:25], v[140:143], v[184:187], v[22:25]
	v_mfma_f32_16x16x32_bf16 v[18:21], v[148:151], v[184:187], v[18:21]
	v_mfma_f32_16x16x32_bf16 v[62:65], v[144:147], v[164:167], v[62:65]
	v_mfma_f32_16x16x32_bf16 v[58:61], v[152:155], v[164:167], v[58:61]
	v_mfma_f32_16x16x32_bf16 v[54:57], v[144:147], v[172:175], v[54:57]
	v_mfma_f32_16x16x32_bf16 v[50:53], v[152:155], v[172:175], v[50:53]
	v_mfma_f32_16x16x32_bf16 v[38:41], v[144:147], v[180:183], v[38:41]
	v_mfma_f32_16x16x32_bf16 v[34:37], v[152:155], v[180:183], v[34:37]
	v_mfma_f32_16x16x32_bf16 v[22:25], v[144:147], v[188:191], v[22:25]
	v_mfma_f32_16x16x32_bf16 v[18:21], v[152:155], v[188:191], v[18:21]
	v_mfma_f32_16x16x32_bf16 v[46:49], v[192:195], v[160:163], v[46:49]
	v_mfma_f32_16x16x32_bf16 v[42:45], v[200:203], v[160:163], v[42:45]
	v_mfma_f32_16x16x32_bf16 v[30:33], v[192:195], v[168:171], v[30:33]
	v_mfma_f32_16x16x32_bf16 v[26:29], v[200:203], v[168:171], v[26:29]
	v_mfma_f32_16x16x32_bf16 v[14:17], v[192:195], v[176:179], v[14:17]
	v_mfma_f32_16x16x32_bf16 v[10:13], v[200:203], v[176:179], v[10:13]
	v_mfma_f32_16x16x32_bf16 v[6:9], v[192:195], v[184:187], v[6:9]
	v_mfma_f32_16x16x32_bf16 v[2:5], v[200:203], v[184:187], v[2:5]
	v_mfma_f32_16x16x32_bf16 v[46:49], v[196:199], v[164:167], v[46:49]
	v_mfma_f32_16x16x32_bf16 v[42:45], v[204:207], v[164:167], v[42:45]
	v_mfma_f32_16x16x32_bf16 v[30:33], v[196:199], v[172:175], v[30:33]
	v_mfma_f32_16x16x32_bf16 v[26:29], v[204:207], v[172:175], v[26:29]
	v_mfma_f32_16x16x32_bf16 v[14:17], v[196:199], v[180:183], v[14:17]
	v_mfma_f32_16x16x32_bf16 v[10:13], v[204:207], v[180:183], v[10:13]
	v_mfma_f32_16x16x32_bf16 v[6:9], v[196:199], v[188:191], v[6:9]
	v_mfma_f32_16x16x32_bf16 v[2:5], v[204:207], v[188:191], v[2:5]
	s_barrier
; #define PG8_STAGE(bufoff, gbase, voff) do { _Pragma("unroll") for (int _i = 0; _i < 2; ++_i) \
;         __builtin_amdgcn_global_load_lds((const unsigned*)((const char*)(gbase) + (voff)[_i]), (LAS unsigned*)(lds + (bufoff) + ldsw + _i * 8192), 16, 0, 0); } while (0)
; #define PG8_LDA(dst, b, h) do { _Pragma("unroll") for (int m = 0; m < 4; ++m) _Pragma("unroll") for (int k = 0; k < 2; ++k) dst[m][k] = *(const LAS bf16x8*)(lds + PG8_SA(b, h) + aoff + m * 2048 + k * 1024); } while (0)
; #define PG8_LDB(dst, b, h) do { _Pragma("unroll") for (int n = 0; n < 2; ++n) _Pragma("unroll") for (int k = 0; k < 2; ++k) dst[n][k] = *(const LAS bf16x8*)(lds + PG8_SB(b, h) + boff + n * 2048 + k * 1024); } while (0)
; #define PG8_MMA(ai, bj, At, Bt) do { __builtin_amdgcn_s_setprio(1); _Pragma("unroll") for (int m = 0; m < 4; ++m) _Pragma("unroll") for (int n = 0; n < 2; ++n) _Pragma("unroll") for (int k = 0; k < 2; ++k) \
;         acc[ai][bj][m][n] = __builtin_amdgcn_mfma_f32_16x16x32_bf16(Bt[n][k], At[m][k], acc[ai][bj][m][n], 0, 0, 0); __builtin_amdgcn_s_setprio(0); } while (0)
; #define PG8_WAIT_V(n) asm volatile("s_waitcnt vmcnt(" #n ")" ::: "memory")
; #define PG8_WAIT_L(n) asm volatile("s_waitcnt lgkmcnt(" #n ")" ::: "memory")
; #define PG8_BAR __builtin_amdgcn_s_barrier()
; #define PG8_SCHED __builtin_amdgcn_sched_barrier(0)
; template <class Epi, class Sched>
; __device__ __forceinline__ void gemm_phase(LAS unsigned char* lds, const Gemm g, const Sched& S, const Epi& E) {
;     ...
;             PG8_STAGE(PG8_SB(0, 1), b2 + hstep, voffB);
;             PG8_WAIT_V(6); PG8_BAR; PG8_MMA(1, 1, At, B1); PG8_BAR;
;             PG8_LDB(B0, 1, 0); PG8_SCHED; PG8_LDA(At, 1, 0); PG8_STAGE(PG8_SA(0, 1), a2 + hstep, voffA);
;             PG8_WAIT_L(8); PG8_BAR; PG8_WAIT_L(0); PG8_MMA(0, 0, At, B0); PG8_BAR; PG8_SCHED;
;             PG8_LDB(B1, 1, 1); PG8_STAGE(PG8_SB(1, 0), b3, voffB);
;             PG8_BAR; PG8_WAIT_L(0); PG8_MMA(0, 1, At, B1); PG8_BAR;
;             PG8_LDA(At, 1, 1); PG8_STAGE(PG8_SA(1, 0), a3, voffA);
;             PG8_BAR; PG8_WAIT_L(0); PG8_MMA(1, 0, At, B0); PG8_BAR; PG8_SCHED;
;             PG8_STAGE(PG8_SB(1, 1), b3 + hstep, voffB);
	s_add_u32 s38, s56, 0x80000
	s_addc_u32 s39, s57, 0
	s_add_i32 s52, s52, s65
	s_mov_b32 m0, s52
	s_nop 0
	global_load_lds_dwordx4 v0, s[38:39]
	s_add_i32 m0, s52, 0x2000
	s_nop 0
	global_load_lds_dwordx4 v130, s[38:39]
	s_add_u32 s38, s58, 0x80000
	s_addc_u32 s39, s59, 0
	s_mov_b32 m0, s66
	s_nop 0
	global_load_lds_dwordx4 v0, s[38:39]
	s_mov_b32 m0, s67
	s_nop 0
	global_load_lds_dwordx4 v130, s[38:39]
	s_add_i32 s52, 0, 0x18000
	v_add_u32_e32 v152, s52, v137
	ds_read_b128 v[140:143], v152
	ds_read_b128 v[144:147], v152 offset:1024
	ds_read_b128 v[148:151], v152 offset:2048
	ds_read_b128 v[152:155], v152 offset:3072
	ds_read_b128 v[160:163], v139 offset:32768
	ds_read_b128 v[164:167], v139 offset:33792
	ds_read_b128 v[168:171], v139 offset:34816
	ds_read_b128 v[172:175], v139 offset:35840
	ds_read_b128 v[176:179], v139 offset:36864
	ds_read_b128 v[180:183], v139 offset:37888
	ds_read_b128 v[184:187], v139 offset:38912
	ds_read_b128 v[188:191], v139 offset:39936
	s_add_i32 s53, 0, 0x1c000
	v_add_u32_e32 v204, s53, v137
	ds_read_b128 v[192:195], v204
	ds_read_b128 v[196:199], v204 offset:1024
	ds_read_b128 v[200:203], v204 offset:2048
	ds_read_b128 v[204:207], v204 offset:3072
	s_waitcnt lgkmcnt(4)
	s_barrier
	s_waitcnt lgkmcnt(0)
	v_mfma_f32_16x16x32_bf16 v[126:129], v[140:143], v[160:163], v[126:129]
	v_mfma_f32_16x16x32_bf16 v[122:125], v[148:151], v[160:163], v[122:125]
	v_mfma_f32_16x16x32_bf16 v[118:121], v[140:143], v[168:171], v[118:121]
	v_mfma_f32_16x16x32_bf16 v[114:117], v[148:151], v[168:171], v[114:117]
	v_mfma_f32_16x16x32_bf16 v[106:109], v[140:143], v[176:179], v[106:109]
	v_mfma_f32_16x16x32_bf16 v[98:101], v[148:151], v[176:179], v[98:101]
	v_mfma_f32_16x16x32_bf16 v[90:93], v[140:143], v[184:187], v[90:93]
	v_mfma_f32_16x16x32_bf16 v[82:85], v[148:151], v[184:187], v[82:85]
	v_mfma_f32_16x16x32_bf16 v[126:129], v[144:147], v[164:167], v[126:129]
	v_mfma_f32_16x16x32_bf16 v[122:125], v[152:155], v[164:167], v[122:125]
	v_mfma_f32_16x16x32_bf16 v[118:121], v[144:147], v[172:175], v[118:121]
	v_mfma_f32_16x16x32_bf16 v[114:117], v[152:155], v[172:175], v[114:117]
	v_mfma_f32_16x16x32_bf16 v[106:109], v[144:147], v[180:183], v[106:109]
	v_mfma_f32_16x16x32_bf16 v[98:101], v[152:155], v[180:183], v[98:101]
	v_mfma_f32_16x16x32_bf16 v[90:93], v[144:147], v[188:191], v[90:93]
	v_mfma_f32_16x16x32_bf16 v[82:85], v[152:155], v[188:191], v[82:85]
	v_mfma_f32_16x16x32_bf16 v[110:113], v[192:195], v[160:163], v[110:113]
	v_mfma_f32_16x16x32_bf16 v[102:105], v[200:203], v[160:163], v[102:105]
	v_mfma_f32_16x16x32_bf16 v[94:97], v[192:195], v[168:171], v[94:97]
	v_mfma_f32_16x16x32_bf16 v[86:89], v[200:203], v[168:171], v[86:89]
	v_mfma_f32_16x16x32_bf16 v[78:81], v[192:195], v[176:179], v[78:81]
	v_mfma_f32_16x16x32_bf16 v[74:77], v[200:203], v[176:179], v[74:77]
	v_mfma_f32_16x16x32_bf16 v[70:73], v[192:195], v[184:187], v[70:73]
	v_mfma_f32_16x16x32_bf16 v[66:69], v[200:203], v[184:187], v[66:69]
	v_mfma_f32_16x16x32_bf16 v[110:113], v[196:199], v[164:167], v[110:113]
	v_mfma_f32_16x16x32_bf16 v[102:105], v[204:207], v[164:167], v[102:105]
	v_mfma_f32_16x16x32_bf16 v[94:97], v[196:199], v[172:175], v[94:97]
	v_mfma_f32_16x16x32_bf16 v[86:89], v[204:207], v[172:175], v[86:89]
	v_mfma_f32_16x16x32_bf16 v[78:81], v[196:199], v[180:183], v[78:81]
	v_mfma_f32_16x16x32_bf16 v[74:77], v[204:207], v[180:183], v[74:77]
	v_mfma_f32_16x16x32_bf16 v[70:73], v[196:199], v[188:191], v[70:73]
	v_mfma_f32_16x16x32_bf16 v[66:69], v[204:207], v[188:191], v[66:69]
	s_barrier
	s_add_i32 s38, s52, s65
	s_add_u32 s100, s56, s36
	s_addc_u32 s101, s57, s37
	s_mov_b32 m0, s38
	s_nop 0
	global_load_lds_dwordx4 v0, s[100:101]
	s_add_i32 m0, s38, 0x2000
	s_nop 0
	global_load_lds_dwordx4 v130, s[100:101]
	s_mov_b32 m0, s68
	s_add_u32 s100, s58, s36
	s_addc_u32 s101, s59, s37
	global_load_lds_dwordx4 v0, s[100:101]
	s_mov_b32 m0, s69
	s_nop 0
	global_load_lds_dwordx4 v130, s[100:101]
	ds_read_b128 v[160:163], v139 offset:49152
	ds_read_b128 v[164:167], v139 offset:50176
	ds_read_b128 v[168:171], v139 offset:51200
	ds_read_b128 v[172:175], v139 offset:52224
	ds_read_b128 v[176:179], v139 offset:53248
	ds_read_b128 v[180:183], v139 offset:54272
	ds_read_b128 v[184:187], v139 offset:55296
	ds_read_b128 v[188:191], v139 offset:56320
	s_waitcnt vmcnt(4)
	s_waitcnt lgkmcnt(0)
	s_barrier
; #define PG8_STAGE(bufoff, gbase, voff) do { _Pragma("unroll") for (int _i = 0; _i < 2; ++_i) \
;         __builtin_amdgcn_global_load_lds((const unsigned*)((const char*)(gbase) + (voff)[_i]), (LAS unsigned*)(lds + (bufoff) + ldsw + _i * 8192), 16, 0, 0); } while (0)
; #define PG8_LDA(dst, b, h) do { _Pragma("unroll") for (int m = 0; m < 4; ++m) _Pragma("unroll") for (int k = 0; k < 2; ++k) dst[m][k] = *(const LAS bf16x8*)(lds + PG8_SA(b, h) + aoff + m * 2048 + k * 1024); } while (0)
; #define PG8_LDB(dst, b, h) do { _Pragma("unroll") for (int n = 0; n < 2; ++n) _Pragma("unroll") for (int k = 0; k < 2; ++k) dst[n][k] = *(const LAS bf16x8*)(lds + PG8_SB(b, h) + boff + n * 2048 + k * 1024); } while (0)
; #define PG8_WAIT_V(n) asm volatile("s_waitcnt vmcnt(" #n ")" ::: "memory")
; #define PG8_WAIT_L(n) asm volatile("s_waitcnt lgkmcnt(" #n ")" ::: "memory")
; #define PG8_BAR __builtin_amdgcn_s_barrier()
; #define PG8_SCHED __builtin_amdgcn_sched_barrier(0)
;     __device__ __forceinline__ void operator()(const f32x4 (&acc)[2][2][4][2], const Unit& u, int wr, int wc, int fr, int fq) const {
;         const int row0 = u.pm * BM + wr * 64 + fr, col0 = u.pn * BM + wc * 32 + 4 * fq;
;         float* base = part + (size_t)u.ks * Mp * ldc;
; #pragma unroll
;         for (int ai = 0; ai < 2; ++ai)
; #pragma unroll
;             for (int m = 0; m < 4; ++m) { float* rowp = base + (size_t)(row0 + ai * HALF + m * 16) * ldc + col0;
; #pragma unroll
;                 for (int bj = 0; bj < 2; ++bj)
; #pragma unroll
;                     for (int n = 0; n < 2; ++n) *(f32x4*)(rowp + bj * HALF + n * 16) = acc[ai][bj][m][n]; }
;     }
; template <class Epi, class Sched>
; __device__ __forceinline__ void gemm_phase(LAS unsigned char* lds, const Gemm g, const Sched& S, const Epi& E) {
;     ...
;             PG8_LDB(B1, 1, 1); PG8_STAGE(PG8_SB(1, 0), b3, voffB);
;             PG8_BAR; PG8_WAIT_L(0); PG8_MMA(0, 1, At, B1); PG8_BAR;
;             PG8_LDA(At, 1, 1); PG8_STAGE(PG8_SA(1, 0), a3, voffA);
;             PG8_BAR; PG8_WAIT_L(0); PG8_MMA(1, 0, At, B0); PG8_BAR; PG8_SCHED;
;             PG8_STAGE(PG8_SB(1, 1), b3 + hstep, voffB);
;             PG8_WAIT_V(6); PG8_BAR; PG8_MMA(1, 1, At, B1); PG8_BAR;
;         }
;         E(acc, cur, wr, wc, fr, fq);
;         if (!has_next) break;
	v_mfma_f32_16x16x32_bf16 v[62:65], v[140:143], v[160:163], v[62:65]
	v_mfma_f32_16x16x32_bf16 v[58:61], v[148:151], v[160:163], v[58:61]
	v_mfma_f32_16x16x32_bf16 v[54:57], v[140:143], v[168:171], v[54:57]
	v_mfma_f32_16x16x32_bf16 v[50:53], v[148:151], v[168:171], v[50:53]
	v_mfma_f32_16x16x32_bf16 v[38:41], v[140:143], v[176:179], v[38:41]
	v_mfma_f32_16x16x32_bf16 v[34:37], v[148:151], v[176:179], v[34:37]
	v_mfma_f32_16x16x32_bf16 v[22:25], v[140:143], v[184:187], v[22:25]
	v_mfma_f32_16x16x32_bf16 v[18:21], v[148:151], v[184:187], v[18:21]
	v_mfma_f32_16x16x32_bf16 v[62:65], v[144:147], v[164:167], v[62:65]
	v_mfma_f32_16x16x32_bf16 v[58:61], v[152:155], v[164:167], v[58:61]
	v_mfma_f32_16x16x32_bf16 v[54:57], v[144:147], v[172:175], v[54:57]
	v_mfma_f32_16x16x32_bf16 v[50:53], v[152:155], v[172:175], v[50:53]
	v_mfma_f32_16x16x32_bf16 v[38:41], v[144:147], v[180:183], v[38:41]
	v_mfma_f32_16x16x32_bf16 v[34:37], v[152:155], v[180:183], v[34:37]
	v_mfma_f32_16x16x32_bf16 v[22:25], v[144:147], v[188:191], v[22:25]
	v_mfma_f32_16x16x32_bf16 v[18:21], v[152:155], v[188:191], v[18:21]
	s_add_u32 s38, s56, 0x80080
	s_addc_u32 s39, s57, 0
	s_add_i32 s52, s53, s65
	s_mov_b32 m0, s52
	s_nop 0
	global_load_lds_dwordx4 v0, s[38:39]
	s_add_i32 m0, s52, 0x2000
	s_nop 0
	global_load_lds_dwordx4 v130, s[38:39]
	v_mfma_f32_16x16x32_bf16 v[46:49], v[192:195], v[160:163], v[46:49]
	v_mfma_f32_16x16x32_bf16 v[42:45], v[200:203], v[160:163], v[42:45]
	v_mfma_f32_16x16x32_bf16 v[30:33], v[192:195], v[168:171], v[30:33]
	v_mfma_f32_16x16x32_bf16 v[26:29], v[200:203], v[168:171], v[26:29]
	v_mfma_f32_16x16x32_bf16 v[14:17], v[192:195], v[176:179], v[14:17]
	v_mfma_f32_16x16x32_bf16 v[10:13], v[200:203], v[176:179], v[10:13]
	v_mfma_f32_16x16x32_bf16 v[6:9], v[192:195], v[184:187], v[6:9]
	v_mfma_f32_16x16x32_bf16 v[2:5], v[200:203], v[184:187], v[2:5]
	v_mfma_f32_16x16x32_bf16 v[46:49], v[196:199], v[164:167], v[46:49]
	v_mfma_f32_16x16x32_bf16 v[42:45], v[204:207], v[164:167], v[42:45]
	v_mfma_f32_16x16x32_bf16 v[30:33], v[196:199], v[172:175], v[30:33]
	v_mfma_f32_16x16x32_bf16 v[26:29], v[204:207], v[172:175], v[26:29]
	v_mfma_f32_16x16x32_bf16 v[14:17], v[196:199], v[180:183], v[14:17]
	v_mfma_f32_16x16x32_bf16 v[10:13], v[204:207], v[180:183], v[10:13]
	v_mfma_f32_16x16x32_bf16 v[6:9], v[196:199], v[188:191], v[6:9]
	v_mfma_f32_16x16x32_bf16 v[2:5], v[204:207], v[188:191], v[2:5]
	s_add_i32 s73, s73, 2
	s_add_u32 s71, s71, 0x100
	s_addc_u32 s72, s72, 0
	s_cmp_gt_u32 s73, 5
	s_mov_b64 s[52:53], s[54:55]
	s_barrier
	s_cbranch_scc0 .LBB0_113
	s_ashr_i32 s11, s10, 31
	s_lshl_b64 s[10:11], s[10:11], 24
	v_lshl_or_b32 v140, s26, 8, v138
	s_add_u32 s10, s8, s10
	v_lshl_add_u32 v142, s24, 8, v136
	s_addc_u32 s11, s9, s11
	v_ashrrev_i32_e32 v141, 31, v140
	v_ashrrev_i32_e32 v143, 31, v142
	v_lshl_add_u64 v[140:141], v[140:141], 2, s[10:11]
	v_lshlrev_b64 v[144:145], 13, v[142:143]
	v_lshl_add_u64 v[144:145], v[140:141], 0, v[144:145]
	global_store_dwordx4 v[144:145], v[126:129], off
	global_store_dwordx4 v[144:145], v[122:125], off offset:64
	global_store_dwordx4 v[144:145], v[110:113], off offset:512
	global_store_dwordx4 v[144:145], v[102:105], off offset:576
	s_mov_b64 s[10:11], 0x100000
	s_mov_b32 s26, s40
	v_or_b32_e32 v102, 16, v142
	v_ashrrev_i32_e32 v103, 31, v102
	v_lshlrev_b64 v[102:103], 13, v[102:103]
	v_lshl_add_u64 v[102:103], v[140:141], 0, v[102:103]
	global_store_dwordx4 v[102:103], v[118:121], off
	global_store_dwordx4 v[102:103], v[114:117], off offset:64
	global_store_dwordx4 v[102:103], v[94:97], off offset:512
	global_store_dwordx4 v[102:103], v[86:89], off offset:576
	s_mov_b32 s24, s44
	s_mov_b64 s[54:55], s[50:51]
	v_or_b32_e32 v86, 32, v142
	v_ashrrev_i32_e32 v87, 31, v86
	v_lshlrev_b64 v[86:87], 13, v[86:87]
	v_lshl_add_u64 v[86:87], v[140:141], 0, v[86:87]
	global_store_dwordx4 v[86:87], v[106:109], off
	global_store_dwordx4 v[86:87], v[98:101], off offset:64
	global_store_dwordx4 v[86:87], v[78:81], off offset:512
	global_store_dwordx4 v[86:87], v[74:77], off offset:576
	s_mov_b64 s[52:53], s[48:49]
	s_nop 0
	v_or_b32_e32 v74, 48, v142
	v_ashrrev_i32_e32 v75, 31, v74
	v_lshlrev_b64 v[74:75], 13, v[74:75]
	v_lshl_add_u64 v[74:75], v[140:141], 0, v[74:75]
	global_store_dwordx4 v[74:75], v[90:93], off
	global_store_dwordx4 v[74:75], v[82:85], off offset:64
	global_store_dwordx4 v[74:75], v[70:73], off offset:512
	global_store_dwordx4 v[74:75], v[66:69], off offset:576
	s_nop 1
	v_add_co_u32_e32 v68, vcc, s93, v144
	v_lshl_add_u64 v[66:67], v[144:145], 0, s[10:11]
	s_nop 0
	v_addc_co_u32_e32 v69, vcc, 0, v145, vcc
	s_mov_b64 s[10:11], 0x120000
	global_store_dwordx4 v[68:69], v[62:65], off
	global_store_dwordx4 v[66:67], v[58:61], off offset:64
	global_store_dwordx4 v[66:67], v[46:49], off offset:512
	global_store_dwordx4 v[66:67], v[42:45], off offset:576
	s_nop 1
	v_lshl_add_u64 v[42:43], v[144:145], 0, s[10:11]
	s_mov_b32 s10, 0x120000
	v_add_co_u32_e32 v44, vcc, s10, v144
	s_mov_b64 s[10:11], 0x140000
	s_nop 0
	v_addc_co_u32_e32 v45, vcc, 0, v145, vcc
	global_store_dwordx4 v[44:45], v[54:57], off
	global_store_dwordx4 v[42:43], v[50:53], off offset:64
	global_store_dwordx4 v[42:43], v[30:33], off offset:512
	global_store_dwordx4 v[42:43], v[26:29], off offset:576
	s_nop 1
	v_lshl_add_u64 v[26:27], v[144:145], 0, s[10:11]
	s_mov_b32 s10, 0x140000
	v_add_co_u32_e32 v28, vcc, s10, v144
	s_mov_b64 s[10:11], 0x160000
	s_nop 0
	v_addc_co_u32_e32 v29, vcc, 0, v145, vcc
	global_store_dwordx4 v[28:29], v[38:41], off
	global_store_dwordx4 v[26:27], v[34:37], off offset:64
	global_store_dwordx4 v[26:27], v[14:17], off offset:512
	global_store_dwordx4 v[26:27], v[10:13], off offset:576
	s_nop 1
	v_add_co_u32_e32 v12, vcc, 0x160000, v144
	v_lshl_add_u64 v[10:11], v[144:145], 0, s[10:11]
	s_nop 0
	v_addc_co_u32_e32 v13, vcc, 0, v145, vcc
	s_and_b64 vcc, exec, s[46:47]
	s_mov_b32 s10, s28
	global_store_dwordx4 v[12:13], v[22:25], off
	global_store_dwordx4 v[10:11], v[18:21], off offset:64
	global_store_dwordx4 v[10:11], v[6:9], off offset:512
	global_store_dwordx4 v[10:11], v[2:5], off offset:576
	s_cbranch_vccz .LBB0_110
	s_waitcnt vmcnt(0)
	s_cmpk_gt_u32 s60, 0xff
	s_cbranch_scc1 .LBB0_117
	s_barrier

; #define PG8_STAGE(bufoff, gbase, voff) do { _Pragma("unroll") for (int _i = 0; _i < 2; ++_i) \
;         __builtin_amdgcn_global_load_lds((const unsigned*)((const char*)(gbase) + (voff)[_i]), (LAS unsigned*)(lds + (bufoff) + ldsw + _i * 8192), 16, 0, 0); } while (0)
; #define PG8_LDA(dst, b, h) do { _Pragma("unroll") for (int m = 0; m < 4; ++m) _Pragma("unroll") for (int k = 0; k < 2; ++k) dst[m][k] = *(const LAS bf16x8*)(lds + PG8_SA(b, h) + aoff + m * 2048 + k * 1024); } while (0)
; #define PG8_LDB(dst, b, h) do { _Pragma("unroll") for (int n = 0; n < 2; ++n) _Pragma("unroll") for (int k = 0; k < 2; ++k) dst[n][k] = *(const LAS bf16x8*)(lds + PG8_SB(b, h) + boff + n * 2048 + k * 1024); } while (0)
; #define PG8_MMA(ai, bj, At, Bt) do { __builtin_amdgcn_s_setprio(1); _Pragma("unroll") for (int m = 0; m < 4; ++m) _Pragma("unroll") for (int n = 0; n < 2; ++n) _Pragma("unroll") for (int k = 0; k < 2; ++k) \
;         acc[ai][bj][m][n] = __builtin_amdgcn_mfma_f32_16x16x32_bf16(Bt[n][k], At[m][k], acc[ai][bj][m][n], 0, 0, 0); __builtin_amdgcn_s_setprio(0); } while (0)
; #define PG8_WAIT_V(n) asm volatile("s_waitcnt vmcnt(" #n ")" ::: "memory")
; #define PG8_WAIT_L(n) asm volatile("s_waitcnt lgkmcnt(" #n ")" ::: "memory")
; #define PG8_BAR __builtin_amdgcn_s_barrier()
; #define PG8_SCHED __builtin_amdgcn_sched_barrier(0)
; template <class Epi, class Sched>
; __device__ __forceinline__ void gemm_phase(LAS unsigned char* lds, const Gemm g, const Sched& S, const Epi& E) {
;     ...
;             PG8_LDB(B0, 0, 0); PG8_SCHED; PG8_LDA(At, 0, 0); PG8_STAGE(PG8_SA(1, 1), a1 + hstep, voffA);
;             PG8_WAIT_L(8); PG8_BAR; PG8_WAIT_L(0); PG8_MMA(0, 0, At, B0); PG8_BAR; PG8_SCHED;
;             PG8_LDB(B1, 0, 1); PG8_STAGE(PG8_SB(0, 0), b2, voffB);
;             PG8_BAR; PG8_WAIT_L(0); PG8_MMA(0, 1, At, B1); PG8_BAR;
;             PG8_LDA(At, 0, 1); PG8_STAGE(PG8_SA(0, 0), a2, voffA);
;             PG8_BAR; PG8_WAIT_L(0); PG8_MMA(1, 0, At, B0); PG8_BAR; PG8_SCHED;
;             PG8_STAGE(PG8_SB(0, 1), b2 + hstep, voffB);
;             PG8_WAIT_V(6); PG8_BAR; PG8_MMA(1, 1, At, B1); PG8_BAR;
.LBB0_354:
	s_add_u32 s38, s50, 0xfff80080
	s_addc_u32 s39, s51, -1
	s_cmp_eq_u32 s70, 28
	s_cselect_b32 s55, s9, s39
	s_cselect_b32 s54, s66, s38
	s_cselect_b32 s53, s43, s69
	s_cselect_b32 s52, s67, s68
	s_add_i32 m0, s29, 0xc000
	s_nop 0
	global_load_lds_dwordx4 v138, s[50:51]
	s_add_i32 m0, s29, 0xe000
	s_nop 0
	global_load_lds_dwordx4 v136, s[50:51]
	s_add_i32 s71, 0, 0x10000
	v_add_u32_e32 v156, s71, v145
	ds_read_b128 v[140:143], v156
	ds_read_b128 v[148:151], v156 offset:1024
	ds_read_b128 v[152:155], v156 offset:2048
	ds_read_b128 v[160:163], v156 offset:3072
	ds_read_b128 v[164:167], v147
	ds_read_b128 v[168:171], v147 offset:1024
	ds_read_b128 v[172:175], v147 offset:2048
	ds_read_b128 v[176:179], v147 offset:3072
	ds_read_b128 v[180:183], v147 offset:4096
	ds_read_b128 v[184:187], v147 offset:5120
	ds_read_b128 v[188:191], v147 offset:6144
	ds_read_b128 v[192:195], v147 offset:7168
	s_add_i32 s38, 0, 0x14000
	v_add_u32_e32 v156, s38, v145
	ds_read_b128 v[196:199], v156
	ds_read_b128 v[200:203], v156 offset:1024
	ds_read_b128 v[204:207], v156 offset:2048
	ds_read_b128 v[210:213], v156 offset:3072
	s_waitcnt lgkmcnt(4)
	s_barrier
	s_waitcnt lgkmcnt(0)
	v_mfma_f32_16x16x32_bf16 v[126:129], v[140:143], v[164:167], v[126:129]
	v_mfma_f32_16x16x32_bf16 v[122:125], v[152:155], v[164:167], v[122:125]
	v_mfma_f32_16x16x32_bf16 v[118:121], v[140:143], v[172:175], v[118:121]
	v_mfma_f32_16x16x32_bf16 v[110:113], v[152:155], v[172:175], v[110:113]
	v_mfma_f32_16x16x32_bf16 v[102:105], v[140:143], v[180:183], v[102:105]
	v_mfma_f32_16x16x32_bf16 v[94:97], v[152:155], v[180:183], v[94:97]
	v_mfma_f32_16x16x32_bf16 v[86:89], v[140:143], v[188:191], v[86:89]
	v_mfma_f32_16x16x32_bf16 v[78:81], v[152:155], v[188:191], v[78:81]
	v_mfma_f32_16x16x32_bf16 v[126:129], v[148:151], v[168:171], v[126:129]
	v_mfma_f32_16x16x32_bf16 v[122:125], v[160:163], v[168:171], v[122:125]
	v_mfma_f32_16x16x32_bf16 v[118:121], v[148:151], v[176:179], v[118:121]
	v_mfma_f32_16x16x32_bf16 v[110:113], v[160:163], v[176:179], v[110:113]
	v_mfma_f32_16x16x32_bf16 v[102:105], v[148:151], v[184:187], v[102:105]
	v_mfma_f32_16x16x32_bf16 v[94:97], v[160:163], v[184:187], v[94:97]
	v_mfma_f32_16x16x32_bf16 v[86:89], v[148:151], v[192:195], v[86:89]
	v_mfma_f32_16x16x32_bf16 v[78:81], v[160:163], v[192:195], v[78:81]
	v_mfma_f32_16x16x32_bf16 v[114:117], v[196:199], v[164:167], v[114:117]
	v_mfma_f32_16x16x32_bf16 v[106:109], v[204:207], v[164:167], v[106:109]
	v_mfma_f32_16x16x32_bf16 v[98:101], v[196:199], v[172:175], v[98:101]
	v_mfma_f32_16x16x32_bf16 v[90:93], v[204:207], v[172:175], v[90:93]
	v_mfma_f32_16x16x32_bf16 v[82:85], v[196:199], v[180:183], v[82:85]
	v_mfma_f32_16x16x32_bf16 v[74:77], v[204:207], v[180:183], v[74:77]
	v_mfma_f32_16x16x32_bf16 v[70:73], v[196:199], v[188:191], v[70:73]
	v_mfma_f32_16x16x32_bf16 v[66:69], v[204:207], v[188:191], v[66:69]
	v_mfma_f32_16x16x32_bf16 v[114:117], v[200:203], v[168:171], v[114:117]
	v_mfma_f32_16x16x32_bf16 v[106:109], v[210:213], v[168:171], v[106:109]
	v_mfma_f32_16x16x32_bf16 v[98:101], v[200:203], v[176:179], v[98:101]
	v_mfma_f32_16x16x32_bf16 v[90:93], v[210:213], v[176:179], v[90:93]
	v_mfma_f32_16x16x32_bf16 v[82:85], v[200:203], v[184:187], v[82:85]
	v_mfma_f32_16x16x32_bf16 v[74:77], v[210:213], v[184:187], v[74:77]
	v_mfma_f32_16x16x32_bf16 v[70:73], v[200:203], v[192:195], v[70:73]
	v_mfma_f32_16x16x32_bf16 v[66:69], v[210:213], v[192:195], v[66:69]
	s_barrier
	s_add_i32 s39, s71, s56
	s_mov_b32 m0, s39
	s_nop 0
	global_load_lds_dwordx4 v0, s[52:53]
	s_add_i32 m0, s39, 0x2000
	s_nop 0
	global_load_lds_dwordx4 v134, s[52:53]
	s_mov_b32 m0, s29
	s_nop 0
	global_load_lds_dwordx4 v130, s[54:55]
	s_mov_b32 m0, s41
	s_nop 0
	global_load_lds_dwordx4 v132, s[54:55]
	ds_read_b128 v[164:167], v147 offset:16384
	ds_read_b128 v[168:171], v147 offset:17408
	ds_read_b128 v[172:175], v147 offset:18432
	ds_read_b128 v[176:179], v147 offset:19456
	ds_read_b128 v[180:183], v147 offset:20480
	ds_read_b128 v[184:187], v147 offset:21504
	ds_read_b128 v[188:191], v147 offset:22528
	ds_read_b128 v[192:195], v147 offset:23552
	s_waitcnt vmcnt(4)
	s_waitcnt lgkmcnt(0)
	s_barrier
	v_mfma_f32_16x16x32_bf16 v[62:65], v[140:143], v[164:167], v[62:65]
	v_mfma_f32_16x16x32_bf16 v[58:61], v[152:155], v[164:167], v[58:61]
	v_mfma_f32_16x16x32_bf16 v[54:57], v[140:143], v[172:175], v[54:57]
	v_mfma_f32_16x16x32_bf16 v[46:49], v[152:155], v[172:175], v[46:49]
	v_mfma_f32_16x16x32_bf16 v[38:41], v[140:143], v[180:183], v[38:41]
	v_mfma_f32_16x16x32_bf16 v[30:33], v[152:155], v[180:183], v[30:33]
	v_mfma_f32_16x16x32_bf16 v[22:25], v[140:143], v[188:191], v[22:25]
	v_mfma_f32_16x16x32_bf16 v[14:17], v[152:155], v[188:191], v[14:17]
	v_mfma_f32_16x16x32_bf16 v[62:65], v[148:151], v[168:171], v[62:65]
	v_mfma_f32_16x16x32_bf16 v[58:61], v[160:163], v[168:171], v[58:61]
	v_mfma_f32_16x16x32_bf16 v[54:57], v[148:151], v[176:179], v[54:57]
	v_mfma_f32_16x16x32_bf16 v[46:49], v[160:163], v[176:179], v[46:49]
	v_mfma_f32_16x16x32_bf16 v[38:41], v[148:151], v[184:187], v[38:41]
	v_mfma_f32_16x16x32_bf16 v[30:33], v[160:163], v[184:187], v[30:33]
	v_mfma_f32_16x16x32_bf16 v[22:25], v[148:151], v[192:195], v[22:25]
	v_mfma_f32_16x16x32_bf16 v[14:17], v[160:163], v[192:195], v[14:17]
	v_mfma_f32_16x16x32_bf16 v[50:53], v[196:199], v[164:167], v[50:53]
	v_mfma_f32_16x16x32_bf16 v[42:45], v[204:207], v[164:167], v[42:45]
	v_mfma_f32_16x16x32_bf16 v[34:37], v[196:199], v[172:175], v[34:37]
	v_mfma_f32_16x16x32_bf16 v[26:29], v[204:207], v[172:175], v[26:29]
	v_mfma_f32_16x16x32_bf16 v[18:21], v[196:199], v[180:183], v[18:21]
	v_mfma_f32_16x16x32_bf16 v[10:13], v[204:207], v[180:183], v[10:13]
	v_mfma_f32_16x16x32_bf16 v[6:9], v[196:199], v[188:191], v[6:9]
	v_mfma_f32_16x16x32_bf16 v[2:5], v[204:207], v[188:191], v[2:5]
	v_mfma_f32_16x16x32_bf16 v[50:53], v[200:203], v[168:171], v[50:53]
	v_mfma_f32_16x16x32_bf16 v[42:45], v[210:213], v[168:171], v[42:45]
	v_mfma_f32_16x16x32_bf16 v[34:37], v[200:203], v[176:179], v[34:37]
	v_mfma_f32_16x16x32_bf16 v[26:29], v[210:213], v[176:179], v[26:29]
	v_mfma_f32_16x16x32_bf16 v[18:21], v[200:203], v[184:187], v[18:21]
	v_mfma_f32_16x16x32_bf16 v[10:13], v[210:213], v[184:187], v[10:13]
	v_mfma_f32_16x16x32_bf16 v[6:9], v[200:203], v[192:195], v[6:9]
	v_mfma_f32_16x16x32_bf16 v[2:5], v[210:213], v[192:195], v[2:5]
	s_barrier
; #define PG8_STAGE(bufoff, gbase, voff) do { _Pragma("unroll") for (int _i = 0; _i < 2; ++_i) \
;         __builtin_amdgcn_global_load_lds((const unsigned*)((const char*)(gbase) + (voff)[_i]), (LAS unsigned*)(lds + (bufoff) + ldsw + _i * 8192), 16, 0, 0); } while (0)
; #define PG8_LDA(dst, b, h) do { _Pragma("unroll") for (int m = 0; m < 4; ++m) _Pragma("unroll") for (int k = 0; k < 2; ++k) dst[m][k] = *(const LAS bf16x8*)(lds + PG8_SA(b, h) + aoff + m * 2048 + k * 1024); } while (0)
; #define PG8_LDB(dst, b, h) do { _Pragma("unroll") for (int n = 0; n < 2; ++n) _Pragma("unroll") for (int k = 0; k < 2; ++k) dst[n][k] = *(const LAS bf16x8*)(lds + PG8_SB(b, h) + boff + n * 2048 + k * 1024); } while (0)
; #define PG8_MMA(ai, bj, At, Bt) do { __builtin_amdgcn_s_setprio(1); _Pragma("unroll") for (int m = 0; m < 4; ++m) _Pragma("unroll") for (int n = 0; n < 2; ++n) _Pragma("unroll") for (int k = 0; k < 2; ++k) \
;         acc[ai][bj][m][n] = __builtin_amdgcn_mfma_f32_16x16x32_bf16(Bt[n][k], At[m][k], acc[ai][bj][m][n], 0, 0, 0); __builtin_amdgcn_s_setprio(0); } while (0)
; #define PG8_WAIT_V(n) asm volatile("s_waitcnt vmcnt(" #n ")" ::: "memory")
; #define PG8_WAIT_L(n) asm volatile("s_waitcnt lgkmcnt(" #n ")" ::: "memory")
; #define PG8_BAR __builtin_amdgcn_s_barrier()
; #define PG8_SCHED __builtin_amdgcn_sched_barrier(0)
; template <class Epi, class Sched>
; __device__ __forceinline__ void gemm_phase(LAS unsigned char* lds, const Gemm g, const Sched& S, const Epi& E) {
;     ...
;             PG8_STAGE(PG8_SB(0, 1), b2 + hstep, voffB);
;             PG8_WAIT_V(6); PG8_BAR; PG8_MMA(1, 1, At, B1); PG8_BAR;
;             PG8_LDB(B0, 1, 0); PG8_SCHED; PG8_LDA(At, 1, 0); PG8_STAGE(PG8_SA(0, 1), a2 + hstep, voffA);
;             PG8_WAIT_L(8); PG8_BAR; PG8_WAIT_L(0); PG8_MMA(0, 0, At, B0); PG8_BAR; PG8_SCHED;
;             PG8_LDB(B1, 1, 1); PG8_STAGE(PG8_SB(1, 0), b3, voffB);
;             PG8_BAR; PG8_WAIT_L(0); PG8_MMA(0, 1, At, B1); PG8_BAR;
;             PG8_LDA(At, 1, 1); PG8_STAGE(PG8_SA(1, 0), a3, voffA);
;             PG8_BAR; PG8_WAIT_L(0); PG8_MMA(1, 0, At, B0); PG8_BAR; PG8_SCHED;
;             PG8_STAGE(PG8_SB(1, 1), b3 + hstep, voffB);
	s_add_u32 s72, s52, 0x80000
	s_addc_u32 s73, s53, 0
	s_add_i32 s38, s38, s56
	s_mov_b32 m0, s38
	s_nop 0
	global_load_lds_dwordx4 v0, s[72:73]
	s_add_i32 m0, s38, 0x2000
	s_nop 0
	global_load_lds_dwordx4 v134, s[72:73]
	s_add_u32 s54, s54, 0x80000
	s_addc_u32 s55, s55, 0
	s_mov_b32 m0, s57
	s_nop 0
	global_load_lds_dwordx4 v130, s[54:55]
	s_mov_b32 m0, s58
	s_nop 0
	global_load_lds_dwordx4 v132, s[54:55]
	s_add_i32 s38, 0, 0x18000
	v_add_u32_e32 v160, s38, v145
	ds_read_b128 v[140:143], v160
	ds_read_b128 v[148:151], v160 offset:1024
	ds_read_b128 v[152:155], v160 offset:2048
	ds_read_b128 v[160:163], v160 offset:3072
	ds_read_b128 v[164:167], v147 offset:32768
	ds_read_b128 v[168:171], v147 offset:33792
	ds_read_b128 v[172:175], v147 offset:34816
	ds_read_b128 v[176:179], v147 offset:35840
	ds_read_b128 v[180:183], v147 offset:36864
	ds_read_b128 v[184:187], v147 offset:37888
	ds_read_b128 v[188:191], v147 offset:38912
	ds_read_b128 v[192:195], v147 offset:39936
	s_add_i32 s39, 0, 0x1c000
	v_add_u32_e32 v210, s39, v145
	ds_read_b128 v[196:199], v210
	ds_read_b128 v[200:203], v210 offset:1024
	ds_read_b128 v[204:207], v210 offset:2048
	ds_read_b128 v[210:213], v210 offset:3072
	s_waitcnt lgkmcnt(4)
	s_barrier
	s_waitcnt lgkmcnt(0)
	v_mfma_f32_16x16x32_bf16 v[126:129], v[140:143], v[164:167], v[126:129]
	v_mfma_f32_16x16x32_bf16 v[122:125], v[152:155], v[164:167], v[122:125]
	v_mfma_f32_16x16x32_bf16 v[118:121], v[140:143], v[172:175], v[118:121]
	v_mfma_f32_16x16x32_bf16 v[110:113], v[152:155], v[172:175], v[110:113]
	v_mfma_f32_16x16x32_bf16 v[102:105], v[140:143], v[180:183], v[102:105]
	v_mfma_f32_16x16x32_bf16 v[94:97], v[152:155], v[180:183], v[94:97]
	v_mfma_f32_16x16x32_bf16 v[86:89], v[140:143], v[188:191], v[86:89]
	v_mfma_f32_16x16x32_bf16 v[78:81], v[152:155], v[188:191], v[78:81]
	v_mfma_f32_16x16x32_bf16 v[126:129], v[148:151], v[168:171], v[126:129]
	v_mfma_f32_16x16x32_bf16 v[122:125], v[160:163], v[168:171], v[122:125]
	v_mfma_f32_16x16x32_bf16 v[118:121], v[148:151], v[176:179], v[118:121]
	v_mfma_f32_16x16x32_bf16 v[110:113], v[160:163], v[176:179], v[110:113]
	v_mfma_f32_16x16x32_bf16 v[102:105], v[148:151], v[184:187], v[102:105]
	v_mfma_f32_16x16x32_bf16 v[94:97], v[160:163], v[184:187], v[94:97]
	v_mfma_f32_16x16x32_bf16 v[86:89], v[148:151], v[192:195], v[86:89]
	v_mfma_f32_16x16x32_bf16 v[78:81], v[160:163], v[192:195], v[78:81]
	v_mfma_f32_16x16x32_bf16 v[114:117], v[196:199], v[164:167], v[114:117]
	v_mfma_f32_16x16x32_bf16 v[106:109], v[204:207], v[164:167], v[106:109]
	v_mfma_f32_16x16x32_bf16 v[98:101], v[196:199], v[172:175], v[98:101]
	v_mfma_f32_16x16x32_bf16 v[90:93], v[204:207], v[172:175], v[90:93]
	v_mfma_f32_16x16x32_bf16 v[82:85], v[196:199], v[180:183], v[82:85]
	v_mfma_f32_16x16x32_bf16 v[74:77], v[204:207], v[180:183], v[74:77]
	v_mfma_f32_16x16x32_bf16 v[70:73], v[196:199], v[188:191], v[70:73]
	v_mfma_f32_16x16x32_bf16 v[66:69], v[204:207], v[188:191], v[66:69]
	v_mfma_f32_16x16x32_bf16 v[114:117], v[200:203], v[168:171], v[114:117]
	v_mfma_f32_16x16x32_bf16 v[106:109], v[210:213], v[168:171], v[106:109]
	v_mfma_f32_16x16x32_bf16 v[98:101], v[200:203], v[176:179], v[98:101]
	v_mfma_f32_16x16x32_bf16 v[90:93], v[210:213], v[176:179], v[90:93]
	v_mfma_f32_16x16x32_bf16 v[82:85], v[200:203], v[184:187], v[82:85]
	v_mfma_f32_16x16x32_bf16 v[74:77], v[210:213], v[184:187], v[74:77]
	v_mfma_f32_16x16x32_bf16 v[70:73], v[200:203], v[192:195], v[70:73]
	v_mfma_f32_16x16x32_bf16 v[66:69], v[210:213], v[192:195], v[66:69]
	s_barrier
	s_add_i32 s38, s38, s56
	s_add_u32 s100, s52, s36
	s_addc_u32 s101, s53, s37
	s_mov_b32 m0, s38
	s_nop 0
	global_load_lds_dwordx4 v0, s[100:101]
	s_add_i32 m0, s38, 0x2000
	s_nop 0
	global_load_lds_dwordx4 v134, s[100:101]
	s_mov_b32 m0, s59
	s_add_u32 s100, s54, s36
	s_addc_u32 s101, s55, s37
	s_sub_u32 s100, s100, 0x80000
	s_subb_u32 s101, s101, 0
	global_load_lds_dwordx4 v130, s[100:101]
	s_mov_b32 m0, s60
	s_nop 0
	global_load_lds_dwordx4 v132, s[100:101]
	ds_read_b128 v[164:167], v147 offset:49152
	ds_read_b128 v[168:171], v147 offset:50176
	ds_read_b128 v[172:175], v147 offset:51200
	ds_read_b128 v[176:179], v147 offset:52224
	ds_read_b128 v[180:183], v147 offset:53248
	ds_read_b128 v[184:187], v147 offset:54272
	ds_read_b128 v[188:191], v147 offset:55296
	ds_read_b128 v[192:195], v147 offset:56320
	s_waitcnt vmcnt(4)
	s_waitcnt lgkmcnt(0)
	s_barrier
; #define PG8_STAGE(bufoff, gbase, voff) do { _Pragma("unroll") for (int _i = 0; _i < 2; ++_i) \
;         __builtin_amdgcn_global_load_lds((const unsigned*)((const char*)(gbase) + (voff)[_i]), (LAS unsigned*)(lds + (bufoff) + ldsw + _i * 8192), 16, 0, 0); } while (0)
; #define PG8_LDA(dst, b, h) do { _Pragma("unroll") for (int m = 0; m < 4; ++m) _Pragma("unroll") for (int k = 0; k < 2; ++k) dst[m][k] = *(const LAS bf16x8*)(lds + PG8_SA(b, h) + aoff + m * 2048 + k * 1024); } while (0)
; #define PG8_MMA(ai, bj, At, Bt) do { __builtin_amdgcn_s_setprio(1); _Pragma("unroll") for (int m = 0; m < 4; ++m) _Pragma("unroll") for (int n = 0; n < 2; ++n) _Pragma("unroll") for (int k = 0; k < 2; ++k) \
;         acc[ai][bj][m][n] = __builtin_amdgcn_mfma_f32_16x16x32_bf16(Bt[n][k], At[m][k], acc[ai][bj][m][n], 0, 0, 0); __builtin_amdgcn_s_setprio(0); } while (0)
; #define PG8_WAIT_V(n) asm volatile("s_waitcnt vmcnt(" #n ")" ::: "memory")
; #define PG8_WAIT_L(n) asm volatile("s_waitcnt lgkmcnt(" #n ")" ::: "memory")
; #define PG8_BAR __builtin_amdgcn_s_barrier()
; #define PG8_SCHED __builtin_amdgcn_sched_barrier(0)
; template <class Epi, class Sched>
; __device__ __forceinline__ void gemm_phase(LAS unsigned char* lds, const Gemm g, const Sched& S, const Epi& E) {
;     ...
;             PG8_LDA(At, 1, 1); PG8_STAGE(PG8_SA(1, 0), a3, voffA);
;             PG8_BAR; PG8_WAIT_L(0); PG8_MMA(1, 0, At, B0); PG8_BAR; PG8_SCHED;
;             PG8_STAGE(PG8_SB(1, 1), b3 + hstep, voffB);
;             PG8_WAIT_V(6); PG8_BAR; PG8_MMA(1, 1, At, B1); PG8_BAR;
;         }
;         E(acc, cur, wr, wc, fr, fq);
;         if (!has_next) break;
	v_mfma_f32_16x16x32_bf16 v[62:65], v[140:143], v[164:167], v[62:65]
	v_mfma_f32_16x16x32_bf16 v[58:61], v[152:155], v[164:167], v[58:61]
	v_mfma_f32_16x16x32_bf16 v[54:57], v[140:143], v[172:175], v[54:57]
	v_mfma_f32_16x16x32_bf16 v[46:49], v[152:155], v[172:175], v[46:49]
	v_mfma_f32_16x16x32_bf16 v[38:41], v[140:143], v[180:183], v[38:41]
	v_mfma_f32_16x16x32_bf16 v[30:33], v[152:155], v[180:183], v[30:33]
	v_mfma_f32_16x16x32_bf16 v[22:25], v[140:143], v[188:191], v[22:25]
	v_mfma_f32_16x16x32_bf16 v[14:17], v[152:155], v[188:191], v[14:17]
	v_mfma_f32_16x16x32_bf16 v[62:65], v[148:151], v[168:171], v[62:65]
	v_mfma_f32_16x16x32_bf16 v[58:61], v[160:163], v[168:171], v[58:61]
	v_mfma_f32_16x16x32_bf16 v[54:57], v[148:151], v[176:179], v[54:57]
	v_mfma_f32_16x16x32_bf16 v[46:49], v[160:163], v[176:179], v[46:49]
	v_mfma_f32_16x16x32_bf16 v[38:41], v[148:151], v[184:187], v[38:41]
	v_mfma_f32_16x16x32_bf16 v[30:33], v[160:163], v[184:187], v[30:33]
	v_mfma_f32_16x16x32_bf16 v[22:25], v[148:151], v[192:195], v[22:25]
	v_mfma_f32_16x16x32_bf16 v[14:17], v[160:163], v[192:195], v[14:17]
	s_add_u32 s52, s52, 0x80080
	s_addc_u32 s53, s53, 0
	s_add_i32 s38, s39, s56
	s_mov_b32 m0, s38
	s_nop 0
	global_load_lds_dwordx4 v0, s[52:53]
	s_add_i32 m0, s38, 0x2000
	s_nop 0
	global_load_lds_dwordx4 v134, s[52:53]
	v_mfma_f32_16x16x32_bf16 v[50:53], v[196:199], v[164:167], v[50:53]
	v_mfma_f32_16x16x32_bf16 v[42:45], v[204:207], v[164:167], v[42:45]
	v_mfma_f32_16x16x32_bf16 v[34:37], v[196:199], v[172:175], v[34:37]
	v_mfma_f32_16x16x32_bf16 v[26:29], v[204:207], v[172:175], v[26:29]
	v_mfma_f32_16x16x32_bf16 v[18:21], v[196:199], v[180:183], v[18:21]
	v_mfma_f32_16x16x32_bf16 v[10:13], v[204:207], v[180:183], v[10:13]
	v_mfma_f32_16x16x32_bf16 v[6:9], v[196:199], v[188:191], v[6:9]
	v_mfma_f32_16x16x32_bf16 v[2:5], v[204:207], v[188:191], v[2:5]
	v_mfma_f32_16x16x32_bf16 v[50:53], v[200:203], v[168:171], v[50:53]
	v_mfma_f32_16x16x32_bf16 v[42:45], v[210:213], v[168:171], v[42:45]
	v_mfma_f32_16x16x32_bf16 v[34:37], v[200:203], v[176:179], v[34:37]
	v_mfma_f32_16x16x32_bf16 v[26:29], v[210:213], v[176:179], v[26:29]
	v_mfma_f32_16x16x32_bf16 v[18:21], v[200:203], v[184:187], v[18:21]
	v_mfma_f32_16x16x32_bf16 v[10:13], v[210:213], v[184:187], v[10:13]
	v_mfma_f32_16x16x32_bf16 v[6:9], v[200:203], v[192:195], v[6:9]
	v_mfma_f32_16x16x32_bf16 v[2:5], v[210:213], v[192:195], v[2:5]
	s_add_i32 s70, s70, 2
	s_add_u32 s68, s68, 0x100
	s_addc_u32 s69, s69, 0
	s_add_u32 s50, s50, 0x100
	s_addc_u32 s51, s51, 0
	s_cmp_gt_u32 s70, 29
	s_barrier
	s_cbranch_scc0 .LBB0_354
; __device__ __forceinline__ unsigned cvt_pk_bf16(float lo, float hi) { unsigned r; asm("v_cvt_pk_bf16_f32 %0, %1, %2" : "=v"(r) : "v"(lo), "v"(hi)); return r; }
; #define PG8_WAIT_V(n) asm volatile("s_waitcnt vmcnt(" #n ")" ::: "memory")
; #define PG8_BAR __builtin_amdgcn_s_barrier()
;     __device__ __forceinline__ void operator()(const f32x4 (&acc)[2][2][4][2], const Unit& u, int wr, int wc, int fr, int fq) const {
;         const int row0 = u.pm * BM + wr * 64 + fr, col0 = u.pn * BM + wc * 32 + 8 * fq;
; #pragma unroll
;         for (int ai = 0; ai < 2; ++ai)
; #pragma unroll
;             for (int m = 0; m < 4; ++m) { bf16_t* rowp = O + (size_t)(row0 + ai * HALF + m * 16) * ldc + col0;
; #pragma unroll
;                 for (int bj = 0; bj < 2; ++bj) { f32x4 v0 = acc[ai][bj][m][0], v1 = acc[ai][bj][m][1];
;                     if (ACT == 1) {
; #pragma unroll
;                         for (int j = 0; j < 4; ++j) { float a = fmaxf(v0[j], 0.f), b = fmaxf(v1[j], 0.f); v0[j] = a * a; v1[j] = b * b; } }
;                     u32x4 w; w.x = cvt_pk_bf16(v0[0], v0[1]); w.y = cvt_pk_bf16(v0[2], v0[3]); w.z = cvt_pk_bf16(v1[0], v1[1]); w.w = cvt_pk_bf16(v1[2], v1[3]);
;                     if (ACT == 1) __builtin_nontemporal_store(w, (u32x4*)(rowp + bj * HALF));
;                     else *(u32x4*)(rowp + bj * HALF) = w; } }
; template <class Epi, class Sched>
; __device__ __forceinline__ void gemm_phase(LAS unsigned char* lds, const Gemm g, const Sched& S, const Epi& E) {
;     ...
;         E(acc, cur, wr, wc, fr, fq);
;         if (!has_next) break;
; #pragma unroll
;         for (int a = 0; a < 2; ++a)
; #pragma unroll
;             for (int b = 0; b < 2; ++b)
; #pragma unroll
;                 for (int m = 0; m < 4; ++m)
; #pragma unroll
;                     for (int n = 0; n < 2; ++n) acc[a][b][m][n] = (f32x4){0.f, 0.f, 0.f, 0.f};
;         cur = nxt; cA = nA; cB = nB; ++ui;
;     }
;     PG8_WAIT_V(0);
;     if (wr == 0) PG8_BAR;
;     PG8_BAR;
	s_load_dwordx2 s[50:51], s[0:1], 0xc0
	v_lshl_add_u32 v150, s28, 8, v144
	v_lshl_or_b32 v142, s40, 8, v146
	v_ashrrev_i32_e32 v143, 31, v142
	v_cvt_pk_bf16_f32 v70, v70, v71
	s_waitcnt lgkmcnt(0)
	v_mov_b64_e32 v[140:141], s[50:51]
	v_cvt_pk_bf16_f32 v71, v72, v73
	v_cvt_pk_bf16_f32 v72, v66, v67
	v_add_u32_e32 v66, 0x80, v150
	v_mad_i64_i32 v[148:149], s[50:51], v150, s17, v[140:141]
	v_lshlrev_b64 v[142:143], 1, v[142:143]
	v_cvt_pk_bf16_f32 v114, v114, v115
	v_cvt_pk_bf16_f32 v115, v116, v117
	v_cvt_pk_bf16_f32 v116, v106, v107
	v_or_b32_e32 v106, 16, v150
	v_mad_i64_i32 v[66:67], s[50:51], v66, s17, v[140:141]
	v_cvt_pk_bf16_f32 v50, v50, v51
	v_cvt_pk_bf16_f32 v51, v52, v53
	v_cvt_pk_bf16_f32 v52, v42, v43
	v_add_u32_e32 v42, 0x90, v150
	v_lshl_add_u64 v[148:149], v[148:149], 0, v[142:143]
	v_mad_i64_i32 v[106:107], s[50:51], v106, s17, v[140:141]
	v_cvt_pk_bf16_f32 v98, v98, v99
	v_cvt_pk_bf16_f32 v99, v100, v101
	v_cvt_pk_bf16_f32 v100, v90, v91
	v_or_b32_e32 v90, 32, v150
	v_lshl_add_u64 v[66:67], v[66:67], 0, v[142:143]
	v_mad_i64_i32 v[42:43], s[50:51], v42, s17, v[140:141]
	v_cvt_pk_bf16_f32 v34, v34, v35
	v_cvt_pk_bf16_f32 v35, v36, v37
	v_cvt_pk_bf16_f32 v36, v26, v27
	v_add_u32_e32 v26, 0xa0, v150
	v_cvt_pk_bf16_f32 v117, v108, v109
	global_store_dwordx4 v[148:149], v[114:117], off offset:256
	v_mad_i64_i32 v[90:91], s[50:51], v90, s17, v[140:141]
	s_nop 0
	v_lshl_add_u64 v[114:115], v[106:107], 0, v[142:143]
	v_cvt_pk_bf16_f32 v82, v82, v83
	v_cvt_pk_bf16_f32 v83, v84, v85
	v_cvt_pk_bf16_f32 v84, v74, v75
	v_or_b32_e32 v74, 48, v150
	v_cvt_pk_bf16_f32 v53, v44, v45
	global_store_dwordx4 v[66:67], v[50:53], off offset:256
	v_mad_i64_i32 v[26:27], s[50:51], v26, s17, v[140:141]
	s_nop 0
	v_lshl_add_u64 v[50:51], v[42:43], 0, v[142:143]
	v_cvt_pk_bf16_f32 v18, v18, v19
	v_cvt_pk_bf16_f32 v19, v20, v21
	v_cvt_pk_bf16_f32 v20, v10, v11
	v_add_u32_e32 v10, 0xb0, v150
	v_cvt_pk_bf16_f32 v101, v92, v93
	global_store_dwordx4 v[114:115], v[98:101], off offset:256
	v_mad_i64_i32 v[74:75], s[50:51], v74, s17, v[140:141]
	s_nop 0
	v_lshl_add_u64 v[98:99], v[90:91], 0, v[142:143]
	v_cvt_pk_bf16_f32 v37, v28, v29
	global_store_dwordx4 v[50:51], v[34:37], off offset:256
	v_mad_i64_i32 v[10:11], s[50:51], v10, s17, v[140:141]
	s_nop 0
	v_lshl_add_u64 v[34:35], v[26:27], 0, v[142:143]
	v_cvt_pk_bf16_f32 v85, v76, v77
	global_store_dwordx4 v[98:99], v[82:85], off offset:256
	v_cvt_pk_bf16_f32 v21, v12, v13
	global_store_dwordx4 v[34:35], v[18:21], off offset:256
	s_and_b64 vcc, exec, s[46:47]
	v_lshl_add_u64 v[82:83], v[74:75], 0, v[142:143]
	v_lshl_add_u64 v[18:19], v[10:11], 0, v[142:143]
	s_mov_b32 s40, s42
	s_mov_b32 s28, s8
	s_mov_b32 s43, s42
	s_mov_b32 s46, s8
	s_mov_b64 s[50:51], s[48:49]
	s_mov_b64 s[52:53], s[44:45]
	v_cvt_pk_bf16_f32 v126, v126, v127
	v_cvt_pk_bf16_f32 v127, v128, v129
	v_cvt_pk_bf16_f32 v128, v122, v123
	v_cvt_pk_bf16_f32 v129, v124, v125
	global_store_dwordx4 v[148:149], v[126:129], off
	v_cvt_pk_bf16_f32 v106, v118, v119
	v_cvt_pk_bf16_f32 v107, v120, v121
	v_cvt_pk_bf16_f32 v108, v110, v111
	v_cvt_pk_bf16_f32 v109, v112, v113
	global_store_dwordx4 v[114:115], v[106:109], off
	v_cvt_pk_bf16_f32 v90, v102, v103
	v_cvt_pk_bf16_f32 v91, v104, v105
	v_cvt_pk_bf16_f32 v92, v94, v95
	v_cvt_pk_bf16_f32 v93, v96, v97
	global_store_dwordx4 v[98:99], v[90:93], off
	v_cvt_pk_bf16_f32 v74, v86, v87
	v_cvt_pk_bf16_f32 v75, v88, v89
	v_cvt_pk_bf16_f32 v76, v78, v79
	v_cvt_pk_bf16_f32 v77, v80, v81
	global_store_dwordx4 v[82:83], v[74:77], off
	v_cvt_pk_bf16_f32 v73, v68, v69
	global_store_dwordx4 v[82:83], v[70:73], off offset:256
	v_cvt_pk_bf16_f32 v62, v62, v63
	v_cvt_pk_bf16_f32 v63, v64, v65
	v_cvt_pk_bf16_f32 v64, v58, v59
	v_cvt_pk_bf16_f32 v65, v60, v61
	global_store_dwordx4 v[66:67], v[62:65], off
	v_cvt_pk_bf16_f32 v42, v54, v55
	v_cvt_pk_bf16_f32 v43, v56, v57
	v_cvt_pk_bf16_f32 v44, v46, v47
	v_cvt_pk_bf16_f32 v45, v48, v49
	global_store_dwordx4 v[50:51], v[42:45], off
	v_cvt_pk_bf16_f32 v26, v38, v39
	v_cvt_pk_bf16_f32 v27, v40, v41
	v_cvt_pk_bf16_f32 v28, v30, v31
	v_cvt_pk_bf16_f32 v29, v32, v33
	global_store_dwordx4 v[34:35], v[26:29], off
	v_cvt_pk_bf16_f32 v10, v22, v23
	v_cvt_pk_bf16_f32 v11, v24, v25
	v_cvt_pk_bf16_f32 v12, v14, v15
	v_cvt_pk_bf16_f32 v13, v16, v17
	global_store_dwordx4 v[18:19], v[10:13], off
	v_cvt_pk_bf16_f32 v6, v6, v7
	v_cvt_pk_bf16_f32 v7, v8, v9
	v_cvt_pk_bf16_f32 v8, v2, v3
	v_cvt_pk_bf16_f32 v9, v4, v5
	global_store_dwordx4 v[18:19], v[6:9], off offset:256
	s_cbranch_vccz .LBB0_346
	s_waitcnt vmcnt(0)
	s_cmpk_gt_u32 s25, 0xff
	s_cbranch_scc1 .LBB0_358
	s_barrier
